# v077 plus fused GEMM rounds of P6/P9/P15: first K-loop iteration peeled with SrcC = 0 on every accumulator's first MFMA (first-touch rule for the rotated tuples), zeroing v_mov removed
# baseline (speedup 1.0000x reference)
; #define PG8_STAGE(bufoff, gbase, voff) do { _Pragma("unroll") for (int _i = 0; _i < 2; ++_i) \
;         __builtin_amdgcn_global_load_lds((const unsigned*)((const char*)(gbase) + (voff)[_i]), (PG8_LAS unsigned*)(lds + (bufoff) + ldsw + _i * 8192), 16, 0, 0); } while (0)
; #define PG8_WAIT_V(n) asm volatile("s_waitcnt vmcnt(" #n ")" ::: "memory")
; #define PG8_WAIT_L(n) asm volatile("s_waitcnt lgkmcnt(" #n ")" ::: "memory")
; template <class Epi, class Sched, bool ALIGN_EPI = false, bool SP2 = false>
; __device__ __forceinline__ void gemm_phase(PG8_LAS unsigned char* lds, const Gemm g, const Sched& S, const Epi& E) {
;     ...
;         PG8_STAGE(PG8_SB(0, 0), cB, voffB); PG8_STAGE(PG8_SB(0, 1), cB + hstepB, voffB); PG8_STAGE(PG8_SA(0, 0), cA, voffA); PG8_STAGE(PG8_SA(0, 1), cA + hstepA, voffA);
;         if (wr == 1) PG8_BAR;
;         PG8_WAIT_V(2); PG8_BAR;
;         PG8_STAGE(PG8_SB(1, 0), cB + kstep, voffB); PG8_STAGE(PG8_SA(1, 0), cA + kstep, voffA); PG8_STAGE(PG8_SB(1, 1), cB + hstepB + kstep, voffB);
;         PG8_WAIT_V(6); PG8_BAR;
;     } else {
;         PG8_STAGE(PG8_SB(0, 0), cB, voffB); PG8_STAGE(PG8_SA(0, 0), cA, voffA); PG8_STAGE(PG8_SB(0, 1), cB + hstepB, voffB); PG8_STAGE(PG8_SA(0, 1), cA + hstepA, voffA);
;         if (wr == 1) PG8_BAR;
;         PG8_WAIT_V(4); PG8_BAR;
;         PG8_STAGE(PG8_SB(1, 0), cB + kstep, voffB); PG8_STAGE(PG8_SA(1, 0), cA + kstep, voffA); PG8_STAGE(PG8_SB(1, 1), cB + hstepB + kstep, voffB);
;         PG8_WAIT_V(6); PG8_BAR;
;     }
;     for (;;) {
;         const bool has_next = S.next(ui + 1, nxt);
;         const char* nA = has_next ? PG8_UA(nxt) : cA; const char* nB = has_next ? PG8_UB(nxt) : cB;
;         for (int t = 0; t < nt; t += 2) {
;             const bool last = (t == nt - 2);
;             const char* a1 = cA + (size_t)(t + 1) * kstep;
;             const char* a2 = last ? nA : cA + (size_t)(t + 2) * kstep; const char* b2 = last ? nB : cB + (size_t)(t + 2) * kstep;
;             const char* a3 = a2 + kstep; const char* b3 = b2 + kstep;
;             if (last && has_next) S.a_ready(nxt);
;             if constexpr (SP2) {
;             PG8_LDB(B0, 0, 0); PG8_LDB(B1, 0, 1); PG8_SCHED; PG8_LDA(At, 0, 0); PG8_STAGE(PG8_SA(1, 1), a1 + hstepA, voffA);
;             PG8_WAIT_V(8); PG8_WAIT_L(0); PG8_BAR; PG8_MMA(0, 0, At, B0); PG8_MMA(0, 1, At, B1); PG8_BAR; PG8_SCHED;
.LBB0_884:
	v_lshlrev_b32_e32 v9, 2, v161
	s_and_b32 s41, s6, 3
	v_lshl_or_b32 v8, v161, 6, v166
	s_lshl_b32 s6, s2, 13
	v_and_b32_e32 v9, 32, v9
	v_bitop3_b32 v8, v8, s6, v9 bitop3:0xde
	s_mov_b64 s[6:7], 0x80
	s_add_i32 m0, s3, 0x18000
	v_lshl_add_u64 v[6:7], v[6:7], 0, s[6:7]
	s_waitcnt vmcnt(2)
	s_barrier
	global_load_lds_dwordx4 v[6:7], off
	v_lshl_add_u64 v[4:5], v[4:5], 0, s[6:7]
	s_add_i32 m0, s3, 0x1a000
	s_add_i32 s45, s3, 0x8000
	s_add_i32 s46, s3, 0xa000
	global_load_lds_dwordx4 v[4:5], off
	v_lshl_add_u64 v[2:3], v[2:3], 0, s[6:7]
	s_mov_b32 m0, s45
	s_add_u32 s24, s0, 0x40080
	global_load_lds_dwordx4 v[2:3], off
	v_lshl_add_u64 v[0:1], v[0:1], 0, s[6:7]
	s_mov_b32 m0, s46
	s_addc_u32 s25, s1, 0
	global_load_lds_dwordx4 v[0:1], off
	s_add_i32 m0, s3, 0x1c000
	v_lshl_add_u64 v[0:1], s[24:25], 0, v[146:147]
	global_load_lds_dwordx4 v[0:1], off
	v_lshl_add_u64 v[0:1], s[24:25], 0, v[150:151]
	s_add_i32 m0, s3, 0x1e000
	v_lshlrev_b32_e32 v2, 11, v164
	global_load_lds_dwordx4 v[0:1], off
	v_lshlrev_b32_e32 v0, 8, v194
	v_and_b32_e32 v0, 0x38000, v0
	s_add_u32 s18, s34, s18
	v_or3_b32 v0, v162, v0, v2
	s_addc_u32 s19, s35, s19
	v_add_u32_e32 v0, v0, v163
	v_mov_b32_e32 v1, v147
	v_lshl_add_u64 v[0:1], s[18:19], 0, v[0:1]
	s_mov_b64 s[24:25], 0x3840080
	v_lshl_add_u64 v[96:97], v[0:1], 0, s[24:25]
	v_lshlrev_b32_e32 v0, 4, v165
	s_add_u32 s20, s34, s20
	v_and_b32_e32 v0, 0x78000, v0
	s_addc_u32 s21, s35, s21
	v_or3_b32 v0, v162, v0, v2
	s_add_u32 s47, s20, 0x700100
	v_lshl_or_b32 v9, s41, 12, v167
	s_waitcnt vmcnt(6)
	v_add_u32_e32 v0, v0, v163
	v_mov_b32_e32 v1, v147
	s_addc_u32 s48, s21, 0
	s_add_i32 s52, 0, 0x10000
	s_add_i32 s54, 0, 0x14000
	s_add_i32 s56, 0, 0x18000
	s_add_i32 s58, 0, 0x1c000
	v_lshl_add_u64 v[0:1], s[18:19], 0, v[0:1]
	v_add_u32_e32 v100, s52, v9
	v_add_u32_e32 v101, s54, v9
	s_add_i32 s52, s52, s22
	s_add_i32 s54, s54, s22
	v_add_u32_e32 v103, s56, v9
	v_add_u32_e32 v104, s58, v9
	s_add_i32 s56, s56, s22
	s_add_i32 s58, s58, s22
	v_lshl_or_b32 v152, s2, 6, v161
	v_lshl_add_u64 v[98:99], v[0:1], 0, s[24:25]
	s_mov_b32 s49, -2
	s_mov_b64 s[20:21], 0
	v_add_u32_e32 v102, 0, v8
	s_add_i32 s50, s3, 0xc000
	s_add_i32 s51, s3, 0xe000
	s_add_i32 s53, s52, 0x2000
	s_add_i32 s55, s54, 0x2000
	s_add_i32 s57, s56, 0x2000
	s_add_i32 s59, s58, 0x2000
	s_barrier
	ds_read_b128 v[106:109], v100
	ds_read_b128 v[154:157], v100 offset:1024
	ds_read_b128 v[168:171], v100 offset:2048
	ds_read_b128 v[172:175], v100 offset:3072
	ds_read_b128 v[176:179], v101
	ds_read_b128 v[180:183], v101 offset:1024
	ds_read_b128 v[184:187], v101 offset:2048
	ds_read_b128 v[188:191], v101 offset:3072
	s_add_u32 s22, s18, s20
	s_addc_u32 s23, s19, s21
	s_add_u32 s22, s22, 0x3800100
	s_addc_u32 s23, s23, 0
	s_add_u32 s60, s47, s20
	s_addc_u32 s61, s48, s21
	s_cmpk_eq_i32 s20, 0x700
	s_cselect_b32 s25, s5, s23
	s_cselect_b32 s24, s4, s22
	s_cselect_b32 s23, s1, s61
	s_cselect_b32 s22, s0, s60
	s_mov_b32 m0, s50
	v_lshl_add_u64 v[110:111], v[96:97], 0, s[20:21]
	ds_read_b128 v[196:199], v102
	ds_read_b128 v[200:203], v102 offset:1024
	ds_read_b128 v[204:207], v102 offset:2048
	ds_read_b128 v[208:211], v102 offset:3072
	ds_read_b128 v[212:215], v102 offset:4096
	ds_read_b128 v[216:219], v102 offset:5120
	ds_read_b128 v[220:223], v102 offset:6144
	ds_read_b128 v[224:227], v102 offset:7168
	global_load_lds_dwordx4 v[110:111], off
	v_lshl_add_u64 v[110:111], v[98:99], 0, s[20:21]
	s_mov_b32 m0, s51
	s_nop 0
	global_load_lds_dwordx4 v[110:111], off
	s_waitcnt vmcnt(8)
	s_waitcnt lgkmcnt(0)
	s_barrier
	s_setprio 1
	s_waitcnt lgkmcnt(0)
	v_mfma_f32_16x16x32_bf16 v[140:143], v[106:109], v[196:199], 0
	v_mfma_f32_16x16x32_bf16 v[136:139], v[168:171], v[196:199], 0
	v_mfma_f32_16x16x32_bf16 v[124:127], v[106:109], v[204:207], 0
	v_mfma_f32_16x16x32_bf16 v[120:123], v[168:171], v[204:207], 0
	v_mfma_f32_16x16x32_bf16 v[92:95], v[106:109], v[212:215], 0
	v_mfma_f32_16x16x32_bf16 v[88:91], v[168:171], v[212:215], 0
	v_mfma_f32_16x16x32_bf16 v[76:79], v[106:109], v[220:223], 0
	v_mfma_f32_16x16x32_bf16 v[72:75], v[168:171], v[220:223], 0
	v_mfma_f32_16x16x32_bf16 v[140:143], v[154:157], v[200:203], v[140:143]
	v_mfma_f32_16x16x32_bf16 v[136:139], v[172:175], v[200:203], v[136:139]
	v_mfma_f32_16x16x32_bf16 v[124:127], v[154:157], v[208:211], v[124:127]
	v_mfma_f32_16x16x32_bf16 v[120:123], v[172:175], v[208:211], v[120:123]
	v_mfma_f32_16x16x32_bf16 v[92:95], v[154:157], v[216:219], v[92:95]
	v_mfma_f32_16x16x32_bf16 v[88:91], v[172:175], v[216:219], v[88:91]
	v_mfma_f32_16x16x32_bf16 v[76:79], v[154:157], v[224:227], v[76:79]
	v_mfma_f32_16x16x32_bf16 v[72:75], v[172:175], v[224:227], v[72:75]
	s_setprio 0
	s_setprio 1
	v_mfma_f32_16x16x32_bf16 v[132:135], v[176:179], v[196:199], 0
	v_mfma_f32_16x16x32_bf16 v[128:131], v[184:187], v[196:199], 0
	v_mfma_f32_16x16x32_bf16 v[116:119], v[176:179], v[204:207], 0
	v_mfma_f32_16x16x32_bf16 v[110:113], v[184:187], v[204:207], 0
	v_mfma_f32_16x16x32_bf16 v[84:87], v[176:179], v[212:215], 0
	v_mfma_f32_16x16x32_bf16 v[80:83], v[184:187], v[212:215], 0
	v_mfma_f32_16x16x32_bf16 v[68:71], v[176:179], v[220:223], 0
	v_mfma_f32_16x16x32_bf16 v[64:67], v[184:187], v[220:223], 0
	v_mfma_f32_16x16x32_bf16 v[132:135], v[180:183], v[200:203], v[132:135]
	v_mfma_f32_16x16x32_bf16 v[128:131], v[188:191], v[200:203], v[128:131]
	v_mfma_f32_16x16x32_bf16 v[116:119], v[180:183], v[208:211], v[116:119]
	v_mfma_f32_16x16x32_bf16 v[110:113], v[188:191], v[208:211], v[110:113]
	v_mfma_f32_16x16x32_bf16 v[84:87], v[180:183], v[216:219], v[84:87]
	v_mfma_f32_16x16x32_bf16 v[80:83], v[188:191], v[216:219], v[80:83]
	v_mfma_f32_16x16x32_bf16 v[68:71], v[180:183], v[224:227], v[68:71]
	v_mfma_f32_16x16x32_bf16 v[64:67], v[188:191], v[224:227], v[64:67]
	s_setprio 0
	s_barrier
; #define PG8_STAGE(bufoff, gbase, voff) do { _Pragma("unroll") for (int _i = 0; _i < 2; ++_i) \
;         __builtin_amdgcn_global_load_lds((const unsigned*)((const char*)(gbase) + (voff)[_i]), (PG8_LAS unsigned*)(lds + (bufoff) + ldsw + _i * 8192), 16, 0, 0); } while (0)
; #define PG8_LDA(dst, b, h) do { _Pragma("unroll") for (int m = 0; m < 4; ++m) _Pragma("unroll") for (int k = 0; k < 2; ++k) dst[m][k] = *(const PG8_LAS bf16x8*)(lds + PG8_SA(b, h) + aoff + m * 2048 + k * 1024); } while (0)
; #define PG8_LDB(dst, b, h) do { _Pragma("unroll") for (int n = 0; n < 2; ++n) _Pragma("unroll") for (int k = 0; k < 2; ++k) dst[n][k] = *(const PG8_LAS bf16x8*)(lds + PG8_SB(b, h) + boff + n * 2048 + k * 1024); } while (0)
; #define PG8_MMA(ai, bj, At, Bt) do { __builtin_amdgcn_s_setprio(1); _Pragma("unroll") for (int m = 0; m < 4; ++m) _Pragma("unroll") for (int n = 0; n < 2; ++n) _Pragma("unroll") for (int k = 0; k < 2; ++k) \
;         acc[ai][bj][m][n] = __builtin_amdgcn_mfma_f32_16x16x32_bf16(Bt[n][k], At[m][k], acc[ai][bj][m][n], 0, 0, 0); __builtin_amdgcn_s_setprio(0); } while (0)
; #define PG8_WAIT_V(n) asm volatile("s_waitcnt vmcnt(" #n ")" ::: "memory")
; #define PG8_WAIT_L(n) asm volatile("s_waitcnt lgkmcnt(" #n ")" ::: "memory")
; #define PG8_BAR __builtin_amdgcn_s_barrier()
; #define PG8_SCHED __builtin_amdgcn_sched_barrier(0)
; template <class Epi, class Sched, bool ALIGN_EPI = false, bool SP2 = false>
; __device__ __forceinline__ void gemm_phase(PG8_LAS unsigned char* lds, const Gemm g, const Sched& S, const Epi& E) {
;     ...
;             PG8_LDA(At, 0, 1); PG8_STAGE(PG8_SB(0, 0), b2, voffB); PG8_STAGE(PG8_SB(0, 1), b2 + hstepB, voffB); PG8_STAGE(PG8_SA(0, 0), a2, voffA);
;             PG8_WAIT_V(8); PG8_WAIT_L(0); PG8_BAR; PG8_MMA(1, 0, At, B0); PG8_MMA(1, 1, At, B1); PG8_BAR; PG8_SCHED;
;             PG8_LDB(B0, 1, 0); PG8_LDB(B1, 1, 1); PG8_SCHED; PG8_LDA(At, 1, 0); PG8_STAGE(PG8_SA(0, 1), a2 + hstepA, voffA);
;             PG8_WAIT_V(8); PG8_WAIT_L(0); PG8_BAR; PG8_MMA(0, 0, At, B0); PG8_MMA(0, 1, At, B1); PG8_BAR; PG8_SCHED;
	s_mov_b32 m0, s52
	v_lshl_add_u64 v[158:159], s[22:23], 0, v[146:147]
	s_add_u32 s60, s22, 0x40000
	ds_read_b128 v[196:199], v102 offset:16384
	ds_read_b128 v[200:203], v102 offset:17408
	ds_read_b128 v[204:207], v102 offset:18432
	ds_read_b128 v[208:211], v102 offset:19456
	ds_read_b128 v[212:215], v102 offset:20480
	ds_read_b128 v[216:219], v102 offset:21504
	ds_read_b128 v[220:223], v102 offset:22528
	ds_read_b128 v[224:227], v102 offset:23552
	global_load_lds_dwordx4 v[158:159], off
	v_lshl_add_u64 v[228:229], s[22:23], 0, v[150:151]
	s_mov_b32 m0, s53
	s_addc_u32 s61, s23, 0
	global_load_lds_dwordx4 v[228:229], off
	v_lshl_add_u64 v[114:115], s[60:61], 0, v[146:147]
	s_mov_b32 m0, s54
	v_lshl_add_u64 v[230:231], s[24:25], 0, v[144:145]
	global_load_lds_dwordx4 v[114:115], off
	v_lshl_add_u64 v[114:115], s[60:61], 0, v[150:151]
	s_mov_b32 m0, s55
	v_lshl_add_u64 v[232:233], s[24:25], 0, v[148:149]
	global_load_lds_dwordx4 v[114:115], off
	s_mov_b32 m0, s3
	s_nop 0
	global_load_lds_dwordx4 v[230:231], off
	s_mov_b32 m0, s42
	s_nop 0
	global_load_lds_dwordx4 v[232:233], off
	s_waitcnt vmcnt(8)
	s_waitcnt lgkmcnt(0)
	s_barrier
	s_setprio 1
	s_waitcnt lgkmcnt(0)
	v_mfma_f32_16x16x32_bf16 v[60:63], v[106:109], v[196:199], 0
	v_mfma_f32_16x16x32_bf16 v[56:59], v[168:171], v[196:199], 0
	v_mfma_f32_16x16x32_bf16 v[44:47], v[106:109], v[204:207], 0
	v_mfma_f32_16x16x32_bf16 v[40:43], v[168:171], v[204:207], 0
	v_mfma_f32_16x16x32_bf16 v[28:31], v[106:109], v[212:215], 0
	v_mfma_f32_16x16x32_bf16 v[24:27], v[168:171], v[212:215], 0
	v_mfma_f32_16x16x32_bf16 v[12:15], v[106:109], v[220:223], 0
	v_mfma_f32_16x16x32_bf16 v[8:11], v[168:171], v[220:223], 0
	v_mfma_f32_16x16x32_bf16 v[60:63], v[154:157], v[200:203], v[60:63]
	v_mfma_f32_16x16x32_bf16 v[56:59], v[172:175], v[200:203], v[56:59]
	v_mfma_f32_16x16x32_bf16 v[44:47], v[154:157], v[208:211], v[44:47]
	v_mfma_f32_16x16x32_bf16 v[40:43], v[172:175], v[208:211], v[40:43]
	v_mfma_f32_16x16x32_bf16 v[28:31], v[154:157], v[216:219], v[28:31]
	v_mfma_f32_16x16x32_bf16 v[24:27], v[172:175], v[216:219], v[24:27]
	v_mfma_f32_16x16x32_bf16 v[12:15], v[154:157], v[224:227], v[12:15]
	v_mfma_f32_16x16x32_bf16 v[8:11], v[172:175], v[224:227], v[8:11]
	s_setprio 0
	s_setprio 1
	v_mfma_f32_16x16x32_bf16 v[52:55], v[176:179], v[196:199], 0
	v_mfma_f32_16x16x32_bf16 v[48:51], v[184:187], v[196:199], 0
	v_mfma_f32_16x16x32_bf16 v[36:39], v[176:179], v[204:207], 0
	v_mfma_f32_16x16x32_bf16 v[32:35], v[184:187], v[204:207], 0
	v_mfma_f32_16x16x32_bf16 v[20:23], v[176:179], v[212:215], 0
	v_mfma_f32_16x16x32_bf16 v[16:19], v[184:187], v[212:215], 0
	v_mfma_f32_16x16x32_bf16 v[4:7], v[176:179], v[220:223], 0
	v_mfma_f32_16x16x32_bf16 v[0:3], v[184:187], v[220:223], 0
	v_mfma_f32_16x16x32_bf16 v[52:55], v[180:183], v[200:203], v[52:55]
	v_mfma_f32_16x16x32_bf16 v[48:51], v[188:191], v[200:203], v[48:51]
	v_mfma_f32_16x16x32_bf16 v[36:39], v[180:183], v[208:211], v[36:39]
	v_mfma_f32_16x16x32_bf16 v[32:35], v[188:191], v[208:211], v[32:35]
	v_mfma_f32_16x16x32_bf16 v[20:23], v[180:183], v[216:219], v[20:23]
	v_mfma_f32_16x16x32_bf16 v[16:19], v[188:191], v[216:219], v[16:19]
	v_mfma_f32_16x16x32_bf16 v[4:7], v[180:183], v[224:227], v[4:7]
	v_mfma_f32_16x16x32_bf16 v[0:3], v[188:191], v[224:227], v[0:3]
	s_setprio 0
	s_barrier
	ds_read_b128 v[106:109], v103
	ds_read_b128 v[154:157], v103 offset:1024
	ds_read_b128 v[168:171], v103 offset:2048
	ds_read_b128 v[172:175], v103 offset:3072
	ds_read_b128 v[176:179], v104
	ds_read_b128 v[180:183], v104 offset:1024
	ds_read_b128 v[184:187], v104 offset:2048
	ds_read_b128 v[188:191], v104 offset:3072
	s_add_u32 s24, s24, 0x40000
	s_addc_u32 s25, s25, 0
	s_mov_b32 m0, s43
	v_lshl_add_u64 v[114:115], s[24:25], 0, v[144:145]
	ds_read_b128 v[196:199], v102 offset:32768
	ds_read_b128 v[200:203], v102 offset:33792
	ds_read_b128 v[204:207], v102 offset:34816
	ds_read_b128 v[208:211], v102 offset:35840
	ds_read_b128 v[212:215], v102 offset:36864
	ds_read_b128 v[216:219], v102 offset:37888
	ds_read_b128 v[220:223], v102 offset:38912
	ds_read_b128 v[224:227], v102 offset:39936
	global_load_lds_dwordx4 v[114:115], off
	v_lshl_add_u64 v[114:115], s[24:25], 0, v[148:149]
	s_mov_b32 m0, s44
	s_nop 0
	global_load_lds_dwordx4 v[114:115], off
	s_waitcnt vmcnt(8)
	s_waitcnt lgkmcnt(0)
	s_barrier
; #define PG8_STAGE(bufoff, gbase, voff) do { _Pragma("unroll") for (int _i = 0; _i < 2; ++_i) \
;         __builtin_amdgcn_global_load_lds((const unsigned*)((const char*)(gbase) + (voff)[_i]), (PG8_LAS unsigned*)(lds + (bufoff) + ldsw + _i * 8192), 16, 0, 0); } while (0)
; #define PG8_LDA(dst, b, h) do { _Pragma("unroll") for (int m = 0; m < 4; ++m) _Pragma("unroll") for (int k = 0; k < 2; ++k) dst[m][k] = *(const PG8_LAS bf16x8*)(lds + PG8_SA(b, h) + aoff + m * 2048 + k * 1024); } while (0)
; #define PG8_MMA(ai, bj, At, Bt) do { __builtin_amdgcn_s_setprio(1); _Pragma("unroll") for (int m = 0; m < 4; ++m) _Pragma("unroll") for (int n = 0; n < 2; ++n) _Pragma("unroll") for (int k = 0; k < 2; ++k) \
;         acc[ai][bj][m][n] = __builtin_amdgcn_mfma_f32_16x16x32_bf16(Bt[n][k], At[m][k], acc[ai][bj][m][n], 0, 0, 0); __builtin_amdgcn_s_setprio(0); } while (0)
; #define PG8_WAIT_V(n) asm volatile("s_waitcnt vmcnt(" #n ")" ::: "memory")
; #define PG8_WAIT_L(n) asm volatile("s_waitcnt lgkmcnt(" #n ")" ::: "memory")
; #define PG8_BAR __builtin_amdgcn_s_barrier()
; #define PG8_SCHED __builtin_amdgcn_sched_barrier(0)
; template <class Epi, class Sched, bool ALIGN_EPI = false, bool SP2 = false>
; __device__ __forceinline__ void gemm_phase(PG8_LAS unsigned char* lds, const Gemm g, const Sched& S, const Epi& E) {
;     ...
;         for (int t = 0; t < nt; t += 2) {
;     ...
;             PG8_WAIT_V(8); PG8_WAIT_L(0); PG8_BAR; PG8_MMA(0, 0, At, B0); PG8_MMA(0, 1, At, B1); PG8_BAR; PG8_SCHED;
;             PG8_LDA(At, 1, 1); PG8_STAGE(PG8_SB(1, 0), b3, voffB); PG8_STAGE(PG8_SB(1, 1), b3 + hstepB, voffB); PG8_STAGE(PG8_SA(1, 0), a3, voffA);
;             PG8_WAIT_V(8); PG8_WAIT_L(0); PG8_BAR; PG8_MMA(1, 0, At, B0); PG8_MMA(1, 1, At, B1); PG8_BAR; PG8_SCHED;
	s_setprio 1
	s_waitcnt lgkmcnt(0)
	v_mfma_f32_16x16x32_bf16 v[140:143], v[106:109], v[196:199], v[140:143]
	v_mfma_f32_16x16x32_bf16 v[136:139], v[168:171], v[196:199], v[136:139]
	v_mfma_f32_16x16x32_bf16 v[124:127], v[106:109], v[204:207], v[124:127]
	v_mfma_f32_16x16x32_bf16 v[120:123], v[168:171], v[204:207], v[120:123]
	v_mfma_f32_16x16x32_bf16 v[92:95], v[106:109], v[212:215], v[92:95]
	v_mfma_f32_16x16x32_bf16 v[88:91], v[168:171], v[212:215], v[88:91]
	v_mfma_f32_16x16x32_bf16 v[76:79], v[106:109], v[220:223], v[76:79]
	v_mfma_f32_16x16x32_bf16 v[72:75], v[168:171], v[220:223], v[72:75]
	v_mfma_f32_16x16x32_bf16 v[140:143], v[154:157], v[200:203], v[140:143]
	v_mfma_f32_16x16x32_bf16 v[136:139], v[172:175], v[200:203], v[136:139]
	v_mfma_f32_16x16x32_bf16 v[124:127], v[154:157], v[208:211], v[124:127]
	v_mfma_f32_16x16x32_bf16 v[120:123], v[172:175], v[208:211], v[120:123]
	v_mfma_f32_16x16x32_bf16 v[92:95], v[154:157], v[216:219], v[92:95]
	v_mfma_f32_16x16x32_bf16 v[88:91], v[172:175], v[216:219], v[88:91]
	v_mfma_f32_16x16x32_bf16 v[76:79], v[154:157], v[224:227], v[76:79]
	v_mfma_f32_16x16x32_bf16 v[72:75], v[172:175], v[224:227], v[72:75]
	s_setprio 0
	s_setprio 1
	v_mfma_f32_16x16x32_bf16 v[132:135], v[176:179], v[196:199], v[132:135]
	v_mfma_f32_16x16x32_bf16 v[128:131], v[184:187], v[196:199], v[128:131]
	v_mfma_f32_16x16x32_bf16 v[114:117], v[176:179], v[204:207], v[116:119]
	v_mfma_f32_16x16x32_bf16 v[110:113], v[184:187], v[204:207], v[110:113]
	v_mfma_f32_16x16x32_bf16 v[84:87], v[176:179], v[212:215], v[84:87]
	v_mfma_f32_16x16x32_bf16 v[80:83], v[184:187], v[212:215], v[80:83]
	v_mfma_f32_16x16x32_bf16 v[68:71], v[176:179], v[220:223], v[68:71]
	v_mfma_f32_16x16x32_bf16 v[64:67], v[184:187], v[220:223], v[64:67]
	v_mfma_f32_16x16x32_bf16 v[132:135], v[180:183], v[200:203], v[132:135]
	v_mfma_f32_16x16x32_bf16 v[128:131], v[188:191], v[200:203], v[128:131]
	v_mfma_f32_16x16x32_bf16 v[116:119], v[180:183], v[208:211], v[114:117]
	v_mfma_f32_16x16x32_bf16 v[112:115], v[188:191], v[208:211], v[110:113]
	v_mfma_f32_16x16x32_bf16 v[84:87], v[180:183], v[216:219], v[84:87]
	v_mfma_f32_16x16x32_bf16 v[80:83], v[188:191], v[216:219], v[80:83]
	v_mfma_f32_16x16x32_bf16 v[68:71], v[180:183], v[224:227], v[68:71]
	v_mfma_f32_16x16x32_bf16 v[64:67], v[188:191], v[224:227], v[64:67]
	s_setprio 0
	s_barrier
	s_mov_b32 m0, s56
	v_lshl_add_u64 v[110:111], v[158:159], 0, s[6:7]
	s_add_u32 s22, s22, 0x40080
	ds_read_b128 v[196:199], v102 offset:49152
	ds_read_b128 v[200:203], v102 offset:50176
	ds_read_b128 v[204:207], v102 offset:51200
	ds_read_b128 v[208:211], v102 offset:52224
	ds_read_b128 v[212:215], v102 offset:53248
	ds_read_b128 v[216:219], v102 offset:54272
	ds_read_b128 v[220:223], v102 offset:55296
	ds_read_b128 v[224:227], v102 offset:56320
	global_load_lds_dwordx4 v[110:111], off
	v_lshl_add_u64 v[110:111], v[228:229], 0, s[6:7]
	s_mov_b32 m0, s57
	s_addc_u32 s23, s23, 0
	global_load_lds_dwordx4 v[110:111], off
	v_lshl_add_u64 v[110:111], s[22:23], 0, v[146:147]
	s_mov_b32 m0, s58
	s_nop 0
	global_load_lds_dwordx4 v[110:111], off
	v_lshl_add_u64 v[110:111], s[22:23], 0, v[150:151]
	s_mov_b32 m0, s59
	s_nop 0
	global_load_lds_dwordx4 v[110:111], off
	v_lshl_add_u64 v[110:111], v[230:231], 0, s[6:7]
	s_mov_b32 m0, s45
	s_nop 0
	global_load_lds_dwordx4 v[110:111], off
	v_lshl_add_u64 v[110:111], v[232:233], 0, s[6:7]
	s_mov_b32 m0, s46
	s_nop 0
	global_load_lds_dwordx4 v[110:111], off
	s_waitcnt vmcnt(8)
	s_waitcnt lgkmcnt(0)
	s_barrier
	s_setprio 1
	s_waitcnt lgkmcnt(0)
	v_mfma_f32_16x16x32_bf16 v[60:63], v[106:109], v[196:199], v[60:63]
	v_mfma_f32_16x16x32_bf16 v[56:59], v[168:171], v[196:199], v[56:59]
	v_mfma_f32_16x16x32_bf16 v[44:47], v[106:109], v[204:207], v[44:47]
	v_mfma_f32_16x16x32_bf16 v[40:43], v[168:171], v[204:207], v[40:43]
	v_mfma_f32_16x16x32_bf16 v[28:31], v[106:109], v[212:215], v[28:31]
	v_mfma_f32_16x16x32_bf16 v[24:27], v[168:171], v[212:215], v[24:27]
	v_mfma_f32_16x16x32_bf16 v[12:15], v[106:109], v[220:223], v[12:15]
	v_mfma_f32_16x16x32_bf16 v[8:11], v[168:171], v[220:223], v[8:11]
	v_mfma_f32_16x16x32_bf16 v[60:63], v[154:157], v[200:203], v[60:63]
	v_mfma_f32_16x16x32_bf16 v[56:59], v[172:175], v[200:203], v[56:59]
	v_mfma_f32_16x16x32_bf16 v[44:47], v[154:157], v[208:211], v[44:47]
	v_mfma_f32_16x16x32_bf16 v[40:43], v[172:175], v[208:211], v[40:43]
	v_mfma_f32_16x16x32_bf16 v[28:31], v[154:157], v[216:219], v[28:31]
	v_mfma_f32_16x16x32_bf16 v[24:27], v[172:175], v[216:219], v[24:27]
	v_mfma_f32_16x16x32_bf16 v[12:15], v[154:157], v[224:227], v[12:15]
	v_mfma_f32_16x16x32_bf16 v[8:11], v[172:175], v[224:227], v[8:11]
	s_setprio 0
	s_setprio 1
	v_mfma_f32_16x16x32_bf16 v[52:55], v[176:179], v[196:199], v[52:55]
	v_mfma_f32_16x16x32_bf16 v[48:51], v[184:187], v[196:199], v[48:51]
	v_mfma_f32_16x16x32_bf16 v[36:39], v[176:179], v[204:207], v[36:39]
	v_mfma_f32_16x16x32_bf16 v[32:35], v[184:187], v[204:207], v[32:35]
	v_mfma_f32_16x16x32_bf16 v[20:23], v[176:179], v[212:215], v[20:23]
	v_mfma_f32_16x16x32_bf16 v[16:19], v[184:187], v[212:215], v[16:19]
	v_mfma_f32_16x16x32_bf16 v[4:7], v[176:179], v[220:223], v[4:7]
	v_mfma_f32_16x16x32_bf16 v[0:3], v[184:187], v[220:223], v[0:3]
	v_mfma_f32_16x16x32_bf16 v[52:55], v[180:183], v[200:203], v[52:55]
	v_mfma_f32_16x16x32_bf16 v[48:51], v[188:191], v[200:203], v[48:51]
	v_mfma_f32_16x16x32_bf16 v[36:39], v[180:183], v[208:211], v[36:39]
	v_mfma_f32_16x16x32_bf16 v[32:35], v[188:191], v[208:211], v[32:35]
	v_mfma_f32_16x16x32_bf16 v[20:23], v[180:183], v[216:219], v[20:23]
	v_mfma_f32_16x16x32_bf16 v[16:19], v[188:191], v[216:219], v[16:19]
	v_mfma_f32_16x16x32_bf16 v[4:7], v[180:183], v[224:227], v[4:7]
	v_mfma_f32_16x16x32_bf16 v[0:3], v[188:191], v[224:227], v[0:3]
	s_setprio 0
	s_barrier
	s_add_i32 s49, s49, 2
	s_add_u32 s20, s20, 0x100
	s_addc_u32 s21, s21, 0

; #define PG8_STAGE(bufoff, gbase, voff) do { _Pragma("unroll") for (int _i = 0; _i < 2; ++_i) \
;         __builtin_amdgcn_global_load_lds((const unsigned*)((const char*)(gbase) + (voff)[_i]), (PG8_LAS unsigned*)(lds + (bufoff) + ldsw + _i * 8192), 16, 0, 0); } while (0)
; #define PG8_LDA(dst, b, h) do { _Pragma("unroll") for (int m = 0; m < 4; ++m) _Pragma("unroll") for (int k = 0; k < 2; ++k) dst[m][k] = *(const PG8_LAS bf16x8*)(lds + PG8_SA(b, h) + aoff + m * 2048 + k * 1024); } while (0)
; #define PG8_WAIT_V(n) asm volatile("s_waitcnt vmcnt(" #n ")" ::: "memory")
; #define PG8_WAIT_L(n) asm volatile("s_waitcnt lgkmcnt(" #n ")" ::: "memory")
; template <class Epi, class Sched, bool ALIGN_EPI = false, bool SP2 = false>
; __device__ __forceinline__ void gemm_phase(PG8_LAS unsigned char* lds, const Gemm g, const Sched& S, const Epi& E) {
;     ...
;         PG8_WAIT_V(2); PG8_BAR;
;         PG8_STAGE(PG8_SB(1, 0), cB + kstep, voffB); PG8_STAGE(PG8_SA(1, 0), cA + kstep, voffA); PG8_STAGE(PG8_SB(1, 1), cB + hstepB + kstep, voffB);
;         PG8_WAIT_V(6); PG8_BAR;
;     } else {
;         PG8_STAGE(PG8_SB(0, 0), cB, voffB); PG8_STAGE(PG8_SA(0, 0), cA, voffA); PG8_STAGE(PG8_SB(0, 1), cB + hstepB, voffB); PG8_STAGE(PG8_SA(0, 1), cA + hstepA, voffA);
;         if (wr == 1) PG8_BAR;
;         PG8_WAIT_V(4); PG8_BAR;
;         PG8_STAGE(PG8_SB(1, 0), cB + kstep, voffB); PG8_STAGE(PG8_SA(1, 0), cA + kstep, voffA); PG8_STAGE(PG8_SB(1, 1), cB + hstepB + kstep, voffB);
;         PG8_WAIT_V(6); PG8_BAR;
;     }
;     for (;;) {
;         const bool has_next = S.next(ui + 1, nxt);
;         const char* nA = has_next ? PG8_UA(nxt) : cA; const char* nB = has_next ? PG8_UB(nxt) : cB;
;         for (int t = 0; t < nt; t += 2) {
;             const bool last = (t == nt - 2);
;             const char* a1 = cA + (size_t)(t + 1) * kstep;
;             const char* a2 = last ? nA : cA + (size_t)(t + 2) * kstep; const char* b2 = last ? nB : cB + (size_t)(t + 2) * kstep;
;             const char* a3 = a2 + kstep; const char* b3 = b2 + kstep;
;             if (last && has_next) S.a_ready(nxt);
;             if constexpr (SP2) {
;             PG8_LDB(B0, 0, 0); PG8_LDB(B1, 0, 1); PG8_SCHED; PG8_LDA(At, 0, 0); PG8_STAGE(PG8_SA(1, 1), a1 + hstepA, voffA);
;             PG8_WAIT_V(8); PG8_WAIT_L(0); PG8_BAR; PG8_MMA(0, 0, At, B0); PG8_MMA(0, 1, At, B1); PG8_BAR; PG8_SCHED;
.LBB0_939:
	v_lshlrev_b32_e32 v9, 2, v161
	s_and_b32 s30, s6, 3
	v_lshl_or_b32 v8, v161, 6, v166
	s_lshl_b32 s6, s3, 13
	v_and_b32_e32 v9, 32, v9
	v_bitop3_b32 v8, v8, s6, v9 bitop3:0xde
	s_mov_b64 s[6:7], 0x80
	s_add_i32 m0, s31, 0x18000
	v_lshl_add_u64 v[6:7], v[6:7], 0, s[6:7]
	s_waitcnt vmcnt(2)
	s_barrier
	global_load_lds_dwordx4 v[6:7], off
	v_lshl_add_u64 v[4:5], v[4:5], 0, s[6:7]
	s_add_i32 m0, s31, 0x1a000
	s_add_i32 s43, s31, 0x8000
	s_add_i32 s44, s31, 0xa000
	global_load_lds_dwordx4 v[4:5], off
	v_lshl_add_u64 v[2:3], v[2:3], 0, s[6:7]
	s_mov_b32 m0, s43
	s_add_u32 s24, s0, 0x40080
	global_load_lds_dwordx4 v[2:3], off
	v_lshl_add_u64 v[0:1], v[0:1], 0, s[6:7]
	s_mov_b32 m0, s44
	s_addc_u32 s25, s1, 0
	global_load_lds_dwordx4 v[0:1], off
	s_add_i32 m0, s31, 0x1c000
	v_lshl_add_u64 v[0:1], s[24:25], 0, v[146:147]
	global_load_lds_dwordx4 v[0:1], off
	v_lshl_add_u64 v[0:1], s[24:25], 0, v[150:151]
	s_add_i32 m0, s31, 0x1e000
	v_lshlrev_b32_e32 v2, 11, v164
	global_load_lds_dwordx4 v[0:1], off
	v_lshlrev_b32_e32 v0, 8, v194
	v_and_b32_e32 v0, 0x38000, v0
	s_add_u32 s18, s34, s18
	v_or3_b32 v0, v162, v0, v2
	s_addc_u32 s19, s35, s19
	v_add_u32_e32 v0, v0, v163
	v_mov_b32_e32 v1, v147
	v_lshl_add_u64 v[0:1], s[18:19], 0, v[0:1]
	s_mov_b64 s[24:25], 0x3840080
	v_lshl_add_u64 v[96:97], v[0:1], 0, s[24:25]
	v_lshlrev_b32_e32 v0, 4, v165
	s_add_u32 s20, s34, s20
	v_and_b32_e32 v0, 0x78000, v0
	s_addc_u32 s21, s35, s21
	v_or3_b32 v0, v162, v0, v2
	s_add_u32 s45, s20, 0x700100
	v_lshl_or_b32 v9, s30, 12, v167
	s_waitcnt vmcnt(6)
	v_add_u32_e32 v0, v0, v163
	v_mov_b32_e32 v1, v147
	s_addc_u32 s46, s21, 0
	s_add_i32 s50, 0, 0x10000
	s_add_i32 s52, 0, 0x14000
	s_add_i32 s54, 0, 0x18000
	s_add_i32 s56, 0, 0x1c000
	v_lshl_add_u64 v[0:1], s[18:19], 0, v[0:1]
	v_add_u32_e32 v100, s50, v9
	v_add_u32_e32 v101, s52, v9
	s_add_i32 s50, s50, s22
	s_add_i32 s52, s52, s22
	v_add_u32_e32 v103, s54, v9
	v_add_u32_e32 v104, s56, v9
	s_add_i32 s54, s54, s22
	s_add_i32 s56, s56, s22
	v_lshl_or_b32 v152, s3, 6, v161
	v_lshl_add_u64 v[98:99], v[0:1], 0, s[24:25]
	s_mov_b32 s47, -2
	s_mov_b64 s[20:21], 0
	v_add_u32_e32 v102, 0, v8
	s_add_i32 s48, s31, 0xc000
	s_add_i32 s49, s31, 0xe000
	s_add_i32 s51, s50, 0x2000
	s_add_i32 s53, s52, 0x2000
	s_add_i32 s55, s54, 0x2000
	s_add_i32 s57, s56, 0x2000
	s_barrier
	ds_read_b128 v[106:109], v100
	ds_read_b128 v[154:157], v100 offset:1024
	ds_read_b128 v[162:165], v100 offset:2048
	ds_read_b128 v[166:169], v100 offset:3072
	ds_read_b128 v[170:173], v101
	ds_read_b128 v[174:177], v101 offset:1024
	ds_read_b128 v[178:181], v101 offset:2048
	ds_read_b128 v[182:185], v101 offset:3072
	s_add_u32 s22, s18, s20
	s_addc_u32 s23, s19, s21
	s_add_u32 s22, s22, 0x3800100
	s_addc_u32 s23, s23, 0
	s_add_u32 s58, s45, s20
	s_addc_u32 s59, s46, s21
	s_cmpk_eq_i32 s20, 0x700
	s_cselect_b32 s25, s5, s23
	s_cselect_b32 s24, s4, s22
	s_cselect_b32 s23, s1, s59
	s_cselect_b32 s22, s0, s58
	s_mov_b32 m0, s48
	v_lshl_add_u64 v[110:111], v[96:97], 0, s[20:21]
	ds_read_b128 v[186:189], v102
	ds_read_b128 v[196:199], v102 offset:1024
	ds_read_b128 v[200:203], v102 offset:2048
	ds_read_b128 v[204:207], v102 offset:3072
	ds_read_b128 v[208:211], v102 offset:4096
	ds_read_b128 v[212:215], v102 offset:5120
	ds_read_b128 v[216:219], v102 offset:6144
	ds_read_b128 v[220:223], v102 offset:7168
	global_load_lds_dwordx4 v[110:111], off
	v_lshl_add_u64 v[110:111], v[98:99], 0, s[20:21]
	s_mov_b32 m0, s49
	s_nop 0
	global_load_lds_dwordx4 v[110:111], off
	s_waitcnt vmcnt(8)
	s_waitcnt lgkmcnt(0)
	s_barrier
	s_setprio 1
	s_waitcnt lgkmcnt(0)
	v_mfma_f32_16x16x32_bf16 v[140:143], v[106:109], v[186:189], 0
	v_mfma_f32_16x16x32_bf16 v[136:139], v[162:165], v[186:189], 0
	v_mfma_f32_16x16x32_bf16 v[124:127], v[106:109], v[200:203], 0
	v_mfma_f32_16x16x32_bf16 v[120:123], v[162:165], v[200:203], 0
	v_mfma_f32_16x16x32_bf16 v[92:95], v[106:109], v[208:211], 0
	v_mfma_f32_16x16x32_bf16 v[88:91], v[162:165], v[208:211], 0
	v_mfma_f32_16x16x32_bf16 v[76:79], v[106:109], v[216:219], 0
	v_mfma_f32_16x16x32_bf16 v[72:75], v[162:165], v[216:219], 0
	v_mfma_f32_16x16x32_bf16 v[140:143], v[154:157], v[196:199], v[140:143]
	v_mfma_f32_16x16x32_bf16 v[136:139], v[166:169], v[196:199], v[136:139]
	v_mfma_f32_16x16x32_bf16 v[124:127], v[154:157], v[204:207], v[124:127]
	v_mfma_f32_16x16x32_bf16 v[120:123], v[166:169], v[204:207], v[120:123]
	v_mfma_f32_16x16x32_bf16 v[92:95], v[154:157], v[212:215], v[92:95]
	v_mfma_f32_16x16x32_bf16 v[88:91], v[166:169], v[212:215], v[88:91]
	v_mfma_f32_16x16x32_bf16 v[76:79], v[154:157], v[220:223], v[76:79]
	v_mfma_f32_16x16x32_bf16 v[72:75], v[166:169], v[220:223], v[72:75]
	s_setprio 0
	s_setprio 1
	v_mfma_f32_16x16x32_bf16 v[132:135], v[170:173], v[186:189], 0
	v_mfma_f32_16x16x32_bf16 v[128:131], v[178:181], v[186:189], 0
	v_mfma_f32_16x16x32_bf16 v[116:119], v[170:173], v[200:203], 0
	v_mfma_f32_16x16x32_bf16 v[110:113], v[178:181], v[200:203], 0
	v_mfma_f32_16x16x32_bf16 v[84:87], v[170:173], v[208:211], 0
	v_mfma_f32_16x16x32_bf16 v[80:83], v[178:181], v[208:211], 0
	v_mfma_f32_16x16x32_bf16 v[68:71], v[170:173], v[216:219], 0
	v_mfma_f32_16x16x32_bf16 v[64:67], v[178:181], v[216:219], 0
	v_mfma_f32_16x16x32_bf16 v[132:135], v[174:177], v[196:199], v[132:135]
	v_mfma_f32_16x16x32_bf16 v[128:131], v[182:185], v[196:199], v[128:131]
	v_mfma_f32_16x16x32_bf16 v[116:119], v[174:177], v[204:207], v[116:119]
	v_mfma_f32_16x16x32_bf16 v[110:113], v[182:185], v[204:207], v[110:113]
	v_mfma_f32_16x16x32_bf16 v[84:87], v[174:177], v[212:215], v[84:87]
	v_mfma_f32_16x16x32_bf16 v[80:83], v[182:185], v[212:215], v[80:83]
	v_mfma_f32_16x16x32_bf16 v[68:71], v[174:177], v[220:223], v[68:71]
	v_mfma_f32_16x16x32_bf16 v[64:67], v[182:185], v[220:223], v[64:67]
	s_setprio 0
	s_barrier
; #define PG8_STAGE(bufoff, gbase, voff) do { _Pragma("unroll") for (int _i = 0; _i < 2; ++_i) \
;         __builtin_amdgcn_global_load_lds((const unsigned*)((const char*)(gbase) + (voff)[_i]), (PG8_LAS unsigned*)(lds + (bufoff) + ldsw + _i * 8192), 16, 0, 0); } while (0)
; #define PG8_LDA(dst, b, h) do { _Pragma("unroll") for (int m = 0; m < 4; ++m) _Pragma("unroll") for (int k = 0; k < 2; ++k) dst[m][k] = *(const PG8_LAS bf16x8*)(lds + PG8_SA(b, h) + aoff + m * 2048 + k * 1024); } while (0)
; #define PG8_LDB(dst, b, h) do { _Pragma("unroll") for (int n = 0; n < 2; ++n) _Pragma("unroll") for (int k = 0; k < 2; ++k) dst[n][k] = *(const PG8_LAS bf16x8*)(lds + PG8_SB(b, h) + boff + n * 2048 + k * 1024); } while (0)
; #define PG8_MMA(ai, bj, At, Bt) do { __builtin_amdgcn_s_setprio(1); _Pragma("unroll") for (int m = 0; m < 4; ++m) _Pragma("unroll") for (int n = 0; n < 2; ++n) _Pragma("unroll") for (int k = 0; k < 2; ++k) \
;         acc[ai][bj][m][n] = __builtin_amdgcn_mfma_f32_16x16x32_bf16(Bt[n][k], At[m][k], acc[ai][bj][m][n], 0, 0, 0); __builtin_amdgcn_s_setprio(0); } while (0)
; #define PG8_WAIT_V(n) asm volatile("s_waitcnt vmcnt(" #n ")" ::: "memory")
; #define PG8_WAIT_L(n) asm volatile("s_waitcnt lgkmcnt(" #n ")" ::: "memory")
; #define PG8_BAR __builtin_amdgcn_s_barrier()
; #define PG8_SCHED __builtin_amdgcn_sched_barrier(0)
; template <class Epi, class Sched, bool ALIGN_EPI = false, bool SP2 = false>
; __device__ __forceinline__ void gemm_phase(PG8_LAS unsigned char* lds, const Gemm g, const Sched& S, const Epi& E) {
;     ...
;             PG8_LDA(At, 0, 1); PG8_STAGE(PG8_SB(0, 0), b2, voffB); PG8_STAGE(PG8_SB(0, 1), b2 + hstepB, voffB); PG8_STAGE(PG8_SA(0, 0), a2, voffA);
;             PG8_WAIT_V(8); PG8_WAIT_L(0); PG8_BAR; PG8_MMA(1, 0, At, B0); PG8_MMA(1, 1, At, B1); PG8_BAR; PG8_SCHED;
;             PG8_LDB(B0, 1, 0); PG8_LDB(B1, 1, 1); PG8_SCHED; PG8_LDA(At, 1, 0); PG8_STAGE(PG8_SA(0, 1), a2 + hstepA, voffA);
;             PG8_WAIT_V(8); PG8_WAIT_L(0); PG8_BAR; PG8_MMA(0, 0, At, B0); PG8_MMA(0, 1, At, B1); PG8_BAR; PG8_SCHED;
	s_mov_b32 m0, s50
	v_lshl_add_u64 v[158:159], s[22:23], 0, v[146:147]
	s_add_u32 s58, s22, 0x40000
	ds_read_b128 v[186:189], v102 offset:16384
	ds_read_b128 v[196:199], v102 offset:17408
	ds_read_b128 v[200:203], v102 offset:18432
	ds_read_b128 v[204:207], v102 offset:19456
	ds_read_b128 v[208:211], v102 offset:20480
	ds_read_b128 v[212:215], v102 offset:21504
	ds_read_b128 v[216:219], v102 offset:22528
	ds_read_b128 v[220:223], v102 offset:23552
	global_load_lds_dwordx4 v[158:159], off
	v_lshl_add_u64 v[190:191], s[22:23], 0, v[150:151]
	s_mov_b32 m0, s51
	s_addc_u32 s59, s23, 0
	global_load_lds_dwordx4 v[190:191], off
	v_lshl_add_u64 v[114:115], s[58:59], 0, v[146:147]
	s_mov_b32 m0, s52
	v_lshl_add_u64 v[224:225], s[24:25], 0, v[144:145]
	global_load_lds_dwordx4 v[114:115], off
	v_lshl_add_u64 v[114:115], s[58:59], 0, v[150:151]
	s_mov_b32 m0, s53
	v_lshl_add_u64 v[226:227], s[24:25], 0, v[148:149]
	global_load_lds_dwordx4 v[114:115], off
	s_mov_b32 m0, s31
	s_nop 0
	global_load_lds_dwordx4 v[224:225], off
	s_mov_b32 m0, s40
	s_nop 0
	global_load_lds_dwordx4 v[226:227], off
	s_waitcnt vmcnt(8)
	s_waitcnt lgkmcnt(0)
	s_barrier
	s_setprio 1
	s_waitcnt lgkmcnt(0)
	v_mfma_f32_16x16x32_bf16 v[60:63], v[106:109], v[186:189], 0
	v_mfma_f32_16x16x32_bf16 v[56:59], v[162:165], v[186:189], 0
	v_mfma_f32_16x16x32_bf16 v[44:47], v[106:109], v[200:203], 0
	v_mfma_f32_16x16x32_bf16 v[40:43], v[162:165], v[200:203], 0
	v_mfma_f32_16x16x32_bf16 v[28:31], v[106:109], v[208:211], 0
	v_mfma_f32_16x16x32_bf16 v[24:27], v[162:165], v[208:211], 0
	v_mfma_f32_16x16x32_bf16 v[12:15], v[106:109], v[216:219], 0
	v_mfma_f32_16x16x32_bf16 v[8:11], v[162:165], v[216:219], 0
	v_mfma_f32_16x16x32_bf16 v[60:63], v[154:157], v[196:199], v[60:63]
	v_mfma_f32_16x16x32_bf16 v[56:59], v[166:169], v[196:199], v[56:59]
	v_mfma_f32_16x16x32_bf16 v[44:47], v[154:157], v[204:207], v[44:47]
	v_mfma_f32_16x16x32_bf16 v[40:43], v[166:169], v[204:207], v[40:43]
	v_mfma_f32_16x16x32_bf16 v[28:31], v[154:157], v[212:215], v[28:31]
	v_mfma_f32_16x16x32_bf16 v[24:27], v[166:169], v[212:215], v[24:27]
	v_mfma_f32_16x16x32_bf16 v[12:15], v[154:157], v[220:223], v[12:15]
	v_mfma_f32_16x16x32_bf16 v[8:11], v[166:169], v[220:223], v[8:11]
	s_setprio 0
	s_setprio 1
	v_mfma_f32_16x16x32_bf16 v[52:55], v[170:173], v[186:189], 0
	v_mfma_f32_16x16x32_bf16 v[48:51], v[178:181], v[186:189], 0
	v_mfma_f32_16x16x32_bf16 v[36:39], v[170:173], v[200:203], 0
	v_mfma_f32_16x16x32_bf16 v[32:35], v[178:181], v[200:203], 0
	v_mfma_f32_16x16x32_bf16 v[20:23], v[170:173], v[208:211], 0
	v_mfma_f32_16x16x32_bf16 v[16:19], v[178:181], v[208:211], 0
	v_mfma_f32_16x16x32_bf16 v[4:7], v[170:173], v[216:219], 0
	v_mfma_f32_16x16x32_bf16 v[0:3], v[178:181], v[216:219], 0
	v_mfma_f32_16x16x32_bf16 v[52:55], v[174:177], v[196:199], v[52:55]
	v_mfma_f32_16x16x32_bf16 v[48:51], v[182:185], v[196:199], v[48:51]
	v_mfma_f32_16x16x32_bf16 v[36:39], v[174:177], v[204:207], v[36:39]
	v_mfma_f32_16x16x32_bf16 v[32:35], v[182:185], v[204:207], v[32:35]
	v_mfma_f32_16x16x32_bf16 v[20:23], v[174:177], v[212:215], v[20:23]
	v_mfma_f32_16x16x32_bf16 v[16:19], v[182:185], v[212:215], v[16:19]
	v_mfma_f32_16x16x32_bf16 v[4:7], v[174:177], v[220:223], v[4:7]
	v_mfma_f32_16x16x32_bf16 v[0:3], v[182:185], v[220:223], v[0:3]
	s_setprio 0
	s_barrier
	ds_read_b128 v[106:109], v103
	ds_read_b128 v[154:157], v103 offset:1024
	ds_read_b128 v[162:165], v103 offset:2048
	ds_read_b128 v[166:169], v103 offset:3072
	ds_read_b128 v[170:173], v104
	ds_read_b128 v[174:177], v104 offset:1024
	ds_read_b128 v[178:181], v104 offset:2048
	ds_read_b128 v[182:185], v104 offset:3072
	s_add_u32 s24, s24, 0x40000
	s_addc_u32 s25, s25, 0
	s_mov_b32 m0, s41
	v_lshl_add_u64 v[114:115], s[24:25], 0, v[144:145]
	ds_read_b128 v[186:189], v102 offset:32768
	ds_read_b128 v[196:199], v102 offset:33792
	ds_read_b128 v[200:203], v102 offset:34816
	ds_read_b128 v[204:207], v102 offset:35840
	ds_read_b128 v[208:211], v102 offset:36864
	ds_read_b128 v[212:215], v102 offset:37888
	ds_read_b128 v[216:219], v102 offset:38912
	ds_read_b128 v[220:223], v102 offset:39936
	global_load_lds_dwordx4 v[114:115], off
	v_lshl_add_u64 v[114:115], s[24:25], 0, v[148:149]
	s_mov_b32 m0, s42
	s_nop 0
	global_load_lds_dwordx4 v[114:115], off
	s_waitcnt vmcnt(8)
	s_waitcnt lgkmcnt(0)
	s_barrier
; #define PG8_STAGE(bufoff, gbase, voff) do { _Pragma("unroll") for (int _i = 0; _i < 2; ++_i) \
;         __builtin_amdgcn_global_load_lds((const unsigned*)((const char*)(gbase) + (voff)[_i]), (PG8_LAS unsigned*)(lds + (bufoff) + ldsw + _i * 8192), 16, 0, 0); } while (0)
; #define PG8_LDA(dst, b, h) do { _Pragma("unroll") for (int m = 0; m < 4; ++m) _Pragma("unroll") for (int k = 0; k < 2; ++k) dst[m][k] = *(const PG8_LAS bf16x8*)(lds + PG8_SA(b, h) + aoff + m * 2048 + k * 1024); } while (0)
; #define PG8_MMA(ai, bj, At, Bt) do { __builtin_amdgcn_s_setprio(1); _Pragma("unroll") for (int m = 0; m < 4; ++m) _Pragma("unroll") for (int n = 0; n < 2; ++n) _Pragma("unroll") for (int k = 0; k < 2; ++k) \
;         acc[ai][bj][m][n] = __builtin_amdgcn_mfma_f32_16x16x32_bf16(Bt[n][k], At[m][k], acc[ai][bj][m][n], 0, 0, 0); __builtin_amdgcn_s_setprio(0); } while (0)
; #define PG8_WAIT_V(n) asm volatile("s_waitcnt vmcnt(" #n ")" ::: "memory")
; #define PG8_WAIT_L(n) asm volatile("s_waitcnt lgkmcnt(" #n ")" ::: "memory")
; #define PG8_BAR __builtin_amdgcn_s_barrier()
; #define PG8_SCHED __builtin_amdgcn_sched_barrier(0)
; template <class Epi, class Sched, bool ALIGN_EPI = false, bool SP2 = false>
; __device__ __forceinline__ void gemm_phase(PG8_LAS unsigned char* lds, const Gemm g, const Sched& S, const Epi& E) {
;     ...
;         for (int t = 0; t < nt; t += 2) {
;     ...
;             PG8_WAIT_V(8); PG8_WAIT_L(0); PG8_BAR; PG8_MMA(0, 0, At, B0); PG8_MMA(0, 1, At, B1); PG8_BAR; PG8_SCHED;
;             PG8_LDA(At, 1, 1); PG8_STAGE(PG8_SB(1, 0), b3, voffB); PG8_STAGE(PG8_SB(1, 1), b3 + hstepB, voffB); PG8_STAGE(PG8_SA(1, 0), a3, voffA);
;             PG8_WAIT_V(8); PG8_WAIT_L(0); PG8_BAR; PG8_MMA(1, 0, At, B0); PG8_MMA(1, 1, At, B1); PG8_BAR; PG8_SCHED;
	s_setprio 1
	s_waitcnt lgkmcnt(0)
	v_mfma_f32_16x16x32_bf16 v[140:143], v[106:109], v[186:189], v[140:143]
	v_mfma_f32_16x16x32_bf16 v[136:139], v[162:165], v[186:189], v[136:139]
	v_mfma_f32_16x16x32_bf16 v[124:127], v[106:109], v[200:203], v[124:127]
	v_mfma_f32_16x16x32_bf16 v[120:123], v[162:165], v[200:203], v[120:123]
	v_mfma_f32_16x16x32_bf16 v[92:95], v[106:109], v[208:211], v[92:95]
	v_mfma_f32_16x16x32_bf16 v[88:91], v[162:165], v[208:211], v[88:91]
	v_mfma_f32_16x16x32_bf16 v[76:79], v[106:109], v[216:219], v[76:79]
	v_mfma_f32_16x16x32_bf16 v[72:75], v[162:165], v[216:219], v[72:75]
	v_mfma_f32_16x16x32_bf16 v[140:143], v[154:157], v[196:199], v[140:143]
	v_mfma_f32_16x16x32_bf16 v[136:139], v[166:169], v[196:199], v[136:139]
	v_mfma_f32_16x16x32_bf16 v[124:127], v[154:157], v[204:207], v[124:127]
	v_mfma_f32_16x16x32_bf16 v[120:123], v[166:169], v[204:207], v[120:123]
	v_mfma_f32_16x16x32_bf16 v[92:95], v[154:157], v[212:215], v[92:95]
	v_mfma_f32_16x16x32_bf16 v[88:91], v[166:169], v[212:215], v[88:91]
	v_mfma_f32_16x16x32_bf16 v[76:79], v[154:157], v[220:223], v[76:79]
	v_mfma_f32_16x16x32_bf16 v[72:75], v[166:169], v[220:223], v[72:75]
	s_setprio 0
	s_setprio 1
	v_mfma_f32_16x16x32_bf16 v[132:135], v[170:173], v[186:189], v[132:135]
	v_mfma_f32_16x16x32_bf16 v[128:131], v[178:181], v[186:189], v[128:131]
	v_mfma_f32_16x16x32_bf16 v[114:117], v[170:173], v[200:203], v[116:119]
	v_mfma_f32_16x16x32_bf16 v[110:113], v[178:181], v[200:203], v[110:113]
	v_mfma_f32_16x16x32_bf16 v[84:87], v[170:173], v[208:211], v[84:87]
	v_mfma_f32_16x16x32_bf16 v[80:83], v[178:181], v[208:211], v[80:83]
	v_mfma_f32_16x16x32_bf16 v[68:71], v[170:173], v[216:219], v[68:71]
	v_mfma_f32_16x16x32_bf16 v[64:67], v[178:181], v[216:219], v[64:67]
	v_mfma_f32_16x16x32_bf16 v[132:135], v[174:177], v[196:199], v[132:135]
	v_mfma_f32_16x16x32_bf16 v[128:131], v[182:185], v[196:199], v[128:131]
	v_mfma_f32_16x16x32_bf16 v[116:119], v[174:177], v[204:207], v[114:117]
	v_mfma_f32_16x16x32_bf16 v[112:115], v[182:185], v[204:207], v[110:113]
	v_mfma_f32_16x16x32_bf16 v[84:87], v[174:177], v[212:215], v[84:87]
	v_mfma_f32_16x16x32_bf16 v[80:83], v[182:185], v[212:215], v[80:83]
	v_mfma_f32_16x16x32_bf16 v[68:71], v[174:177], v[220:223], v[68:71]
	v_mfma_f32_16x16x32_bf16 v[64:67], v[182:185], v[220:223], v[64:67]
	s_setprio 0
	s_barrier
	s_mov_b32 m0, s54
	v_lshl_add_u64 v[110:111], v[158:159], 0, s[6:7]
	s_add_u32 s22, s22, 0x40080
	ds_read_b128 v[186:189], v102 offset:49152
	ds_read_b128 v[196:199], v102 offset:50176
	ds_read_b128 v[200:203], v102 offset:51200
	ds_read_b128 v[204:207], v102 offset:52224
	ds_read_b128 v[208:211], v102 offset:53248
	ds_read_b128 v[212:215], v102 offset:54272
	ds_read_b128 v[216:219], v102 offset:55296
	ds_read_b128 v[220:223], v102 offset:56320
	global_load_lds_dwordx4 v[110:111], off
	v_lshl_add_u64 v[110:111], v[190:191], 0, s[6:7]
	s_mov_b32 m0, s55
	s_addc_u32 s23, s23, 0
	global_load_lds_dwordx4 v[110:111], off
	v_lshl_add_u64 v[110:111], s[22:23], 0, v[146:147]
	s_mov_b32 m0, s56
	s_nop 0
	global_load_lds_dwordx4 v[110:111], off
	v_lshl_add_u64 v[110:111], s[22:23], 0, v[150:151]
	s_mov_b32 m0, s57
	s_nop 0
	global_load_lds_dwordx4 v[110:111], off
	v_lshl_add_u64 v[110:111], v[224:225], 0, s[6:7]
	s_mov_b32 m0, s43
	s_nop 0
	global_load_lds_dwordx4 v[110:111], off
	v_lshl_add_u64 v[110:111], v[226:227], 0, s[6:7]
	s_mov_b32 m0, s44
	s_nop 0
	global_load_lds_dwordx4 v[110:111], off
	s_waitcnt vmcnt(8)
	s_waitcnt lgkmcnt(0)
	s_barrier
	s_setprio 1
	s_waitcnt lgkmcnt(0)
	v_mfma_f32_16x16x32_bf16 v[60:63], v[106:109], v[186:189], v[60:63]
	v_mfma_f32_16x16x32_bf16 v[56:59], v[162:165], v[186:189], v[56:59]
	v_mfma_f32_16x16x32_bf16 v[44:47], v[106:109], v[200:203], v[44:47]
	v_mfma_f32_16x16x32_bf16 v[40:43], v[162:165], v[200:203], v[40:43]
	v_mfma_f32_16x16x32_bf16 v[28:31], v[106:109], v[208:211], v[28:31]
	v_mfma_f32_16x16x32_bf16 v[24:27], v[162:165], v[208:211], v[24:27]
	v_mfma_f32_16x16x32_bf16 v[12:15], v[106:109], v[216:219], v[12:15]
	v_mfma_f32_16x16x32_bf16 v[8:11], v[162:165], v[216:219], v[8:11]
	v_mfma_f32_16x16x32_bf16 v[60:63], v[154:157], v[196:199], v[60:63]
	v_mfma_f32_16x16x32_bf16 v[56:59], v[166:169], v[196:199], v[56:59]
	v_mfma_f32_16x16x32_bf16 v[44:47], v[154:157], v[204:207], v[44:47]
	v_mfma_f32_16x16x32_bf16 v[40:43], v[166:169], v[204:207], v[40:43]
	v_mfma_f32_16x16x32_bf16 v[28:31], v[154:157], v[212:215], v[28:31]
	v_mfma_f32_16x16x32_bf16 v[24:27], v[166:169], v[212:215], v[24:27]
	v_mfma_f32_16x16x32_bf16 v[12:15], v[154:157], v[220:223], v[12:15]
	v_mfma_f32_16x16x32_bf16 v[8:11], v[166:169], v[220:223], v[8:11]
	s_setprio 0
	s_setprio 1
	v_mfma_f32_16x16x32_bf16 v[52:55], v[170:173], v[186:189], v[52:55]
	v_mfma_f32_16x16x32_bf16 v[48:51], v[178:181], v[186:189], v[48:51]
	v_mfma_f32_16x16x32_bf16 v[36:39], v[170:173], v[200:203], v[36:39]
	v_mfma_f32_16x16x32_bf16 v[32:35], v[178:181], v[200:203], v[32:35]
	v_mfma_f32_16x16x32_bf16 v[20:23], v[170:173], v[208:211], v[20:23]
	v_mfma_f32_16x16x32_bf16 v[16:19], v[178:181], v[208:211], v[16:19]
	v_mfma_f32_16x16x32_bf16 v[4:7], v[170:173], v[216:219], v[4:7]
	v_mfma_f32_16x16x32_bf16 v[0:3], v[178:181], v[216:219], v[0:3]
	v_mfma_f32_16x16x32_bf16 v[52:55], v[174:177], v[196:199], v[52:55]
	v_mfma_f32_16x16x32_bf16 v[48:51], v[182:185], v[196:199], v[48:51]
	v_mfma_f32_16x16x32_bf16 v[36:39], v[174:177], v[204:207], v[36:39]
	v_mfma_f32_16x16x32_bf16 v[32:35], v[182:185], v[204:207], v[32:35]
	v_mfma_f32_16x16x32_bf16 v[20:23], v[174:177], v[212:215], v[20:23]
	v_mfma_f32_16x16x32_bf16 v[16:19], v[182:185], v[212:215], v[16:19]
	v_mfma_f32_16x16x32_bf16 v[4:7], v[174:177], v[220:223], v[4:7]
	v_mfma_f32_16x16x32_bf16 v[0:3], v[182:185], v[220:223], v[0:3]
	s_setprio 0
	s_barrier
	s_add_i32 s47, s47, 2
	s_add_u32 s20, s20, 0x100
	s_addc_u32 s21, s21, 0

; #define PG8_STAGE(bufoff, gbase, voff) do { _Pragma("unroll") for (int _i = 0; _i < 2; ++_i) \
;         __builtin_amdgcn_global_load_lds((const unsigned*)((const char*)(gbase) + (voff)[_i]), (PG8_LAS unsigned*)(lds + (bufoff) + ldsw + _i * 8192), 16, 0, 0); } while (0)
; #define PG8_LDA(dst, b, h) do { _Pragma("unroll") for (int m = 0; m < 4; ++m) _Pragma("unroll") for (int k = 0; k < 2; ++k) dst[m][k] = *(const PG8_LAS bf16x8*)(lds + PG8_SA(b, h) + aoff + m * 2048 + k * 1024); } while (0)
; #define PG8_WAIT_V(n) asm volatile("s_waitcnt vmcnt(" #n ")" ::: "memory")
; #define PG8_WAIT_L(n) asm volatile("s_waitcnt lgkmcnt(" #n ")" ::: "memory")
; template <class Epi, class Sched, bool ALIGN_EPI = false, bool SP2 = false>
; __device__ __forceinline__ void gemm_phase(PG8_LAS unsigned char* lds, const Gemm g, const Sched& S, const Epi& E) {
;     ...
;         PG8_WAIT_V(2); PG8_BAR;
;         PG8_STAGE(PG8_SB(1, 0), cB + kstep, voffB); PG8_STAGE(PG8_SA(1, 0), cA + kstep, voffA); PG8_STAGE(PG8_SB(1, 1), cB + hstepB + kstep, voffB);
;         PG8_WAIT_V(6); PG8_BAR;
;     } else {
;         PG8_STAGE(PG8_SB(0, 0), cB, voffB); PG8_STAGE(PG8_SA(0, 0), cA, voffA); PG8_STAGE(PG8_SB(0, 1), cB + hstepB, voffB); PG8_STAGE(PG8_SA(0, 1), cA + hstepA, voffA);
;         if (wr == 1) PG8_BAR;
;         PG8_WAIT_V(4); PG8_BAR;
;         PG8_STAGE(PG8_SB(1, 0), cB + kstep, voffB); PG8_STAGE(PG8_SA(1, 0), cA + kstep, voffA); PG8_STAGE(PG8_SB(1, 1), cB + hstepB + kstep, voffB);
;         PG8_WAIT_V(6); PG8_BAR;
;     }
;     for (;;) {
;         const bool has_next = S.next(ui + 1, nxt);
;         const char* nA = has_next ? PG8_UA(nxt) : cA; const char* nB = has_next ? PG8_UB(nxt) : cB;
;         for (int t = 0; t < nt; t += 2) {
;             const bool last = (t == nt - 2);
;             const char* a1 = cA + (size_t)(t + 1) * kstep;
;             const char* a2 = last ? nA : cA + (size_t)(t + 2) * kstep; const char* b2 = last ? nB : cB + (size_t)(t + 2) * kstep;
;             const char* a3 = a2 + kstep; const char* b3 = b2 + kstep;
;             if (last && has_next) S.a_ready(nxt);
;             if constexpr (SP2) {
;             PG8_LDB(B0, 0, 0); PG8_LDB(B1, 0, 1); PG8_SCHED; PG8_LDA(At, 0, 0); PG8_STAGE(PG8_SA(1, 1), a1 + hstepA, voffA);
;             PG8_WAIT_V(8); PG8_WAIT_L(0); PG8_BAR; PG8_MMA(0, 0, At, B0); PG8_MMA(0, 1, At, B1); PG8_BAR; PG8_SCHED;
.LBB0_1120:
	v_lshlrev_b32_e32 v9, 2, v161
	s_and_b32 s37, s6, 3
	v_lshl_or_b32 v8, v161, 6, v166
	s_lshl_b32 s6, s2, 13
	v_and_b32_e32 v9, 32, v9
	v_bitop3_b32 v8, v8, s6, v9 bitop3:0xde
	s_mov_b64 s[6:7], 0x80
	s_add_i32 m0, s3, 0x18000
	v_lshl_add_u64 v[6:7], v[6:7], 0, s[6:7]
	s_waitcnt vmcnt(2)
	s_barrier
	global_load_lds_dwordx4 v[6:7], off
	v_lshl_add_u64 v[4:5], v[4:5], 0, s[6:7]
	s_add_i32 m0, s3, 0x1a000
	s_add_i32 s43, s3, 0x8000
	s_add_i32 s44, s3, 0xa000
	global_load_lds_dwordx4 v[4:5], off
	v_lshl_add_u64 v[2:3], v[2:3], 0, s[6:7]
	s_mov_b32 m0, s43
	s_add_u32 s22, s0, 0xb0080
	global_load_lds_dwordx4 v[2:3], off
	v_lshl_add_u64 v[0:1], v[0:1], 0, s[6:7]
	s_mov_b32 m0, s44
	s_addc_u32 s23, s1, 0
	global_load_lds_dwordx4 v[0:1], off
	s_add_i32 m0, s3, 0x1c000
	v_lshl_add_u64 v[0:1], s[22:23], 0, v[146:147]
	global_load_lds_dwordx4 v[0:1], off
	v_lshl_add_u64 v[0:1], s[22:23], 0, v[150:151]
	s_add_i32 m0, s3, 0x1e000
	s_add_u32 s22, s34, s19
	global_load_lds_dwordx4 v[0:1], off
	v_add_u16_e32 v0, v162, v163
	v_lshrrev_b16_e32 v2, 1, v0
	v_lshl_or_b32 v9, s37, 12, v167
	s_waitcnt vmcnt(6)
	v_add_lshl_u32 v0, v164, v2, 1
	v_mov_b32_e32 v1, v147
	s_addc_u32 s23, s35, s18
	s_add_i32 s48, 0, 0x10000
	s_add_i32 s50, 0, 0x14000
	s_add_i32 s52, 0, 0x18000
	s_add_i32 s54, 0, 0x1c000
	v_lshl_add_u64 v[96:97], s[22:23], 0, v[0:1]
	v_add_lshl_u32 v0, v165, v2, 1
	v_add_u32_e32 v100, s48, v9
	v_add_u32_e32 v101, s50, v9
	s_add_i32 s48, s48, s20
	s_add_i32 s50, s50, s20
	v_add_u32_e32 v103, s52, v9
	v_add_u32_e32 v104, s54, v9
	s_add_i32 s52, s52, s20
	s_add_i32 s54, s54, s20
	v_lshl_or_b32 v152, s2, 6, v161
	v_lshl_add_u64 v[98:99], s[22:23], 0, v[0:1]
	s_mov_b32 s45, -2
	s_mov_b64 s[18:19], 0x78b4080
	v_add_u32_e32 v102, 0, v8
	s_add_i32 s46, s3, 0xc000
	s_add_i32 s47, s3, 0xe000
	s_add_i32 s49, s48, 0x2000
	s_add_i32 s51, s50, 0x2000
	s_add_i32 s53, s52, 0x2000
	s_add_i32 s55, s54, 0x2000
	s_barrier
	ds_read_b128 v[106:109], v100
	ds_read_b128 v[154:157], v100 offset:1024
	ds_read_b128 v[168:171], v100 offset:2048
	ds_read_b128 v[172:175], v100 offset:3072
	ds_read_b128 v[176:179], v101
	ds_read_b128 v[180:183], v101 offset:1024
	ds_read_b128 v[184:187], v101 offset:2048
	ds_read_b128 v[188:191], v101 offset:3072
	s_add_u32 s20, s18, 0xf874c080
	s_addc_u32 s21, s19, -1
	s_cmp_lg_u32 s45, 40
	s_cselect_b32 s20, s20, 0
	s_cselect_b32 s21, s21, 0
	s_add_u32 s22, s4, s20
	s_addc_u32 s23, s5, s21
	s_add_u32 s20, s0, s20
	s_addc_u32 s21, s1, s21
	s_mov_b32 m0, s46
	v_lshl_add_u64 v[110:111], v[96:97], 0, s[18:19]
	ds_read_b128 v[196:199], v102
	ds_read_b128 v[200:203], v102 offset:1024
	ds_read_b128 v[204:207], v102 offset:2048
	ds_read_b128 v[208:211], v102 offset:3072
	ds_read_b128 v[212:215], v102 offset:4096
	ds_read_b128 v[216:219], v102 offset:5120
	ds_read_b128 v[220:223], v102 offset:6144
	ds_read_b128 v[224:227], v102 offset:7168
	global_load_lds_dwordx4 v[110:111], off
	v_lshl_add_u64 v[110:111], v[98:99], 0, s[18:19]
	s_mov_b32 m0, s47
	s_nop 0
	global_load_lds_dwordx4 v[110:111], off
	s_waitcnt vmcnt(8)
	s_waitcnt lgkmcnt(0)
	s_barrier
	s_setprio 1
	s_waitcnt lgkmcnt(0)
	v_mfma_f32_16x16x32_bf16 v[140:143], v[106:109], v[196:199], 0
	v_mfma_f32_16x16x32_bf16 v[136:139], v[168:171], v[196:199], 0
	v_mfma_f32_16x16x32_bf16 v[124:127], v[106:109], v[204:207], 0
	v_mfma_f32_16x16x32_bf16 v[120:123], v[168:171], v[204:207], 0
	v_mfma_f32_16x16x32_bf16 v[92:95], v[106:109], v[212:215], 0
	v_mfma_f32_16x16x32_bf16 v[88:91], v[168:171], v[212:215], 0
	v_mfma_f32_16x16x32_bf16 v[76:79], v[106:109], v[220:223], 0
	v_mfma_f32_16x16x32_bf16 v[72:75], v[168:171], v[220:223], 0
	v_mfma_f32_16x16x32_bf16 v[140:143], v[154:157], v[200:203], v[140:143]
	v_mfma_f32_16x16x32_bf16 v[136:139], v[172:175], v[200:203], v[136:139]
	v_mfma_f32_16x16x32_bf16 v[124:127], v[154:157], v[208:211], v[124:127]
	v_mfma_f32_16x16x32_bf16 v[120:123], v[172:175], v[208:211], v[120:123]
	v_mfma_f32_16x16x32_bf16 v[92:95], v[154:157], v[216:219], v[92:95]
	v_mfma_f32_16x16x32_bf16 v[88:91], v[172:175], v[216:219], v[88:91]
	v_mfma_f32_16x16x32_bf16 v[76:79], v[154:157], v[224:227], v[76:79]
	v_mfma_f32_16x16x32_bf16 v[72:75], v[172:175], v[224:227], v[72:75]
	s_setprio 0
	s_setprio 1
	v_mfma_f32_16x16x32_bf16 v[132:135], v[176:179], v[196:199], 0
	v_mfma_f32_16x16x32_bf16 v[128:131], v[184:187], v[196:199], 0
	v_mfma_f32_16x16x32_bf16 v[116:119], v[176:179], v[204:207], 0
	v_mfma_f32_16x16x32_bf16 v[110:113], v[184:187], v[204:207], 0
	v_mfma_f32_16x16x32_bf16 v[84:87], v[176:179], v[212:215], 0
	v_mfma_f32_16x16x32_bf16 v[80:83], v[184:187], v[212:215], 0
	v_mfma_f32_16x16x32_bf16 v[68:71], v[176:179], v[220:223], 0
	v_mfma_f32_16x16x32_bf16 v[64:67], v[184:187], v[220:223], 0
	v_mfma_f32_16x16x32_bf16 v[132:135], v[180:183], v[200:203], v[132:135]
	v_mfma_f32_16x16x32_bf16 v[128:131], v[188:191], v[200:203], v[128:131]
	v_mfma_f32_16x16x32_bf16 v[116:119], v[180:183], v[208:211], v[116:119]
	v_mfma_f32_16x16x32_bf16 v[110:113], v[188:191], v[208:211], v[110:113]
	v_mfma_f32_16x16x32_bf16 v[84:87], v[180:183], v[216:219], v[84:87]
	v_mfma_f32_16x16x32_bf16 v[80:83], v[188:191], v[216:219], v[80:83]
	v_mfma_f32_16x16x32_bf16 v[68:71], v[180:183], v[224:227], v[68:71]
	v_mfma_f32_16x16x32_bf16 v[64:67], v[188:191], v[224:227], v[64:67]
	s_setprio 0
	s_barrier
; #define PG8_STAGE(bufoff, gbase, voff) do { _Pragma("unroll") for (int _i = 0; _i < 2; ++_i) \
;         __builtin_amdgcn_global_load_lds((const unsigned*)((const char*)(gbase) + (voff)[_i]), (PG8_LAS unsigned*)(lds + (bufoff) + ldsw + _i * 8192), 16, 0, 0); } while (0)
; #define PG8_LDA(dst, b, h) do { _Pragma("unroll") for (int m = 0; m < 4; ++m) _Pragma("unroll") for (int k = 0; k < 2; ++k) dst[m][k] = *(const PG8_LAS bf16x8*)(lds + PG8_SA(b, h) + aoff + m * 2048 + k * 1024); } while (0)
; #define PG8_LDB(dst, b, h) do { _Pragma("unroll") for (int n = 0; n < 2; ++n) _Pragma("unroll") for (int k = 0; k < 2; ++k) dst[n][k] = *(const PG8_LAS bf16x8*)(lds + PG8_SB(b, h) + boff + n * 2048 + k * 1024); } while (0)
; #define PG8_MMA(ai, bj, At, Bt) do { __builtin_amdgcn_s_setprio(1); _Pragma("unroll") for (int m = 0; m < 4; ++m) _Pragma("unroll") for (int n = 0; n < 2; ++n) _Pragma("unroll") for (int k = 0; k < 2; ++k) \
;         acc[ai][bj][m][n] = __builtin_amdgcn_mfma_f32_16x16x32_bf16(Bt[n][k], At[m][k], acc[ai][bj][m][n], 0, 0, 0); __builtin_amdgcn_s_setprio(0); } while (0)
; #define PG8_WAIT_V(n) asm volatile("s_waitcnt vmcnt(" #n ")" ::: "memory")
; #define PG8_WAIT_L(n) asm volatile("s_waitcnt lgkmcnt(" #n ")" ::: "memory")
; #define PG8_BAR __builtin_amdgcn_s_barrier()
; #define PG8_SCHED __builtin_amdgcn_sched_barrier(0)
; template <class Epi, class Sched, bool ALIGN_EPI = false, bool SP2 = false>
; __device__ __forceinline__ void gemm_phase(PG8_LAS unsigned char* lds, const Gemm g, const Sched& S, const Epi& E) {
;     ...
;             PG8_LDA(At, 0, 1); PG8_STAGE(PG8_SB(0, 0), b2, voffB); PG8_STAGE(PG8_SB(0, 1), b2 + hstepB, voffB); PG8_STAGE(PG8_SA(0, 0), a2, voffA);
;             PG8_WAIT_V(8); PG8_WAIT_L(0); PG8_BAR; PG8_MMA(1, 0, At, B0); PG8_MMA(1, 1, At, B1); PG8_BAR; PG8_SCHED;
;             PG8_LDB(B0, 1, 0); PG8_LDB(B1, 1, 1); PG8_SCHED; PG8_LDA(At, 1, 0); PG8_STAGE(PG8_SA(0, 1), a2 + hstepA, voffA);
;             PG8_WAIT_V(8); PG8_WAIT_L(0); PG8_BAR; PG8_MMA(0, 0, At, B0); PG8_MMA(0, 1, At, B1); PG8_BAR; PG8_SCHED;
	s_mov_b32 m0, s48
	v_lshl_add_u64 v[158:159], s[20:21], 0, v[146:147]
	s_add_u32 s56, s20, 0xb0000
	ds_read_b128 v[196:199], v102 offset:16384
	ds_read_b128 v[200:203], v102 offset:17408
	ds_read_b128 v[204:207], v102 offset:18432
	ds_read_b128 v[208:211], v102 offset:19456
	ds_read_b128 v[212:215], v102 offset:20480
	ds_read_b128 v[216:219], v102 offset:21504
	ds_read_b128 v[220:223], v102 offset:22528
	ds_read_b128 v[224:227], v102 offset:23552
	global_load_lds_dwordx4 v[158:159], off
	v_lshl_add_u64 v[228:229], s[20:21], 0, v[150:151]
	s_mov_b32 m0, s49
	s_addc_u32 s57, s21, 0
	global_load_lds_dwordx4 v[228:229], off
	v_lshl_add_u64 v[114:115], s[56:57], 0, v[146:147]
	s_mov_b32 m0, s50
	v_lshl_add_u64 v[230:231], s[22:23], 0, v[144:145]
	global_load_lds_dwordx4 v[114:115], off
	v_lshl_add_u64 v[114:115], s[56:57], 0, v[150:151]
	s_mov_b32 m0, s51
	v_lshl_add_u64 v[232:233], s[22:23], 0, v[148:149]
	global_load_lds_dwordx4 v[114:115], off
	s_mov_b32 m0, s3
	s_nop 0
	global_load_lds_dwordx4 v[230:231], off
	s_mov_b32 m0, s40
	s_nop 0
	global_load_lds_dwordx4 v[232:233], off
	s_waitcnt vmcnt(8)
	s_waitcnt lgkmcnt(0)
	s_barrier
	s_setprio 1
	s_waitcnt lgkmcnt(0)
	v_mfma_f32_16x16x32_bf16 v[60:63], v[106:109], v[196:199], 0
	v_mfma_f32_16x16x32_bf16 v[56:59], v[168:171], v[196:199], 0
	v_mfma_f32_16x16x32_bf16 v[44:47], v[106:109], v[204:207], 0
	v_mfma_f32_16x16x32_bf16 v[40:43], v[168:171], v[204:207], 0
	v_mfma_f32_16x16x32_bf16 v[28:31], v[106:109], v[212:215], 0
	v_mfma_f32_16x16x32_bf16 v[24:27], v[168:171], v[212:215], 0
	v_mfma_f32_16x16x32_bf16 v[12:15], v[106:109], v[220:223], 0
	v_mfma_f32_16x16x32_bf16 v[8:11], v[168:171], v[220:223], 0
	v_mfma_f32_16x16x32_bf16 v[60:63], v[154:157], v[200:203], v[60:63]
	v_mfma_f32_16x16x32_bf16 v[56:59], v[172:175], v[200:203], v[56:59]
	v_mfma_f32_16x16x32_bf16 v[44:47], v[154:157], v[208:211], v[44:47]
	v_mfma_f32_16x16x32_bf16 v[40:43], v[172:175], v[208:211], v[40:43]
	v_mfma_f32_16x16x32_bf16 v[28:31], v[154:157], v[216:219], v[28:31]
	v_mfma_f32_16x16x32_bf16 v[24:27], v[172:175], v[216:219], v[24:27]
	v_mfma_f32_16x16x32_bf16 v[12:15], v[154:157], v[224:227], v[12:15]
	v_mfma_f32_16x16x32_bf16 v[8:11], v[172:175], v[224:227], v[8:11]
	s_setprio 0
	s_setprio 1
	v_mfma_f32_16x16x32_bf16 v[52:55], v[176:179], v[196:199], 0
	v_mfma_f32_16x16x32_bf16 v[48:51], v[184:187], v[196:199], 0
	v_mfma_f32_16x16x32_bf16 v[36:39], v[176:179], v[204:207], 0
	v_mfma_f32_16x16x32_bf16 v[32:35], v[184:187], v[204:207], 0
	v_mfma_f32_16x16x32_bf16 v[20:23], v[176:179], v[212:215], 0
	v_mfma_f32_16x16x32_bf16 v[16:19], v[184:187], v[212:215], 0
	v_mfma_f32_16x16x32_bf16 v[4:7], v[176:179], v[220:223], 0
	v_mfma_f32_16x16x32_bf16 v[0:3], v[184:187], v[220:223], 0
	v_mfma_f32_16x16x32_bf16 v[52:55], v[180:183], v[200:203], v[52:55]
	v_mfma_f32_16x16x32_bf16 v[48:51], v[188:191], v[200:203], v[48:51]
	v_mfma_f32_16x16x32_bf16 v[36:39], v[180:183], v[208:211], v[36:39]
	v_mfma_f32_16x16x32_bf16 v[32:35], v[188:191], v[208:211], v[32:35]
	v_mfma_f32_16x16x32_bf16 v[20:23], v[180:183], v[216:219], v[20:23]
	v_mfma_f32_16x16x32_bf16 v[16:19], v[188:191], v[216:219], v[16:19]
	v_mfma_f32_16x16x32_bf16 v[4:7], v[180:183], v[224:227], v[4:7]
	v_mfma_f32_16x16x32_bf16 v[0:3], v[188:191], v[224:227], v[0:3]
	s_setprio 0
	s_barrier
	ds_read_b128 v[106:109], v103
	ds_read_b128 v[154:157], v103 offset:1024
	ds_read_b128 v[168:171], v103 offset:2048
	ds_read_b128 v[172:175], v103 offset:3072
	ds_read_b128 v[176:179], v104
	ds_read_b128 v[180:183], v104 offset:1024
	ds_read_b128 v[184:187], v104 offset:2048
	ds_read_b128 v[188:191], v104 offset:3072
	s_add_u32 s22, s22, 0xb4000
	s_addc_u32 s23, s23, 0
	s_mov_b32 m0, s41
	v_lshl_add_u64 v[114:115], s[22:23], 0, v[144:145]
	ds_read_b128 v[196:199], v102 offset:32768
	ds_read_b128 v[200:203], v102 offset:33792
	ds_read_b128 v[204:207], v102 offset:34816
	ds_read_b128 v[208:211], v102 offset:35840
	ds_read_b128 v[212:215], v102 offset:36864
	ds_read_b128 v[216:219], v102 offset:37888
	ds_read_b128 v[220:223], v102 offset:38912
	ds_read_b128 v[224:227], v102 offset:39936
	global_load_lds_dwordx4 v[114:115], off
	v_lshl_add_u64 v[114:115], s[22:23], 0, v[148:149]
	s_mov_b32 m0, s42
	s_nop 0
	global_load_lds_dwordx4 v[114:115], off
	s_waitcnt vmcnt(8)
	s_waitcnt lgkmcnt(0)
	s_barrier
; #define PG8_STAGE(bufoff, gbase, voff) do { _Pragma("unroll") for (int _i = 0; _i < 2; ++_i) \
;         __builtin_amdgcn_global_load_lds((const unsigned*)((const char*)(gbase) + (voff)[_i]), (PG8_LAS unsigned*)(lds + (bufoff) + ldsw + _i * 8192), 16, 0, 0); } while (0)
; #define PG8_LDA(dst, b, h) do { _Pragma("unroll") for (int m = 0; m < 4; ++m) _Pragma("unroll") for (int k = 0; k < 2; ++k) dst[m][k] = *(const PG8_LAS bf16x8*)(lds + PG8_SA(b, h) + aoff + m * 2048 + k * 1024); } while (0)
; #define PG8_MMA(ai, bj, At, Bt) do { __builtin_amdgcn_s_setprio(1); _Pragma("unroll") for (int m = 0; m < 4; ++m) _Pragma("unroll") for (int n = 0; n < 2; ++n) _Pragma("unroll") for (int k = 0; k < 2; ++k) \
;         acc[ai][bj][m][n] = __builtin_amdgcn_mfma_f32_16x16x32_bf16(Bt[n][k], At[m][k], acc[ai][bj][m][n], 0, 0, 0); __builtin_amdgcn_s_setprio(0); } while (0)
; #define PG8_WAIT_V(n) asm volatile("s_waitcnt vmcnt(" #n ")" ::: "memory")
; #define PG8_WAIT_L(n) asm volatile("s_waitcnt lgkmcnt(" #n ")" ::: "memory")
; #define PG8_BAR __builtin_amdgcn_s_barrier()
; #define PG8_SCHED __builtin_amdgcn_sched_barrier(0)
; template <class Epi, class Sched, bool ALIGN_EPI = false, bool SP2 = false>
; __device__ __forceinline__ void gemm_phase(PG8_LAS unsigned char* lds, const Gemm g, const Sched& S, const Epi& E) {
;     ...
;         for (int t = 0; t < nt; t += 2) {
;     ...
;             PG8_WAIT_V(8); PG8_WAIT_L(0); PG8_BAR; PG8_MMA(0, 0, At, B0); PG8_MMA(0, 1, At, B1); PG8_BAR; PG8_SCHED;
;             PG8_LDA(At, 1, 1); PG8_STAGE(PG8_SB(1, 0), b3, voffB); PG8_STAGE(PG8_SB(1, 1), b3 + hstepB, voffB); PG8_STAGE(PG8_SA(1, 0), a3, voffA);
;             PG8_WAIT_V(8); PG8_WAIT_L(0); PG8_BAR; PG8_MMA(1, 0, At, B0); PG8_MMA(1, 1, At, B1); PG8_BAR; PG8_SCHED;
	s_setprio 1
	s_waitcnt lgkmcnt(0)
	v_mfma_f32_16x16x32_bf16 v[140:143], v[106:109], v[196:199], v[140:143]
	v_mfma_f32_16x16x32_bf16 v[136:139], v[168:171], v[196:199], v[136:139]
	v_mfma_f32_16x16x32_bf16 v[124:127], v[106:109], v[204:207], v[124:127]
	v_mfma_f32_16x16x32_bf16 v[120:123], v[168:171], v[204:207], v[120:123]
	v_mfma_f32_16x16x32_bf16 v[92:95], v[106:109], v[212:215], v[92:95]
	v_mfma_f32_16x16x32_bf16 v[88:91], v[168:171], v[212:215], v[88:91]
	v_mfma_f32_16x16x32_bf16 v[76:79], v[106:109], v[220:223], v[76:79]
	v_mfma_f32_16x16x32_bf16 v[72:75], v[168:171], v[220:223], v[72:75]
	v_mfma_f32_16x16x32_bf16 v[140:143], v[154:157], v[200:203], v[140:143]
	v_mfma_f32_16x16x32_bf16 v[136:139], v[172:175], v[200:203], v[136:139]
	v_mfma_f32_16x16x32_bf16 v[124:127], v[154:157], v[208:211], v[124:127]
	v_mfma_f32_16x16x32_bf16 v[120:123], v[172:175], v[208:211], v[120:123]
	v_mfma_f32_16x16x32_bf16 v[92:95], v[154:157], v[216:219], v[92:95]
	v_mfma_f32_16x16x32_bf16 v[88:91], v[172:175], v[216:219], v[88:91]
	v_mfma_f32_16x16x32_bf16 v[76:79], v[154:157], v[224:227], v[76:79]
	v_mfma_f32_16x16x32_bf16 v[72:75], v[172:175], v[224:227], v[72:75]
	s_setprio 0
	s_setprio 1
	v_mfma_f32_16x16x32_bf16 v[132:135], v[176:179], v[196:199], v[132:135]
	v_mfma_f32_16x16x32_bf16 v[128:131], v[184:187], v[196:199], v[128:131]
	v_mfma_f32_16x16x32_bf16 v[114:117], v[176:179], v[204:207], v[116:119]
	v_mfma_f32_16x16x32_bf16 v[110:113], v[184:187], v[204:207], v[110:113]
	v_mfma_f32_16x16x32_bf16 v[84:87], v[176:179], v[212:215], v[84:87]
	v_mfma_f32_16x16x32_bf16 v[80:83], v[184:187], v[212:215], v[80:83]
	v_mfma_f32_16x16x32_bf16 v[68:71], v[176:179], v[220:223], v[68:71]
	v_mfma_f32_16x16x32_bf16 v[64:67], v[184:187], v[220:223], v[64:67]
	v_mfma_f32_16x16x32_bf16 v[132:135], v[180:183], v[200:203], v[132:135]
	v_mfma_f32_16x16x32_bf16 v[128:131], v[188:191], v[200:203], v[128:131]
	v_mfma_f32_16x16x32_bf16 v[116:119], v[180:183], v[208:211], v[114:117]
	v_mfma_f32_16x16x32_bf16 v[112:115], v[188:191], v[208:211], v[110:113]
	v_mfma_f32_16x16x32_bf16 v[84:87], v[180:183], v[216:219], v[84:87]
	v_mfma_f32_16x16x32_bf16 v[80:83], v[188:191], v[216:219], v[80:83]
	v_mfma_f32_16x16x32_bf16 v[68:71], v[180:183], v[224:227], v[68:71]
	v_mfma_f32_16x16x32_bf16 v[64:67], v[188:191], v[224:227], v[64:67]
	s_setprio 0
	s_barrier
	s_mov_b32 m0, s52
	v_lshl_add_u64 v[110:111], v[158:159], 0, s[6:7]
	s_add_u32 s20, s20, 0xb0080
	ds_read_b128 v[196:199], v102 offset:49152
	ds_read_b128 v[200:203], v102 offset:50176
	ds_read_b128 v[204:207], v102 offset:51200
	ds_read_b128 v[208:211], v102 offset:52224
	ds_read_b128 v[212:215], v102 offset:53248
	ds_read_b128 v[216:219], v102 offset:54272
	ds_read_b128 v[220:223], v102 offset:55296
	ds_read_b128 v[224:227], v102 offset:56320
	global_load_lds_dwordx4 v[110:111], off
	v_lshl_add_u64 v[110:111], v[228:229], 0, s[6:7]
	s_mov_b32 m0, s53
	s_addc_u32 s21, s21, 0
	global_load_lds_dwordx4 v[110:111], off
	v_lshl_add_u64 v[110:111], s[20:21], 0, v[146:147]
	s_mov_b32 m0, s54
	s_nop 0
	global_load_lds_dwordx4 v[110:111], off
	v_lshl_add_u64 v[110:111], s[20:21], 0, v[150:151]
	s_mov_b32 m0, s55
	s_nop 0
	global_load_lds_dwordx4 v[110:111], off
	v_lshl_add_u64 v[110:111], v[230:231], 0, s[6:7]
	s_mov_b32 m0, s43
	s_nop 0
	global_load_lds_dwordx4 v[110:111], off
	v_lshl_add_u64 v[110:111], v[232:233], 0, s[6:7]
	s_mov_b32 m0, s44
	s_nop 0
	global_load_lds_dwordx4 v[110:111], off
	s_waitcnt vmcnt(8)
	s_waitcnt lgkmcnt(0)
	s_barrier
	s_setprio 1
	s_waitcnt lgkmcnt(0)
	v_mfma_f32_16x16x32_bf16 v[60:63], v[106:109], v[196:199], v[60:63]
	v_mfma_f32_16x16x32_bf16 v[56:59], v[168:171], v[196:199], v[56:59]
	v_mfma_f32_16x16x32_bf16 v[44:47], v[106:109], v[204:207], v[44:47]
	v_mfma_f32_16x16x32_bf16 v[40:43], v[168:171], v[204:207], v[40:43]
	v_mfma_f32_16x16x32_bf16 v[28:31], v[106:109], v[212:215], v[28:31]
	v_mfma_f32_16x16x32_bf16 v[24:27], v[168:171], v[212:215], v[24:27]
	v_mfma_f32_16x16x32_bf16 v[12:15], v[106:109], v[220:223], v[12:15]
	v_mfma_f32_16x16x32_bf16 v[8:11], v[168:171], v[220:223], v[8:11]
	v_mfma_f32_16x16x32_bf16 v[60:63], v[154:157], v[200:203], v[60:63]
	v_mfma_f32_16x16x32_bf16 v[56:59], v[172:175], v[200:203], v[56:59]
	v_mfma_f32_16x16x32_bf16 v[44:47], v[154:157], v[208:211], v[44:47]
	v_mfma_f32_16x16x32_bf16 v[40:43], v[172:175], v[208:211], v[40:43]
	v_mfma_f32_16x16x32_bf16 v[28:31], v[154:157], v[216:219], v[28:31]
	v_mfma_f32_16x16x32_bf16 v[24:27], v[172:175], v[216:219], v[24:27]
	v_mfma_f32_16x16x32_bf16 v[12:15], v[154:157], v[224:227], v[12:15]
	v_mfma_f32_16x16x32_bf16 v[8:11], v[172:175], v[224:227], v[8:11]
	s_setprio 0
	s_setprio 1
	v_mfma_f32_16x16x32_bf16 v[52:55], v[176:179], v[196:199], v[52:55]
	v_mfma_f32_16x16x32_bf16 v[48:51], v[184:187], v[196:199], v[48:51]
	v_mfma_f32_16x16x32_bf16 v[36:39], v[176:179], v[204:207], v[36:39]
	v_mfma_f32_16x16x32_bf16 v[32:35], v[184:187], v[204:207], v[32:35]
	v_mfma_f32_16x16x32_bf16 v[20:23], v[176:179], v[212:215], v[20:23]
	v_mfma_f32_16x16x32_bf16 v[16:19], v[184:187], v[212:215], v[16:19]
	v_mfma_f32_16x16x32_bf16 v[4:7], v[176:179], v[220:223], v[4:7]
	v_mfma_f32_16x16x32_bf16 v[0:3], v[184:187], v[220:223], v[0:3]
	v_mfma_f32_16x16x32_bf16 v[52:55], v[180:183], v[200:203], v[52:55]
	v_mfma_f32_16x16x32_bf16 v[48:51], v[188:191], v[200:203], v[48:51]
	v_mfma_f32_16x16x32_bf16 v[36:39], v[180:183], v[208:211], v[36:39]
	v_mfma_f32_16x16x32_bf16 v[32:35], v[188:191], v[208:211], v[32:35]
	v_mfma_f32_16x16x32_bf16 v[20:23], v[180:183], v[216:219], v[20:23]
	v_mfma_f32_16x16x32_bf16 v[16:19], v[188:191], v[216:219], v[16:19]
	v_mfma_f32_16x16x32_bf16 v[4:7], v[180:183], v[224:227], v[4:7]
	v_mfma_f32_16x16x32_bf16 v[0:3], v[188:191], v[224:227], v[0:3]
	s_setprio 0
	s_barrier
	s_add_i32 s45, s45, 2
	s_add_u32 s18, s18, 0x100
	s_addc_u32 s19, s19, 0

; #define PG8_STAGE(bufoff, gbase, voff) do { _Pragma("unroll") for (int _i = 0; _i < 2; ++_i) \
;         __builtin_amdgcn_global_load_lds((const unsigned*)((const char*)(gbase) + (voff)[_i]), (PG8_LAS unsigned*)(lds + (bufoff) + ldsw + _i * 8192), 16, 0, 0); } while (0)
; #define PG8_LDA(dst, b, h) do { _Pragma("unroll") for (int m = 0; m < 4; ++m) _Pragma("unroll") for (int k = 0; k < 2; ++k) dst[m][k] = *(const PG8_LAS bf16x8*)(lds + PG8_SA(b, h) + aoff + m * 2048 + k * 1024); } while (0)
; #define PG8_WAIT_V(n) asm volatile("s_waitcnt vmcnt(" #n ")" ::: "memory")
; #define PG8_WAIT_L(n) asm volatile("s_waitcnt lgkmcnt(" #n ")" ::: "memory")
; template <class Epi, class Sched, bool ALIGN_EPI = false, bool SP2 = false>
; __device__ __forceinline__ void gemm_phase(PG8_LAS unsigned char* lds, const Gemm g, const Sched& S, const Epi& E) {
;     ...
;         PG8_WAIT_V(2); PG8_BAR;
;         PG8_STAGE(PG8_SB(1, 0), cB + kstep, voffB); PG8_STAGE(PG8_SA(1, 0), cA + kstep, voffA); PG8_STAGE(PG8_SB(1, 1), cB + hstepB + kstep, voffB);
;         PG8_WAIT_V(6); PG8_BAR;
;     } else {
;         PG8_STAGE(PG8_SB(0, 0), cB, voffB); PG8_STAGE(PG8_SA(0, 0), cA, voffA); PG8_STAGE(PG8_SB(0, 1), cB + hstepB, voffB); PG8_STAGE(PG8_SA(0, 1), cA + hstepA, voffA);
;         if (wr == 1) PG8_BAR;
;         PG8_WAIT_V(4); PG8_BAR;
;         PG8_STAGE(PG8_SB(1, 0), cB + kstep, voffB); PG8_STAGE(PG8_SA(1, 0), cA + kstep, voffA); PG8_STAGE(PG8_SB(1, 1), cB + hstepB + kstep, voffB);
;         PG8_WAIT_V(6); PG8_BAR;
;     }
;     for (;;) {
;         const bool has_next = S.next(ui + 1, nxt);
;         const char* nA = has_next ? PG8_UA(nxt) : cA; const char* nB = has_next ? PG8_UB(nxt) : cB;
;         for (int t = 0; t < nt; t += 2) {
;             const bool last = (t == nt - 2);
;             const char* a1 = cA + (size_t)(t + 1) * kstep;
;             const char* a2 = last ? nA : cA + (size_t)(t + 2) * kstep; const char* b2 = last ? nB : cB + (size_t)(t + 2) * kstep;
;             const char* a3 = a2 + kstep; const char* b3 = b2 + kstep;
;             if (last && has_next) S.a_ready(nxt);
;             if constexpr (SP2) {
;             PG8_LDB(B0, 0, 0); PG8_LDB(B1, 0, 1); PG8_SCHED; PG8_LDA(At, 0, 0); PG8_STAGE(PG8_SA(1, 1), a1 + hstepA, voffA);
;             PG8_WAIT_V(8); PG8_WAIT_L(0); PG8_BAR; PG8_MMA(0, 0, At, B0); PG8_MMA(0, 1, At, B1); PG8_BAR; PG8_SCHED;
.LBB0_1175:
	v_lshlrev_b32_e32 v9, 2, v161
	s_and_b32 s28, s6, 3
	v_lshl_or_b32 v8, v161, 6, v166
	s_lshl_b32 s6, s3, 13
	v_and_b32_e32 v9, 32, v9
	v_bitop3_b32 v8, v8, s6, v9 bitop3:0xde
	s_mov_b64 s[6:7], 0x80
	s_add_i32 m0, s30, 0x18000
	v_lshl_add_u64 v[6:7], v[6:7], 0, s[6:7]
	s_waitcnt vmcnt(2)
	s_barrier
	global_load_lds_dwordx4 v[6:7], off
	v_lshl_add_u64 v[4:5], v[4:5], 0, s[6:7]
	s_add_i32 m0, s30, 0x1a000
	s_add_i32 s37, s30, 0x8000
	s_add_i32 s40, s30, 0xa000
	global_load_lds_dwordx4 v[4:5], off
	v_lshl_add_u64 v[2:3], v[2:3], 0, s[6:7]
	s_mov_b32 m0, s37
	s_add_u32 s22, s0, 0xb0080
	global_load_lds_dwordx4 v[2:3], off
	v_lshl_add_u64 v[0:1], v[0:1], 0, s[6:7]
	s_mov_b32 m0, s40
	s_addc_u32 s23, s1, 0
	global_load_lds_dwordx4 v[0:1], off
	s_add_i32 m0, s30, 0x1c000
	v_lshl_add_u64 v[0:1], s[22:23], 0, v[146:147]
	global_load_lds_dwordx4 v[0:1], off
	v_lshl_add_u64 v[0:1], s[22:23], 0, v[150:151]
	s_add_i32 m0, s30, 0x1e000
	s_add_u32 s22, s34, s19
	global_load_lds_dwordx4 v[0:1], off
	v_add_u16_e32 v0, v162, v163
	v_lshrrev_b16_e32 v2, 1, v0
	v_lshl_or_b32 v9, s28, 12, v167
	s_waitcnt vmcnt(6)
	v_add_lshl_u32 v0, v164, v2, 1
	v_mov_b32_e32 v1, v147
	s_addc_u32 s23, s35, s18
	s_add_i32 s44, 0, 0x10000
	s_add_i32 s46, 0, 0x14000
	s_add_i32 s48, 0, 0x18000
	s_add_i32 s50, 0, 0x1c000
	v_lshl_add_u64 v[96:97], s[22:23], 0, v[0:1]
	v_add_lshl_u32 v0, v165, v2, 1
	v_add_u32_e32 v100, s44, v9
	v_add_u32_e32 v101, s46, v9
	s_add_i32 s44, s44, s20
	s_add_i32 s46, s46, s20
	v_add_u32_e32 v103, s48, v9
	v_add_u32_e32 v104, s50, v9
	s_add_i32 s48, s48, s20
	s_add_i32 s50, s50, s20
	v_lshl_or_b32 v152, s3, 6, v161
	v_lshl_add_u64 v[98:99], s[22:23], 0, v[0:1]
	s_mov_b32 s41, -2
	s_mov_b64 s[18:19], 0x78b4080
	v_add_u32_e32 v102, 0, v8
	s_add_i32 s42, s30, 0xc000
	s_add_i32 s43, s30, 0xe000
	s_add_i32 s45, s44, 0x2000
	s_add_i32 s47, s46, 0x2000
	s_add_i32 s49, s48, 0x2000
	s_add_i32 s51, s50, 0x2000
	s_barrier
	ds_read_b128 v[106:109], v100
	ds_read_b128 v[154:157], v100 offset:1024
	ds_read_b128 v[162:165], v100 offset:2048
	ds_read_b128 v[166:169], v100 offset:3072
	ds_read_b128 v[170:173], v101
	ds_read_b128 v[174:177], v101 offset:1024
	ds_read_b128 v[178:181], v101 offset:2048
	ds_read_b128 v[182:185], v101 offset:3072
	s_add_u32 s20, s18, 0xf874c080
	s_addc_u32 s21, s19, -1
	s_cmp_lg_u32 s41, 40
	s_cselect_b32 s20, s20, 0
	s_cselect_b32 s21, s21, 0
	s_add_u32 s22, s4, s20
	s_addc_u32 s23, s5, s21
	s_add_u32 s20, s0, s20
	s_addc_u32 s21, s1, s21
	s_mov_b32 m0, s42
	v_lshl_add_u64 v[110:111], v[96:97], 0, s[18:19]
	ds_read_b128 v[186:189], v102
	ds_read_b128 v[196:199], v102 offset:1024
	ds_read_b128 v[200:203], v102 offset:2048
	ds_read_b128 v[204:207], v102 offset:3072
	ds_read_b128 v[208:211], v102 offset:4096
	ds_read_b128 v[212:215], v102 offset:5120
	ds_read_b128 v[216:219], v102 offset:6144
	ds_read_b128 v[220:223], v102 offset:7168
	global_load_lds_dwordx4 v[110:111], off
	v_lshl_add_u64 v[110:111], v[98:99], 0, s[18:19]
	s_mov_b32 m0, s43
	s_nop 0
	global_load_lds_dwordx4 v[110:111], off
	s_waitcnt vmcnt(8)
	s_waitcnt lgkmcnt(0)
	s_barrier
	s_setprio 1
	s_waitcnt lgkmcnt(0)
	v_mfma_f32_16x16x32_bf16 v[140:143], v[106:109], v[186:189], 0
	v_mfma_f32_16x16x32_bf16 v[136:139], v[162:165], v[186:189], 0
	v_mfma_f32_16x16x32_bf16 v[124:127], v[106:109], v[200:203], 0
	v_mfma_f32_16x16x32_bf16 v[120:123], v[162:165], v[200:203], 0
	v_mfma_f32_16x16x32_bf16 v[92:95], v[106:109], v[208:211], 0
	v_mfma_f32_16x16x32_bf16 v[88:91], v[162:165], v[208:211], 0
	v_mfma_f32_16x16x32_bf16 v[76:79], v[106:109], v[216:219], 0
	v_mfma_f32_16x16x32_bf16 v[72:75], v[162:165], v[216:219], 0
	v_mfma_f32_16x16x32_bf16 v[140:143], v[154:157], v[196:199], v[140:143]
	v_mfma_f32_16x16x32_bf16 v[136:139], v[166:169], v[196:199], v[136:139]
	v_mfma_f32_16x16x32_bf16 v[124:127], v[154:157], v[204:207], v[124:127]
	v_mfma_f32_16x16x32_bf16 v[120:123], v[166:169], v[204:207], v[120:123]
	v_mfma_f32_16x16x32_bf16 v[92:95], v[154:157], v[212:215], v[92:95]
	v_mfma_f32_16x16x32_bf16 v[88:91], v[166:169], v[212:215], v[88:91]
	v_mfma_f32_16x16x32_bf16 v[76:79], v[154:157], v[220:223], v[76:79]
	v_mfma_f32_16x16x32_bf16 v[72:75], v[166:169], v[220:223], v[72:75]
	s_setprio 0
	s_setprio 1
	v_mfma_f32_16x16x32_bf16 v[132:135], v[170:173], v[186:189], 0
	v_mfma_f32_16x16x32_bf16 v[128:131], v[178:181], v[186:189], 0
	v_mfma_f32_16x16x32_bf16 v[116:119], v[170:173], v[200:203], 0
	v_mfma_f32_16x16x32_bf16 v[110:113], v[178:181], v[200:203], 0
	v_mfma_f32_16x16x32_bf16 v[84:87], v[170:173], v[208:211], 0
	v_mfma_f32_16x16x32_bf16 v[80:83], v[178:181], v[208:211], 0
	v_mfma_f32_16x16x32_bf16 v[68:71], v[170:173], v[216:219], 0
	v_mfma_f32_16x16x32_bf16 v[64:67], v[178:181], v[216:219], 0
	v_mfma_f32_16x16x32_bf16 v[132:135], v[174:177], v[196:199], v[132:135]
	v_mfma_f32_16x16x32_bf16 v[128:131], v[182:185], v[196:199], v[128:131]
	v_mfma_f32_16x16x32_bf16 v[116:119], v[174:177], v[204:207], v[116:119]
	v_mfma_f32_16x16x32_bf16 v[110:113], v[182:185], v[204:207], v[110:113]
	v_mfma_f32_16x16x32_bf16 v[84:87], v[174:177], v[212:215], v[84:87]
	v_mfma_f32_16x16x32_bf16 v[80:83], v[182:185], v[212:215], v[80:83]
	v_mfma_f32_16x16x32_bf16 v[68:71], v[174:177], v[220:223], v[68:71]
	v_mfma_f32_16x16x32_bf16 v[64:67], v[182:185], v[220:223], v[64:67]
	s_setprio 0
	s_barrier
; #define PG8_STAGE(bufoff, gbase, voff) do { _Pragma("unroll") for (int _i = 0; _i < 2; ++_i) \
;         __builtin_amdgcn_global_load_lds((const unsigned*)((const char*)(gbase) + (voff)[_i]), (PG8_LAS unsigned*)(lds + (bufoff) + ldsw + _i * 8192), 16, 0, 0); } while (0)
; #define PG8_LDA(dst, b, h) do { _Pragma("unroll") for (int m = 0; m < 4; ++m) _Pragma("unroll") for (int k = 0; k < 2; ++k) dst[m][k] = *(const PG8_LAS bf16x8*)(lds + PG8_SA(b, h) + aoff + m * 2048 + k * 1024); } while (0)
; #define PG8_LDB(dst, b, h) do { _Pragma("unroll") for (int n = 0; n < 2; ++n) _Pragma("unroll") for (int k = 0; k < 2; ++k) dst[n][k] = *(const PG8_LAS bf16x8*)(lds + PG8_SB(b, h) + boff + n * 2048 + k * 1024); } while (0)
; #define PG8_MMA(ai, bj, At, Bt) do { __builtin_amdgcn_s_setprio(1); _Pragma("unroll") for (int m = 0; m < 4; ++m) _Pragma("unroll") for (int n = 0; n < 2; ++n) _Pragma("unroll") for (int k = 0; k < 2; ++k) \
;         acc[ai][bj][m][n] = __builtin_amdgcn_mfma_f32_16x16x32_bf16(Bt[n][k], At[m][k], acc[ai][bj][m][n], 0, 0, 0); __builtin_amdgcn_s_setprio(0); } while (0)
; #define PG8_WAIT_V(n) asm volatile("s_waitcnt vmcnt(" #n ")" ::: "memory")
; #define PG8_WAIT_L(n) asm volatile("s_waitcnt lgkmcnt(" #n ")" ::: "memory")
; #define PG8_BAR __builtin_amdgcn_s_barrier()
; #define PG8_SCHED __builtin_amdgcn_sched_barrier(0)
; template <class Epi, class Sched, bool ALIGN_EPI = false, bool SP2 = false>
; __device__ __forceinline__ void gemm_phase(PG8_LAS unsigned char* lds, const Gemm g, const Sched& S, const Epi& E) {
;     ...
;             PG8_LDA(At, 0, 1); PG8_STAGE(PG8_SB(0, 0), b2, voffB); PG8_STAGE(PG8_SB(0, 1), b2 + hstepB, voffB); PG8_STAGE(PG8_SA(0, 0), a2, voffA);
;             PG8_WAIT_V(8); PG8_WAIT_L(0); PG8_BAR; PG8_MMA(1, 0, At, B0); PG8_MMA(1, 1, At, B1); PG8_BAR; PG8_SCHED;
;             PG8_LDB(B0, 1, 0); PG8_LDB(B1, 1, 1); PG8_SCHED; PG8_LDA(At, 1, 0); PG8_STAGE(PG8_SA(0, 1), a2 + hstepA, voffA);
;             PG8_WAIT_V(8); PG8_WAIT_L(0); PG8_BAR; PG8_MMA(0, 0, At, B0); PG8_MMA(0, 1, At, B1); PG8_BAR; PG8_SCHED;
	s_mov_b32 m0, s44
	v_lshl_add_u64 v[158:159], s[20:21], 0, v[146:147]
	s_add_u32 s52, s20, 0xb0000
	ds_read_b128 v[186:189], v102 offset:16384
	ds_read_b128 v[196:199], v102 offset:17408
	ds_read_b128 v[200:203], v102 offset:18432
	ds_read_b128 v[204:207], v102 offset:19456
	ds_read_b128 v[208:211], v102 offset:20480
	ds_read_b128 v[212:215], v102 offset:21504
	ds_read_b128 v[216:219], v102 offset:22528
	ds_read_b128 v[220:223], v102 offset:23552
	global_load_lds_dwordx4 v[158:159], off
	v_lshl_add_u64 v[190:191], s[20:21], 0, v[150:151]
	s_mov_b32 m0, s45
	s_addc_u32 s53, s21, 0
	global_load_lds_dwordx4 v[190:191], off
	v_lshl_add_u64 v[114:115], s[52:53], 0, v[146:147]
	s_mov_b32 m0, s46
	v_lshl_add_u64 v[224:225], s[22:23], 0, v[144:145]
	global_load_lds_dwordx4 v[114:115], off
	v_lshl_add_u64 v[114:115], s[52:53], 0, v[150:151]
	s_mov_b32 m0, s47
	v_lshl_add_u64 v[226:227], s[22:23], 0, v[148:149]
	global_load_lds_dwordx4 v[114:115], off
	s_mov_b32 m0, s30
	s_nop 0
	global_load_lds_dwordx4 v[224:225], off
	s_mov_b32 m0, s29
	s_nop 0
	global_load_lds_dwordx4 v[226:227], off
	s_waitcnt vmcnt(8)
	s_waitcnt lgkmcnt(0)
	s_barrier
	s_setprio 1
	s_waitcnt lgkmcnt(0)
	v_mfma_f32_16x16x32_bf16 v[60:63], v[106:109], v[186:189], 0
	v_mfma_f32_16x16x32_bf16 v[56:59], v[162:165], v[186:189], 0
	v_mfma_f32_16x16x32_bf16 v[44:47], v[106:109], v[200:203], 0
	v_mfma_f32_16x16x32_bf16 v[40:43], v[162:165], v[200:203], 0
	v_mfma_f32_16x16x32_bf16 v[28:31], v[106:109], v[208:211], 0
	v_mfma_f32_16x16x32_bf16 v[24:27], v[162:165], v[208:211], 0
	v_mfma_f32_16x16x32_bf16 v[12:15], v[106:109], v[216:219], 0
	v_mfma_f32_16x16x32_bf16 v[8:11], v[162:165], v[216:219], 0
	v_mfma_f32_16x16x32_bf16 v[60:63], v[154:157], v[196:199], v[60:63]
	v_mfma_f32_16x16x32_bf16 v[56:59], v[166:169], v[196:199], v[56:59]
	v_mfma_f32_16x16x32_bf16 v[44:47], v[154:157], v[204:207], v[44:47]
	v_mfma_f32_16x16x32_bf16 v[40:43], v[166:169], v[204:207], v[40:43]
	v_mfma_f32_16x16x32_bf16 v[28:31], v[154:157], v[212:215], v[28:31]
	v_mfma_f32_16x16x32_bf16 v[24:27], v[166:169], v[212:215], v[24:27]
	v_mfma_f32_16x16x32_bf16 v[12:15], v[154:157], v[220:223], v[12:15]
	v_mfma_f32_16x16x32_bf16 v[8:11], v[166:169], v[220:223], v[8:11]
	s_setprio 0
	s_setprio 1
	v_mfma_f32_16x16x32_bf16 v[52:55], v[170:173], v[186:189], 0
	v_mfma_f32_16x16x32_bf16 v[48:51], v[178:181], v[186:189], 0
	v_mfma_f32_16x16x32_bf16 v[36:39], v[170:173], v[200:203], 0
	v_mfma_f32_16x16x32_bf16 v[32:35], v[178:181], v[200:203], 0
	v_mfma_f32_16x16x32_bf16 v[20:23], v[170:173], v[208:211], 0
	v_mfma_f32_16x16x32_bf16 v[16:19], v[178:181], v[208:211], 0
	v_mfma_f32_16x16x32_bf16 v[4:7], v[170:173], v[216:219], 0
	v_mfma_f32_16x16x32_bf16 v[0:3], v[178:181], v[216:219], 0
	v_mfma_f32_16x16x32_bf16 v[52:55], v[174:177], v[196:199], v[52:55]
	v_mfma_f32_16x16x32_bf16 v[48:51], v[182:185], v[196:199], v[48:51]
	v_mfma_f32_16x16x32_bf16 v[36:39], v[174:177], v[204:207], v[36:39]
	v_mfma_f32_16x16x32_bf16 v[32:35], v[182:185], v[204:207], v[32:35]
	v_mfma_f32_16x16x32_bf16 v[20:23], v[174:177], v[212:215], v[20:23]
	v_mfma_f32_16x16x32_bf16 v[16:19], v[182:185], v[212:215], v[16:19]
	v_mfma_f32_16x16x32_bf16 v[4:7], v[174:177], v[220:223], v[4:7]
	v_mfma_f32_16x16x32_bf16 v[0:3], v[182:185], v[220:223], v[0:3]
	s_setprio 0
	s_barrier
	ds_read_b128 v[106:109], v103
	ds_read_b128 v[154:157], v103 offset:1024
	ds_read_b128 v[162:165], v103 offset:2048
	ds_read_b128 v[166:169], v103 offset:3072
	ds_read_b128 v[170:173], v104
	ds_read_b128 v[174:177], v104 offset:1024
	ds_read_b128 v[178:181], v104 offset:2048
	ds_read_b128 v[182:185], v104 offset:3072
	s_add_u32 s22, s22, 0xb4000
	s_addc_u32 s23, s23, 0
	s_mov_b32 m0, s31
	v_lshl_add_u64 v[114:115], s[22:23], 0, v[144:145]
	ds_read_b128 v[186:189], v102 offset:32768
	ds_read_b128 v[196:199], v102 offset:33792
	ds_read_b128 v[200:203], v102 offset:34816
	ds_read_b128 v[204:207], v102 offset:35840
	ds_read_b128 v[208:211], v102 offset:36864
	ds_read_b128 v[212:215], v102 offset:37888
	ds_read_b128 v[216:219], v102 offset:38912
	ds_read_b128 v[220:223], v102 offset:39936
	global_load_lds_dwordx4 v[114:115], off
	v_lshl_add_u64 v[114:115], s[22:23], 0, v[148:149]
	s_mov_b32 m0, s36
	s_nop 0
	global_load_lds_dwordx4 v[114:115], off
	s_waitcnt vmcnt(8)
	s_waitcnt lgkmcnt(0)
	s_barrier
; #define PG8_STAGE(bufoff, gbase, voff) do { _Pragma("unroll") for (int _i = 0; _i < 2; ++_i) \
;         __builtin_amdgcn_global_load_lds((const unsigned*)((const char*)(gbase) + (voff)[_i]), (PG8_LAS unsigned*)(lds + (bufoff) + ldsw + _i * 8192), 16, 0, 0); } while (0)
; #define PG8_LDA(dst, b, h) do { _Pragma("unroll") for (int m = 0; m < 4; ++m) _Pragma("unroll") for (int k = 0; k < 2; ++k) dst[m][k] = *(const PG8_LAS bf16x8*)(lds + PG8_SA(b, h) + aoff + m * 2048 + k * 1024); } while (0)
; #define PG8_MMA(ai, bj, At, Bt) do { __builtin_amdgcn_s_setprio(1); _Pragma("unroll") for (int m = 0; m < 4; ++m) _Pragma("unroll") for (int n = 0; n < 2; ++n) _Pragma("unroll") for (int k = 0; k < 2; ++k) \
;         acc[ai][bj][m][n] = __builtin_amdgcn_mfma_f32_16x16x32_bf16(Bt[n][k], At[m][k], acc[ai][bj][m][n], 0, 0, 0); __builtin_amdgcn_s_setprio(0); } while (0)
; #define PG8_WAIT_V(n) asm volatile("s_waitcnt vmcnt(" #n ")" ::: "memory")
; #define PG8_WAIT_L(n) asm volatile("s_waitcnt lgkmcnt(" #n ")" ::: "memory")
; #define PG8_BAR __builtin_amdgcn_s_barrier()
; #define PG8_SCHED __builtin_amdgcn_sched_barrier(0)
; template <class Epi, class Sched, bool ALIGN_EPI = false, bool SP2 = false>
; __device__ __forceinline__ void gemm_phase(PG8_LAS unsigned char* lds, const Gemm g, const Sched& S, const Epi& E) {
;     ...
;         for (int t = 0; t < nt; t += 2) {
;     ...
;             PG8_WAIT_V(8); PG8_WAIT_L(0); PG8_BAR; PG8_MMA(0, 0, At, B0); PG8_MMA(0, 1, At, B1); PG8_BAR; PG8_SCHED;
;             PG8_LDA(At, 1, 1); PG8_STAGE(PG8_SB(1, 0), b3, voffB); PG8_STAGE(PG8_SB(1, 1), b3 + hstepB, voffB); PG8_STAGE(PG8_SA(1, 0), a3, voffA);
;             PG8_WAIT_V(8); PG8_WAIT_L(0); PG8_BAR; PG8_MMA(1, 0, At, B0); PG8_MMA(1, 1, At, B1); PG8_BAR; PG8_SCHED;
	s_setprio 1
	s_waitcnt lgkmcnt(0)
	v_mfma_f32_16x16x32_bf16 v[140:143], v[106:109], v[186:189], v[140:143]
	v_mfma_f32_16x16x32_bf16 v[136:139], v[162:165], v[186:189], v[136:139]
	v_mfma_f32_16x16x32_bf16 v[124:127], v[106:109], v[200:203], v[124:127]
	v_mfma_f32_16x16x32_bf16 v[120:123], v[162:165], v[200:203], v[120:123]
	v_mfma_f32_16x16x32_bf16 v[92:95], v[106:109], v[208:211], v[92:95]
	v_mfma_f32_16x16x32_bf16 v[88:91], v[162:165], v[208:211], v[88:91]
	v_mfma_f32_16x16x32_bf16 v[76:79], v[106:109], v[216:219], v[76:79]
	v_mfma_f32_16x16x32_bf16 v[72:75], v[162:165], v[216:219], v[72:75]
	v_mfma_f32_16x16x32_bf16 v[140:143], v[154:157], v[196:199], v[140:143]
	v_mfma_f32_16x16x32_bf16 v[136:139], v[166:169], v[196:199], v[136:139]
	v_mfma_f32_16x16x32_bf16 v[124:127], v[154:157], v[204:207], v[124:127]
	v_mfma_f32_16x16x32_bf16 v[120:123], v[166:169], v[204:207], v[120:123]
	v_mfma_f32_16x16x32_bf16 v[92:95], v[154:157], v[212:215], v[92:95]
	v_mfma_f32_16x16x32_bf16 v[88:91], v[166:169], v[212:215], v[88:91]
	v_mfma_f32_16x16x32_bf16 v[76:79], v[154:157], v[220:223], v[76:79]
	v_mfma_f32_16x16x32_bf16 v[72:75], v[166:169], v[220:223], v[72:75]
	s_setprio 0
	s_setprio 1
	v_mfma_f32_16x16x32_bf16 v[132:135], v[170:173], v[186:189], v[132:135]
	v_mfma_f32_16x16x32_bf16 v[128:131], v[178:181], v[186:189], v[128:131]
	v_mfma_f32_16x16x32_bf16 v[114:117], v[170:173], v[200:203], v[116:119]
	v_mfma_f32_16x16x32_bf16 v[110:113], v[178:181], v[200:203], v[110:113]
	v_mfma_f32_16x16x32_bf16 v[84:87], v[170:173], v[208:211], v[84:87]
	v_mfma_f32_16x16x32_bf16 v[80:83], v[178:181], v[208:211], v[80:83]
	v_mfma_f32_16x16x32_bf16 v[68:71], v[170:173], v[216:219], v[68:71]
	v_mfma_f32_16x16x32_bf16 v[64:67], v[178:181], v[216:219], v[64:67]
	v_mfma_f32_16x16x32_bf16 v[132:135], v[174:177], v[196:199], v[132:135]
	v_mfma_f32_16x16x32_bf16 v[128:131], v[182:185], v[196:199], v[128:131]
	v_mfma_f32_16x16x32_bf16 v[116:119], v[174:177], v[204:207], v[114:117]
	v_mfma_f32_16x16x32_bf16 v[112:115], v[182:185], v[204:207], v[110:113]
	v_mfma_f32_16x16x32_bf16 v[84:87], v[174:177], v[212:215], v[84:87]
	v_mfma_f32_16x16x32_bf16 v[80:83], v[182:185], v[212:215], v[80:83]
	v_mfma_f32_16x16x32_bf16 v[68:71], v[174:177], v[220:223], v[68:71]
	v_mfma_f32_16x16x32_bf16 v[64:67], v[182:185], v[220:223], v[64:67]
	s_setprio 0
	s_barrier
	s_mov_b32 m0, s48
	v_lshl_add_u64 v[110:111], v[158:159], 0, s[6:7]
	s_add_u32 s20, s20, 0xb0080
	ds_read_b128 v[186:189], v102 offset:49152
	ds_read_b128 v[196:199], v102 offset:50176
	ds_read_b128 v[200:203], v102 offset:51200
	ds_read_b128 v[204:207], v102 offset:52224
	ds_read_b128 v[208:211], v102 offset:53248
	ds_read_b128 v[212:215], v102 offset:54272
	ds_read_b128 v[216:219], v102 offset:55296
	ds_read_b128 v[220:223], v102 offset:56320
	global_load_lds_dwordx4 v[110:111], off
	v_lshl_add_u64 v[110:111], v[190:191], 0, s[6:7]
	s_mov_b32 m0, s49
	s_addc_u32 s21, s21, 0
	global_load_lds_dwordx4 v[110:111], off
	v_lshl_add_u64 v[110:111], s[20:21], 0, v[146:147]
	s_mov_b32 m0, s50
	s_nop 0
	global_load_lds_dwordx4 v[110:111], off
	v_lshl_add_u64 v[110:111], s[20:21], 0, v[150:151]
	s_mov_b32 m0, s51
	s_nop 0
	global_load_lds_dwordx4 v[110:111], off
	v_lshl_add_u64 v[110:111], v[224:225], 0, s[6:7]
	s_mov_b32 m0, s37
	s_nop 0
	global_load_lds_dwordx4 v[110:111], off
	v_lshl_add_u64 v[110:111], v[226:227], 0, s[6:7]
	s_mov_b32 m0, s40
	s_nop 0
	global_load_lds_dwordx4 v[110:111], off
	s_waitcnt vmcnt(8)
	s_waitcnt lgkmcnt(0)
	s_barrier
	s_setprio 1
	s_waitcnt lgkmcnt(0)
	v_mfma_f32_16x16x32_bf16 v[60:63], v[106:109], v[186:189], v[60:63]
	v_mfma_f32_16x16x32_bf16 v[56:59], v[162:165], v[186:189], v[56:59]
	v_mfma_f32_16x16x32_bf16 v[44:47], v[106:109], v[200:203], v[44:47]
	v_mfma_f32_16x16x32_bf16 v[40:43], v[162:165], v[200:203], v[40:43]
	v_mfma_f32_16x16x32_bf16 v[28:31], v[106:109], v[208:211], v[28:31]
	v_mfma_f32_16x16x32_bf16 v[24:27], v[162:165], v[208:211], v[24:27]
	v_mfma_f32_16x16x32_bf16 v[12:15], v[106:109], v[216:219], v[12:15]
	v_mfma_f32_16x16x32_bf16 v[8:11], v[162:165], v[216:219], v[8:11]
	v_mfma_f32_16x16x32_bf16 v[60:63], v[154:157], v[196:199], v[60:63]
	v_mfma_f32_16x16x32_bf16 v[56:59], v[166:169], v[196:199], v[56:59]
	v_mfma_f32_16x16x32_bf16 v[44:47], v[154:157], v[204:207], v[44:47]
	v_mfma_f32_16x16x32_bf16 v[40:43], v[166:169], v[204:207], v[40:43]
	v_mfma_f32_16x16x32_bf16 v[28:31], v[154:157], v[212:215], v[28:31]
	v_mfma_f32_16x16x32_bf16 v[24:27], v[166:169], v[212:215], v[24:27]
	v_mfma_f32_16x16x32_bf16 v[12:15], v[154:157], v[220:223], v[12:15]
	v_mfma_f32_16x16x32_bf16 v[8:11], v[166:169], v[220:223], v[8:11]
	s_setprio 0
	s_setprio 1
	v_mfma_f32_16x16x32_bf16 v[52:55], v[170:173], v[186:189], v[52:55]
	v_mfma_f32_16x16x32_bf16 v[48:51], v[178:181], v[186:189], v[48:51]
	v_mfma_f32_16x16x32_bf16 v[36:39], v[170:173], v[200:203], v[36:39]
	v_mfma_f32_16x16x32_bf16 v[32:35], v[178:181], v[200:203], v[32:35]
	v_mfma_f32_16x16x32_bf16 v[20:23], v[170:173], v[208:211], v[20:23]
	v_mfma_f32_16x16x32_bf16 v[16:19], v[178:181], v[208:211], v[16:19]
	v_mfma_f32_16x16x32_bf16 v[4:7], v[170:173], v[216:219], v[4:7]
	v_mfma_f32_16x16x32_bf16 v[0:3], v[178:181], v[216:219], v[0:3]
	v_mfma_f32_16x16x32_bf16 v[52:55], v[174:177], v[196:199], v[52:55]
	v_mfma_f32_16x16x32_bf16 v[48:51], v[182:185], v[196:199], v[48:51]
	v_mfma_f32_16x16x32_bf16 v[36:39], v[174:177], v[204:207], v[36:39]
	v_mfma_f32_16x16x32_bf16 v[32:35], v[182:185], v[204:207], v[32:35]
	v_mfma_f32_16x16x32_bf16 v[20:23], v[174:177], v[212:215], v[20:23]
	v_mfma_f32_16x16x32_bf16 v[16:19], v[182:185], v[212:215], v[16:19]
	v_mfma_f32_16x16x32_bf16 v[4:7], v[174:177], v[220:223], v[4:7]
	v_mfma_f32_16x16x32_bf16 v[0:3], v[182:185], v[220:223], v[0:3]
	s_setprio 0
	s_barrier
	s_add_i32 s41, s41, 2
	s_add_u32 s18, s18, 0x100
	s_addc_u32 s19, s19, 0

; #define PG8_STAGE(bufoff, gbase, voff) do { _Pragma("unroll") for (int _i = 0; _i < 2; ++_i) \
;         __builtin_amdgcn_global_load_lds((const unsigned*)((const char*)(gbase) + (voff)[_i]), (PG8_LAS unsigned*)(lds + (bufoff) + ldsw + _i * 8192), 16, 0, 0); } while (0)
; #define PG8_LDA(dst, b, h) do { _Pragma("unroll") for (int m = 0; m < 4; ++m) _Pragma("unroll") for (int k = 0; k < 2; ++k) dst[m][k] = *(const PG8_LAS bf16x8*)(lds + PG8_SA(b, h) + aoff + m * 2048 + k * 1024); } while (0)
; #define PG8_WAIT_V(n) asm volatile("s_waitcnt vmcnt(" #n ")" ::: "memory")
; #define PG8_WAIT_L(n) asm volatile("s_waitcnt lgkmcnt(" #n ")" ::: "memory")
; template <class Epi, class Sched, bool ALIGN_EPI = false, bool SP2 = false>
; __device__ __forceinline__ void gemm_phase(PG8_LAS unsigned char* lds, const Gemm g, const Sched& S, const Epi& E) {
;     ...
;         PG8_WAIT_V(2); PG8_BAR;
;         PG8_STAGE(PG8_SB(1, 0), cB + kstep, voffB); PG8_STAGE(PG8_SA(1, 0), cA + kstep, voffA); PG8_STAGE(PG8_SB(1, 1), cB + hstepB + kstep, voffB);
;         PG8_WAIT_V(6); PG8_BAR;
;     } else {
;         PG8_STAGE(PG8_SB(0, 0), cB, voffB); PG8_STAGE(PG8_SA(0, 0), cA, voffA); PG8_STAGE(PG8_SB(0, 1), cB + hstepB, voffB); PG8_STAGE(PG8_SA(0, 1), cA + hstepA, voffA);
;         if (wr == 1) PG8_BAR;
;         PG8_WAIT_V(4); PG8_BAR;
;         PG8_STAGE(PG8_SB(1, 0), cB + kstep, voffB); PG8_STAGE(PG8_SA(1, 0), cA + kstep, voffA); PG8_STAGE(PG8_SB(1, 1), cB + hstepB + kstep, voffB);
;         PG8_WAIT_V(6); PG8_BAR;
;     }
;     for (;;) {
;         const bool has_next = S.next(ui + 1, nxt);
;         const char* nA = has_next ? PG8_UA(nxt) : cA; const char* nB = has_next ? PG8_UB(nxt) : cB;
;         for (int t = 0; t < nt; t += 2) {
;             const bool last = (t == nt - 2);
;             const char* a1 = cA + (size_t)(t + 1) * kstep;
;             const char* a2 = last ? nA : cA + (size_t)(t + 2) * kstep; const char* b2 = last ? nB : cB + (size_t)(t + 2) * kstep;
;             const char* a3 = a2 + kstep; const char* b3 = b2 + kstep;
;             if (last && has_next) S.a_ready(nxt);
;             if constexpr (SP2) {
;             PG8_LDB(B0, 0, 0); PG8_LDB(B1, 0, 1); PG8_SCHED; PG8_LDA(At, 0, 0); PG8_STAGE(PG8_SA(1, 1), a1 + hstepA, voffA);
;             PG8_WAIT_V(8); PG8_WAIT_L(0); PG8_BAR; PG8_MMA(0, 0, At, B0); PG8_MMA(0, 1, At, B1); PG8_BAR; PG8_SCHED;
.LBB0_1602:
	v_lshlrev_b32_e32 v9, 2, v157
	s_and_b32 s33, s14, 3
	v_lshl_or_b32 v8, v157, 6, v162
	s_lshl_b32 s14, s36, 13
	v_and_b32_e32 v9, 32, v9
	v_bitop3_b32 v8, v8, s14, v9 bitop3:0xde
	s_mov_b64 s[14:15], 0x80
	s_add_i32 m0, s2, 0x18000
	v_lshl_add_u64 v[6:7], v[6:7], 0, s[14:15]
	s_waitcnt vmcnt(2)
	s_barrier
	global_load_lds_dwordx4 v[6:7], off
	v_lshl_add_u64 v[4:5], v[4:5], 0, s[14:15]
	s_add_i32 m0, s2, 0x1a000
	s_add_i32 s39, s2, 0x8000
	s_add_i32 s40, s2, 0xa000
	global_load_lds_dwordx4 v[4:5], off
	v_lshl_add_u64 v[2:3], v[2:3], 0, s[14:15]
	s_mov_b32 m0, s39
	s_add_u32 s22, s10, 0xb0080
	global_load_lds_dwordx4 v[2:3], off
	v_lshl_add_u64 v[0:1], v[0:1], 0, s[14:15]
	s_mov_b32 m0, s40
	s_addc_u32 s23, s11, 0
	global_load_lds_dwordx4 v[0:1], off
	s_add_i32 m0, s2, 0x1c000
	v_lshl_add_u64 v[0:1], s[22:23], 0, v[146:147]
	global_load_lds_dwordx4 v[0:1], off
	v_lshl_add_u64 v[0:1], s[22:23], 0, v[150:151]
	s_add_i32 m0, s2, 0x1e000
	s_add_u32 s16, s34, s16
	global_load_lds_dwordx4 v[0:1], off
	s_addc_u32 s17, s35, s17
	v_add_u16_e32 v0, v158, v159
	v_lshrrev_b16_e32 v2, 1, v0
	s_add_u32 s19, s34, s19
	v_add_lshl_u32 v0, v160, v2, 1
	v_mov_b32_e32 v1, v147
	s_addc_u32 s18, s35, s18
	v_lshl_add_u64 v[0:1], s[16:17], 0, v[0:1]
	s_mov_b64 s[22:23], 0x78b4080
	s_add_u32 s41, s19, 0x2a00100
	v_lshl_or_b32 v9, s33, 12, v163
	s_waitcnt vmcnt(6)
	v_lshl_add_u64 v[108:109], v[0:1], 0, s[22:23]
	v_add_lshl_u32 v0, v161, v2, 1
	v_mov_b32_e32 v1, v147
	s_addc_u32 s42, s18, 0
	s_add_i32 s46, 0, 0x10000
	s_add_i32 s48, 0, 0x14000
	s_add_i32 s50, 0, 0x18000
	s_add_i32 s52, 0, 0x1c000
	v_lshl_add_u64 v[0:1], s[16:17], 0, v[0:1]
	v_add_u32_e32 v116, s46, v9
	v_add_u32_e32 v117, s48, v9
	s_add_i32 s46, s46, s20
	s_add_i32 s48, s48, s20
	v_add_u32_e32 v119, s50, v9
	v_add_u32_e32 v120, s52, v9
	s_add_i32 s50, s50, s20
	s_add_i32 s52, s52, s20
	v_lshl_or_b32 v152, s36, 6, v157
	v_lshl_add_u64 v[110:111], v[0:1], 0, s[22:23]
	s_mov_b32 s43, -2
	s_mov_b64 s[18:19], 0
	v_add_u32_e32 v118, 0, v8
	s_add_i32 s44, s2, 0xc000
	s_add_i32 s45, s2, 0xe000
	s_add_i32 s47, s46, 0x2000
	s_add_i32 s49, s48, 0x2000
	s_add_i32 s51, s50, 0x2000
	s_add_i32 s53, s52, 0x2000
	s_barrier
	ds_read_b128 v[122:125], v116
	ds_read_b128 v[164:167], v116 offset:1024
	ds_read_b128 v[168:171], v116 offset:2048
	ds_read_b128 v[172:175], v116 offset:3072
	ds_read_b128 v[176:179], v117
	ds_read_b128 v[180:183], v117 offset:1024
	ds_read_b128 v[184:187], v117 offset:2048
	ds_read_b128 v[188:191], v117 offset:3072
	s_add_u32 s20, s16, s18
	s_addc_u32 s21, s17, s19
	s_add_u32 s20, s20, 0x7800100
	s_addc_u32 s21, s21, 0
	s_add_u32 s54, s41, s18
	s_addc_u32 s55, s42, s19
	s_cmpk_eq_i32 s18, 0x1500
	s_cselect_b32 s23, s13, s21
	s_cselect_b32 s22, s12, s20
	s_cselect_b32 s21, s11, s55
	s_cselect_b32 s20, s10, s54
	s_mov_b32 m0, s44
	v_lshl_add_u64 v[126:127], v[108:109], 0, s[18:19]
	ds_read_b128 v[196:199], v118
	ds_read_b128 v[200:203], v118 offset:1024
	ds_read_b128 v[204:207], v118 offset:2048
	ds_read_b128 v[208:211], v118 offset:3072
	ds_read_b128 v[212:215], v118 offset:4096
	ds_read_b128 v[216:219], v118 offset:5120
	ds_read_b128 v[220:223], v118 offset:6144
	ds_read_b128 v[224:227], v118 offset:7168
	global_load_lds_dwordx4 v[126:127], off
	v_lshl_add_u64 v[126:127], v[110:111], 0, s[18:19]
	s_mov_b32 m0, s45
	s_nop 0
	global_load_lds_dwordx4 v[126:127], off
	s_waitcnt vmcnt(8)
	s_waitcnt lgkmcnt(0)
	s_barrier
	s_setprio 1
	s_waitcnt lgkmcnt(0)
	v_mfma_f32_16x16x32_bf16 v[140:143], v[122:125], v[196:199], 0
	v_mfma_f32_16x16x32_bf16 v[136:139], v[168:171], v[196:199], 0
	v_mfma_f32_16x16x32_bf16 v[112:115], v[122:125], v[204:207], 0
	v_mfma_f32_16x16x32_bf16 v[104:107], v[168:171], v[204:207], 0
	v_mfma_f32_16x16x32_bf16 v[92:95], v[122:125], v[212:215], 0
	v_mfma_f32_16x16x32_bf16 v[88:91], v[168:171], v[212:215], 0
	v_mfma_f32_16x16x32_bf16 v[76:79], v[122:125], v[220:223], 0
	v_mfma_f32_16x16x32_bf16 v[72:75], v[168:171], v[220:223], 0
	v_mfma_f32_16x16x32_bf16 v[140:143], v[164:167], v[200:203], v[140:143]
	v_mfma_f32_16x16x32_bf16 v[136:139], v[172:175], v[200:203], v[136:139]
	v_mfma_f32_16x16x32_bf16 v[112:115], v[164:167], v[208:211], v[112:115]
	v_mfma_f32_16x16x32_bf16 v[104:107], v[172:175], v[208:211], v[104:107]
	v_mfma_f32_16x16x32_bf16 v[92:95], v[164:167], v[216:219], v[92:95]
	v_mfma_f32_16x16x32_bf16 v[88:91], v[172:175], v[216:219], v[88:91]
	v_mfma_f32_16x16x32_bf16 v[76:79], v[164:167], v[224:227], v[76:79]
	v_mfma_f32_16x16x32_bf16 v[72:75], v[172:175], v[224:227], v[72:75]
	s_setprio 0
	s_setprio 1
	v_mfma_f32_16x16x32_bf16 v[132:135], v[176:179], v[196:199], 0
	v_mfma_f32_16x16x32_bf16 v[126:129], v[184:187], v[196:199], 0
	v_mfma_f32_16x16x32_bf16 v[100:103], v[176:179], v[204:207], 0
	v_mfma_f32_16x16x32_bf16 v[96:99], v[184:187], v[204:207], 0
	v_mfma_f32_16x16x32_bf16 v[84:87], v[176:179], v[212:215], 0
	v_mfma_f32_16x16x32_bf16 v[80:83], v[184:187], v[212:215], 0
	v_mfma_f32_16x16x32_bf16 v[68:71], v[176:179], v[220:223], 0
	v_mfma_f32_16x16x32_bf16 v[64:67], v[184:187], v[220:223], 0
	v_mfma_f32_16x16x32_bf16 v[132:135], v[180:183], v[200:203], v[132:135]
	v_mfma_f32_16x16x32_bf16 v[126:129], v[188:191], v[200:203], v[126:129]
	v_mfma_f32_16x16x32_bf16 v[100:103], v[180:183], v[208:211], v[100:103]
	v_mfma_f32_16x16x32_bf16 v[96:99], v[188:191], v[208:211], v[96:99]
	v_mfma_f32_16x16x32_bf16 v[84:87], v[180:183], v[216:219], v[84:87]
	v_mfma_f32_16x16x32_bf16 v[80:83], v[188:191], v[216:219], v[80:83]
	v_mfma_f32_16x16x32_bf16 v[68:71], v[180:183], v[224:227], v[68:71]
	v_mfma_f32_16x16x32_bf16 v[64:67], v[188:191], v[224:227], v[64:67]
	s_setprio 0
	s_barrier
; #define PG8_STAGE(bufoff, gbase, voff) do { _Pragma("unroll") for (int _i = 0; _i < 2; ++_i) \
;         __builtin_amdgcn_global_load_lds((const unsigned*)((const char*)(gbase) + (voff)[_i]), (PG8_LAS unsigned*)(lds + (bufoff) + ldsw + _i * 8192), 16, 0, 0); } while (0)
; #define PG8_LDA(dst, b, h) do { _Pragma("unroll") for (int m = 0; m < 4; ++m) _Pragma("unroll") for (int k = 0; k < 2; ++k) dst[m][k] = *(const PG8_LAS bf16x8*)(lds + PG8_SA(b, h) + aoff + m * 2048 + k * 1024); } while (0)
; #define PG8_LDB(dst, b, h) do { _Pragma("unroll") for (int n = 0; n < 2; ++n) _Pragma("unroll") for (int k = 0; k < 2; ++k) dst[n][k] = *(const PG8_LAS bf16x8*)(lds + PG8_SB(b, h) + boff + n * 2048 + k * 1024); } while (0)
; #define PG8_MMA(ai, bj, At, Bt) do { __builtin_amdgcn_s_setprio(1); _Pragma("unroll") for (int m = 0; m < 4; ++m) _Pragma("unroll") for (int n = 0; n < 2; ++n) _Pragma("unroll") for (int k = 0; k < 2; ++k) \
;         acc[ai][bj][m][n] = __builtin_amdgcn_mfma_f32_16x16x32_bf16(Bt[n][k], At[m][k], acc[ai][bj][m][n], 0, 0, 0); __builtin_amdgcn_s_setprio(0); } while (0)
; #define PG8_WAIT_V(n) asm volatile("s_waitcnt vmcnt(" #n ")" ::: "memory")
; #define PG8_WAIT_L(n) asm volatile("s_waitcnt lgkmcnt(" #n ")" ::: "memory")
; #define PG8_BAR __builtin_amdgcn_s_barrier()
; #define PG8_SCHED __builtin_amdgcn_sched_barrier(0)
; template <class Epi, class Sched, bool ALIGN_EPI = false, bool SP2 = false>
; __device__ __forceinline__ void gemm_phase(PG8_LAS unsigned char* lds, const Gemm g, const Sched& S, const Epi& E) {
;     ...
;             PG8_LDA(At, 0, 1); PG8_STAGE(PG8_SB(0, 0), b2, voffB); PG8_STAGE(PG8_SB(0, 1), b2 + hstepB, voffB); PG8_STAGE(PG8_SA(0, 0), a2, voffA);
;             PG8_WAIT_V(8); PG8_WAIT_L(0); PG8_BAR; PG8_MMA(1, 0, At, B0); PG8_MMA(1, 1, At, B1); PG8_BAR; PG8_SCHED;
;             PG8_LDB(B0, 1, 0); PG8_LDB(B1, 1, 1); PG8_SCHED; PG8_LDA(At, 1, 0); PG8_STAGE(PG8_SA(0, 1), a2 + hstepA, voffA);
;             PG8_WAIT_V(8); PG8_WAIT_L(0); PG8_BAR; PG8_MMA(0, 0, At, B0); PG8_MMA(0, 1, At, B1); PG8_BAR; PG8_SCHED;
	s_mov_b32 m0, s46
	v_lshl_add_u64 v[154:155], s[20:21], 0, v[146:147]
	s_add_u32 s54, s20, 0xb0000
	ds_read_b128 v[196:199], v118 offset:16384
	ds_read_b128 v[200:203], v118 offset:17408
	ds_read_b128 v[204:207], v118 offset:18432
	ds_read_b128 v[208:211], v118 offset:19456
	ds_read_b128 v[212:215], v118 offset:20480
	ds_read_b128 v[216:219], v118 offset:21504
	ds_read_b128 v[220:223], v118 offset:22528
	ds_read_b128 v[224:227], v118 offset:23552
	global_load_lds_dwordx4 v[154:155], off
	v_lshl_add_u64 v[228:229], s[20:21], 0, v[150:151]
	s_mov_b32 m0, s47
	s_addc_u32 s55, s21, 0
	global_load_lds_dwordx4 v[228:229], off
	v_lshl_add_u64 v[130:131], s[54:55], 0, v[146:147]
	s_mov_b32 m0, s48
	v_lshl_add_u64 v[230:231], s[22:23], 0, v[144:145]
	global_load_lds_dwordx4 v[130:131], off
	v_lshl_add_u64 v[130:131], s[54:55], 0, v[150:151]
	s_mov_b32 m0, s49
	v_lshl_add_u64 v[232:233], s[22:23], 0, v[148:149]
	global_load_lds_dwordx4 v[130:131], off
	s_mov_b32 m0, s2
	s_nop 0
	global_load_lds_dwordx4 v[230:231], off
	s_mov_b32 m0, s3
	s_nop 0
	global_load_lds_dwordx4 v[232:233], off
	s_waitcnt vmcnt(8)
	s_waitcnt lgkmcnt(0)
	s_barrier
	s_setprio 1
	s_waitcnt lgkmcnt(0)
	v_mfma_f32_16x16x32_bf16 v[60:63], v[122:125], v[196:199], 0
	v_mfma_f32_16x16x32_bf16 v[56:59], v[168:171], v[196:199], 0
	v_mfma_f32_16x16x32_bf16 v[44:47], v[122:125], v[204:207], 0
	v_mfma_f32_16x16x32_bf16 v[40:43], v[168:171], v[204:207], 0
	v_mfma_f32_16x16x32_bf16 v[28:31], v[122:125], v[212:215], 0
	v_mfma_f32_16x16x32_bf16 v[24:27], v[168:171], v[212:215], 0
	v_mfma_f32_16x16x32_bf16 v[12:15], v[122:125], v[220:223], 0
	v_mfma_f32_16x16x32_bf16 v[8:11], v[168:171], v[220:223], 0
	v_mfma_f32_16x16x32_bf16 v[60:63], v[164:167], v[200:203], v[60:63]
	v_mfma_f32_16x16x32_bf16 v[56:59], v[172:175], v[200:203], v[56:59]
	v_mfma_f32_16x16x32_bf16 v[44:47], v[164:167], v[208:211], v[44:47]
	v_mfma_f32_16x16x32_bf16 v[40:43], v[172:175], v[208:211], v[40:43]
	v_mfma_f32_16x16x32_bf16 v[28:31], v[164:167], v[216:219], v[28:31]
	v_mfma_f32_16x16x32_bf16 v[24:27], v[172:175], v[216:219], v[24:27]
	v_mfma_f32_16x16x32_bf16 v[12:15], v[164:167], v[224:227], v[12:15]
	v_mfma_f32_16x16x32_bf16 v[8:11], v[172:175], v[224:227], v[8:11]
	s_setprio 0
	s_setprio 1
	v_mfma_f32_16x16x32_bf16 v[52:55], v[176:179], v[196:199], 0
	v_mfma_f32_16x16x32_bf16 v[48:51], v[184:187], v[196:199], 0
	v_mfma_f32_16x16x32_bf16 v[36:39], v[176:179], v[204:207], 0
	v_mfma_f32_16x16x32_bf16 v[32:35], v[184:187], v[204:207], 0
	v_mfma_f32_16x16x32_bf16 v[20:23], v[176:179], v[212:215], 0
	v_mfma_f32_16x16x32_bf16 v[16:19], v[184:187], v[212:215], 0
	v_mfma_f32_16x16x32_bf16 v[4:7], v[176:179], v[220:223], 0
	v_mfma_f32_16x16x32_bf16 v[0:3], v[184:187], v[220:223], 0
	v_mfma_f32_16x16x32_bf16 v[52:55], v[180:183], v[200:203], v[52:55]
	v_mfma_f32_16x16x32_bf16 v[48:51], v[188:191], v[200:203], v[48:51]
	v_mfma_f32_16x16x32_bf16 v[36:39], v[180:183], v[208:211], v[36:39]
	v_mfma_f32_16x16x32_bf16 v[32:35], v[188:191], v[208:211], v[32:35]
	v_mfma_f32_16x16x32_bf16 v[20:23], v[180:183], v[216:219], v[20:23]
	v_mfma_f32_16x16x32_bf16 v[16:19], v[188:191], v[216:219], v[16:19]
	v_mfma_f32_16x16x32_bf16 v[4:7], v[180:183], v[224:227], v[4:7]
	v_mfma_f32_16x16x32_bf16 v[0:3], v[188:191], v[224:227], v[0:3]
	s_setprio 0
	s_barrier
	ds_read_b128 v[122:125], v119
	ds_read_b128 v[164:167], v119 offset:1024
	ds_read_b128 v[168:171], v119 offset:2048
	ds_read_b128 v[172:175], v119 offset:3072
	ds_read_b128 v[176:179], v120
	ds_read_b128 v[180:183], v120 offset:1024
	ds_read_b128 v[184:187], v120 offset:2048
	ds_read_b128 v[188:191], v120 offset:3072
	s_add_u32 s22, s22, 0xb4000
	s_addc_u32 s23, s23, 0
	s_mov_b32 m0, s37
	v_lshl_add_u64 v[130:131], s[22:23], 0, v[144:145]
	ds_read_b128 v[196:199], v118 offset:32768
	ds_read_b128 v[200:203], v118 offset:33792
	ds_read_b128 v[204:207], v118 offset:34816
	ds_read_b128 v[208:211], v118 offset:35840
	ds_read_b128 v[212:215], v118 offset:36864
	ds_read_b128 v[216:219], v118 offset:37888
	ds_read_b128 v[220:223], v118 offset:38912
	ds_read_b128 v[224:227], v118 offset:39936
	global_load_lds_dwordx4 v[130:131], off
	v_lshl_add_u64 v[130:131], s[22:23], 0, v[148:149]
	s_mov_b32 m0, s38
	s_nop 0
	global_load_lds_dwordx4 v[130:131], off
	s_waitcnt vmcnt(8)
	s_waitcnt lgkmcnt(0)
	s_barrier
; #define PG8_STAGE(bufoff, gbase, voff) do { _Pragma("unroll") for (int _i = 0; _i < 2; ++_i) \
;         __builtin_amdgcn_global_load_lds((const unsigned*)((const char*)(gbase) + (voff)[_i]), (PG8_LAS unsigned*)(lds + (bufoff) + ldsw + _i * 8192), 16, 0, 0); } while (0)
; #define PG8_LDA(dst, b, h) do { _Pragma("unroll") for (int m = 0; m < 4; ++m) _Pragma("unroll") for (int k = 0; k < 2; ++k) dst[m][k] = *(const PG8_LAS bf16x8*)(lds + PG8_SA(b, h) + aoff + m * 2048 + k * 1024); } while (0)
; #define PG8_MMA(ai, bj, At, Bt) do { __builtin_amdgcn_s_setprio(1); _Pragma("unroll") for (int m = 0; m < 4; ++m) _Pragma("unroll") for (int n = 0; n < 2; ++n) _Pragma("unroll") for (int k = 0; k < 2; ++k) \
;         acc[ai][bj][m][n] = __builtin_amdgcn_mfma_f32_16x16x32_bf16(Bt[n][k], At[m][k], acc[ai][bj][m][n], 0, 0, 0); __builtin_amdgcn_s_setprio(0); } while (0)
; #define PG8_WAIT_V(n) asm volatile("s_waitcnt vmcnt(" #n ")" ::: "memory")
; #define PG8_WAIT_L(n) asm volatile("s_waitcnt lgkmcnt(" #n ")" ::: "memory")
; #define PG8_BAR __builtin_amdgcn_s_barrier()
; #define PG8_SCHED __builtin_amdgcn_sched_barrier(0)
; template <class Epi, class Sched, bool ALIGN_EPI = false, bool SP2 = false>
; __device__ __forceinline__ void gemm_phase(PG8_LAS unsigned char* lds, const Gemm g, const Sched& S, const Epi& E) {
;     ...
;         for (int t = 0; t < nt; t += 2) {
;     ...
;             PG8_WAIT_V(8); PG8_WAIT_L(0); PG8_BAR; PG8_MMA(0, 0, At, B0); PG8_MMA(0, 1, At, B1); PG8_BAR; PG8_SCHED;
;             PG8_LDA(At, 1, 1); PG8_STAGE(PG8_SB(1, 0), b3, voffB); PG8_STAGE(PG8_SB(1, 1), b3 + hstepB, voffB); PG8_STAGE(PG8_SA(1, 0), a3, voffA);
;             PG8_WAIT_V(8); PG8_WAIT_L(0); PG8_BAR; PG8_MMA(1, 0, At, B0); PG8_MMA(1, 1, At, B1); PG8_BAR; PG8_SCHED;
	s_setprio 1
	s_waitcnt lgkmcnt(0)
	v_mfma_f32_16x16x32_bf16 v[140:143], v[122:125], v[196:199], v[140:143]
	v_mfma_f32_16x16x32_bf16 v[136:139], v[168:171], v[196:199], v[136:139]
	v_mfma_f32_16x16x32_bf16 v[112:115], v[122:125], v[204:207], v[112:115]
	v_mfma_f32_16x16x32_bf16 v[104:107], v[168:171], v[204:207], v[104:107]
	v_mfma_f32_16x16x32_bf16 v[92:95], v[122:125], v[212:215], v[92:95]
	v_mfma_f32_16x16x32_bf16 v[88:91], v[168:171], v[212:215], v[88:91]
	v_mfma_f32_16x16x32_bf16 v[76:79], v[122:125], v[220:223], v[76:79]
	v_mfma_f32_16x16x32_bf16 v[72:75], v[168:171], v[220:223], v[72:75]
	v_mfma_f32_16x16x32_bf16 v[140:143], v[164:167], v[200:203], v[140:143]
	v_mfma_f32_16x16x32_bf16 v[136:139], v[172:175], v[200:203], v[136:139]
	v_mfma_f32_16x16x32_bf16 v[112:115], v[164:167], v[208:211], v[112:115]
	v_mfma_f32_16x16x32_bf16 v[104:107], v[172:175], v[208:211], v[104:107]
	v_mfma_f32_16x16x32_bf16 v[92:95], v[164:167], v[216:219], v[92:95]
	v_mfma_f32_16x16x32_bf16 v[88:91], v[172:175], v[216:219], v[88:91]
	v_mfma_f32_16x16x32_bf16 v[76:79], v[164:167], v[224:227], v[76:79]
	v_mfma_f32_16x16x32_bf16 v[72:75], v[172:175], v[224:227], v[72:75]
	s_setprio 0
	s_setprio 1
	v_mfma_f32_16x16x32_bf16 v[130:133], v[176:179], v[196:199], v[132:135]
	v_mfma_f32_16x16x32_bf16 v[126:129], v[184:187], v[196:199], v[126:129]
	v_mfma_f32_16x16x32_bf16 v[100:103], v[176:179], v[204:207], v[100:103]
	v_mfma_f32_16x16x32_bf16 v[96:99], v[184:187], v[204:207], v[96:99]
	v_mfma_f32_16x16x32_bf16 v[84:87], v[176:179], v[212:215], v[84:87]
	v_mfma_f32_16x16x32_bf16 v[80:83], v[184:187], v[212:215], v[80:83]
	v_mfma_f32_16x16x32_bf16 v[68:71], v[176:179], v[220:223], v[68:71]
	v_mfma_f32_16x16x32_bf16 v[64:67], v[184:187], v[220:223], v[64:67]
	v_mfma_f32_16x16x32_bf16 v[132:135], v[180:183], v[200:203], v[130:133]
	v_mfma_f32_16x16x32_bf16 v[128:131], v[188:191], v[200:203], v[126:129]
	v_mfma_f32_16x16x32_bf16 v[100:103], v[180:183], v[208:211], v[100:103]
	v_mfma_f32_16x16x32_bf16 v[96:99], v[188:191], v[208:211], v[96:99]
	v_mfma_f32_16x16x32_bf16 v[84:87], v[180:183], v[216:219], v[84:87]
	v_mfma_f32_16x16x32_bf16 v[80:83], v[188:191], v[216:219], v[80:83]
	v_mfma_f32_16x16x32_bf16 v[68:71], v[180:183], v[224:227], v[68:71]
	v_mfma_f32_16x16x32_bf16 v[64:67], v[188:191], v[224:227], v[64:67]
	s_setprio 0
	s_barrier
	s_mov_b32 m0, s50
	v_lshl_add_u64 v[126:127], v[154:155], 0, s[14:15]
	s_add_u32 s20, s20, 0xb0080
	ds_read_b128 v[196:199], v118 offset:49152
	ds_read_b128 v[200:203], v118 offset:50176
	ds_read_b128 v[204:207], v118 offset:51200
	ds_read_b128 v[208:211], v118 offset:52224
	ds_read_b128 v[212:215], v118 offset:53248
	ds_read_b128 v[216:219], v118 offset:54272
	ds_read_b128 v[220:223], v118 offset:55296
	ds_read_b128 v[224:227], v118 offset:56320
	global_load_lds_dwordx4 v[126:127], off
	v_lshl_add_u64 v[126:127], v[228:229], 0, s[14:15]
	s_mov_b32 m0, s51
	s_addc_u32 s21, s21, 0
	global_load_lds_dwordx4 v[126:127], off
	v_lshl_add_u64 v[126:127], s[20:21], 0, v[146:147]
	s_mov_b32 m0, s52
	s_nop 0
	global_load_lds_dwordx4 v[126:127], off
	v_lshl_add_u64 v[126:127], s[20:21], 0, v[150:151]
	s_mov_b32 m0, s53
	s_nop 0
	global_load_lds_dwordx4 v[126:127], off
	v_lshl_add_u64 v[126:127], v[230:231], 0, s[14:15]
	s_mov_b32 m0, s39
	s_nop 0
	global_load_lds_dwordx4 v[126:127], off
	v_lshl_add_u64 v[126:127], v[232:233], 0, s[14:15]
	s_mov_b32 m0, s40
	s_nop 0
	global_load_lds_dwordx4 v[126:127], off
	s_waitcnt vmcnt(8)
	s_waitcnt lgkmcnt(0)
	s_barrier
	s_setprio 1
	s_waitcnt lgkmcnt(0)
	v_mfma_f32_16x16x32_bf16 v[60:63], v[122:125], v[196:199], v[60:63]
	v_mfma_f32_16x16x32_bf16 v[56:59], v[168:171], v[196:199], v[56:59]
	v_mfma_f32_16x16x32_bf16 v[44:47], v[122:125], v[204:207], v[44:47]
	v_mfma_f32_16x16x32_bf16 v[40:43], v[168:171], v[204:207], v[40:43]
	v_mfma_f32_16x16x32_bf16 v[28:31], v[122:125], v[212:215], v[28:31]
	v_mfma_f32_16x16x32_bf16 v[24:27], v[168:171], v[212:215], v[24:27]
	v_mfma_f32_16x16x32_bf16 v[12:15], v[122:125], v[220:223], v[12:15]
	v_mfma_f32_16x16x32_bf16 v[8:11], v[168:171], v[220:223], v[8:11]
	v_mfma_f32_16x16x32_bf16 v[60:63], v[164:167], v[200:203], v[60:63]
	v_mfma_f32_16x16x32_bf16 v[56:59], v[172:175], v[200:203], v[56:59]
	v_mfma_f32_16x16x32_bf16 v[44:47], v[164:167], v[208:211], v[44:47]
	v_mfma_f32_16x16x32_bf16 v[40:43], v[172:175], v[208:211], v[40:43]
	v_mfma_f32_16x16x32_bf16 v[28:31], v[164:167], v[216:219], v[28:31]
	v_mfma_f32_16x16x32_bf16 v[24:27], v[172:175], v[216:219], v[24:27]
	v_mfma_f32_16x16x32_bf16 v[12:15], v[164:167], v[224:227], v[12:15]
	v_mfma_f32_16x16x32_bf16 v[8:11], v[172:175], v[224:227], v[8:11]
	s_setprio 0
	s_setprio 1
	v_mfma_f32_16x16x32_bf16 v[52:55], v[176:179], v[196:199], v[52:55]
	v_mfma_f32_16x16x32_bf16 v[48:51], v[184:187], v[196:199], v[48:51]
	v_mfma_f32_16x16x32_bf16 v[36:39], v[176:179], v[204:207], v[36:39]
	v_mfma_f32_16x16x32_bf16 v[32:35], v[184:187], v[204:207], v[32:35]
	v_mfma_f32_16x16x32_bf16 v[20:23], v[176:179], v[212:215], v[20:23]
	v_mfma_f32_16x16x32_bf16 v[16:19], v[184:187], v[212:215], v[16:19]
	v_mfma_f32_16x16x32_bf16 v[4:7], v[176:179], v[220:223], v[4:7]
	v_mfma_f32_16x16x32_bf16 v[0:3], v[184:187], v[220:223], v[0:3]
	v_mfma_f32_16x16x32_bf16 v[52:55], v[180:183], v[200:203], v[52:55]
	v_mfma_f32_16x16x32_bf16 v[48:51], v[188:191], v[200:203], v[48:51]
	v_mfma_f32_16x16x32_bf16 v[36:39], v[180:183], v[208:211], v[36:39]
	v_mfma_f32_16x16x32_bf16 v[32:35], v[188:191], v[208:211], v[32:35]
	v_mfma_f32_16x16x32_bf16 v[20:23], v[180:183], v[216:219], v[20:23]
	v_mfma_f32_16x16x32_bf16 v[16:19], v[188:191], v[216:219], v[16:19]
	v_mfma_f32_16x16x32_bf16 v[4:7], v[180:183], v[224:227], v[4:7]
	v_mfma_f32_16x16x32_bf16 v[0:3], v[188:191], v[224:227], v[0:3]
	s_setprio 0
	s_barrier
	s_add_i32 s43, s43, 2
	s_add_u32 s18, s18, 0x100
	s_addc_u32 s19, s19, 0

; #define PG8_STAGE(bufoff, gbase, voff) do { _Pragma("unroll") for (int _i = 0; _i < 2; ++_i) \
;         __builtin_amdgcn_global_load_lds((const unsigned*)((const char*)(gbase) + (voff)[_i]), (PG8_LAS unsigned*)(lds + (bufoff) + ldsw + _i * 8192), 16, 0, 0); } while (0)
; #define PG8_LDA(dst, b, h) do { _Pragma("unroll") for (int m = 0; m < 4; ++m) _Pragma("unroll") for (int k = 0; k < 2; ++k) dst[m][k] = *(const PG8_LAS bf16x8*)(lds + PG8_SA(b, h) + aoff + m * 2048 + k * 1024); } while (0)
; #define PG8_WAIT_V(n) asm volatile("s_waitcnt vmcnt(" #n ")" ::: "memory")
; #define PG8_WAIT_L(n) asm volatile("s_waitcnt lgkmcnt(" #n ")" ::: "memory")
; template <class Epi, class Sched, bool ALIGN_EPI = false, bool SP2 = false>
; __device__ __forceinline__ void gemm_phase(PG8_LAS unsigned char* lds, const Gemm g, const Sched& S, const Epi& E) {
;     ...
;         PG8_WAIT_V(2); PG8_BAR;
;         PG8_STAGE(PG8_SB(1, 0), cB + kstep, voffB); PG8_STAGE(PG8_SA(1, 0), cA + kstep, voffA); PG8_STAGE(PG8_SB(1, 1), cB + hstepB + kstep, voffB);
;         PG8_WAIT_V(6); PG8_BAR;
;     } else {
;         PG8_STAGE(PG8_SB(0, 0), cB, voffB); PG8_STAGE(PG8_SA(0, 0), cA, voffA); PG8_STAGE(PG8_SB(0, 1), cB + hstepB, voffB); PG8_STAGE(PG8_SA(0, 1), cA + hstepA, voffA);
;         if (wr == 1) PG8_BAR;
;         PG8_WAIT_V(4); PG8_BAR;
;         PG8_STAGE(PG8_SB(1, 0), cB + kstep, voffB); PG8_STAGE(PG8_SA(1, 0), cA + kstep, voffA); PG8_STAGE(PG8_SB(1, 1), cB + hstepB + kstep, voffB);
;         PG8_WAIT_V(6); PG8_BAR;
;     }
;     for (;;) {
;         const bool has_next = S.next(ui + 1, nxt);
;         const char* nA = has_next ? PG8_UA(nxt) : cA; const char* nB = has_next ? PG8_UB(nxt) : cB;
;         for (int t = 0; t < nt; t += 2) {
;             const bool last = (t == nt - 2);
;             const char* a1 = cA + (size_t)(t + 1) * kstep;
;             const char* a2 = last ? nA : cA + (size_t)(t + 2) * kstep; const char* b2 = last ? nB : cB + (size_t)(t + 2) * kstep;
;             const char* a3 = a2 + kstep; const char* b3 = b2 + kstep;
;             if (last && has_next) S.a_ready(nxt);
;             if constexpr (SP2) {
;             PG8_LDB(B0, 0, 0); PG8_LDB(B1, 0, 1); PG8_SCHED; PG8_LDA(At, 0, 0); PG8_STAGE(PG8_SA(1, 1), a1 + hstepA, voffA);
;             PG8_WAIT_V(8); PG8_WAIT_L(0); PG8_BAR; PG8_MMA(0, 0, At, B0); PG8_MMA(0, 1, At, B1); PG8_BAR; PG8_SCHED;
.LBB0_1639:
	v_lshlrev_b32_e32 v9, 2, v157
	s_and_b32 s26, s12, 3
	v_lshl_or_b32 v8, v157, 6, v162
	s_lshl_b32 s12, s30, 13
	v_and_b32_e32 v9, 32, v9
	v_bitop3_b32 v8, v8, s12, v9 bitop3:0xde
	s_mov_b64 s[12:13], 0x80
	s_add_i32 m0, s28, 0x18000
	v_lshl_add_u64 v[6:7], v[6:7], 0, s[12:13]
	s_waitcnt vmcnt(2)
	s_barrier
	global_load_lds_dwordx4 v[6:7], off
	v_lshl_add_u64 v[4:5], v[4:5], 0, s[12:13]
	s_add_i32 m0, s28, 0x1a000
	s_add_i32 s33, s28, 0x8000
	s_add_i32 s36, s28, 0xa000
	global_load_lds_dwordx4 v[4:5], off
	v_lshl_add_u64 v[2:3], v[2:3], 0, s[12:13]
	s_mov_b32 m0, s33
	s_add_u32 s20, s0, 0xb0080
	global_load_lds_dwordx4 v[2:3], off
	v_lshl_add_u64 v[0:1], v[0:1], 0, s[12:13]
	s_mov_b32 m0, s36
	s_addc_u32 s21, s1, 0
	global_load_lds_dwordx4 v[0:1], off
	s_add_i32 m0, s28, 0x1c000
	v_lshl_add_u64 v[0:1], s[20:21], 0, v[146:147]
	global_load_lds_dwordx4 v[0:1], off
	v_lshl_add_u64 v[0:1], s[20:21], 0, v[150:151]
	s_add_i32 m0, s28, 0x1e000
	s_add_u32 s14, s34, s14
	global_load_lds_dwordx4 v[0:1], off
	s_addc_u32 s15, s35, s15
	v_add_u16_e32 v0, v158, v159
	v_lshrrev_b16_e32 v2, 1, v0
	s_add_u32 s17, s34, s17
	v_add_lshl_u32 v0, v160, v2, 1
	v_mov_b32_e32 v1, v147
	s_addc_u32 s16, s35, s16
	v_lshl_add_u64 v[0:1], s[14:15], 0, v[0:1]
	s_mov_b64 s[20:21], 0x78b4080
	s_add_u32 s34, s17, 0x2a00100
	v_lshl_or_b32 v9, s26, 12, v163
	s_waitcnt vmcnt(6)
	v_lshl_add_u64 v[112:113], v[0:1], 0, s[20:21]
	v_add_lshl_u32 v0, v161, v2, 1
	v_mov_b32_e32 v1, v147
	s_addc_u32 s35, s16, 0
	s_add_i32 s40, 0, 0x10000
	s_add_i32 s42, 0, 0x14000
	s_add_i32 s44, 0, 0x18000
	s_add_i32 s46, 0, 0x1c000
	v_lshl_add_u64 v[0:1], s[14:15], 0, v[0:1]
	v_add_u32_e32 v116, s40, v9
	v_add_u32_e32 v117, s42, v9
	s_add_i32 s40, s40, s18
	s_add_i32 s42, s42, s18
	v_add_u32_e32 v119, s44, v9
	v_add_u32_e32 v120, s46, v9
	s_add_i32 s44, s44, s18
	s_add_i32 s46, s46, s18
	v_lshl_or_b32 v152, s30, 6, v157
	v_lshl_add_u64 v[114:115], v[0:1], 0, s[20:21]
	s_mov_b32 s37, -2
	s_mov_b64 s[16:17], 0
	v_add_u32_e32 v118, 0, v8
	s_add_i32 s38, s28, 0xc000
	s_add_i32 s39, s28, 0xe000
	s_add_i32 s41, s40, 0x2000
	s_add_i32 s43, s42, 0x2000
	s_add_i32 s45, s44, 0x2000
	s_add_i32 s47, s46, 0x2000
	s_barrier
	ds_read_b128 v[122:125], v116
	ds_read_b128 v[158:161], v116 offset:1024
	ds_read_b128 v[162:165], v116 offset:2048
	ds_read_b128 v[166:169], v116 offset:3072
	ds_read_b128 v[170:173], v117
	ds_read_b128 v[174:177], v117 offset:1024
	ds_read_b128 v[178:181], v117 offset:2048
	ds_read_b128 v[182:185], v117 offset:3072
	s_add_u32 s18, s14, s16
	s_addc_u32 s19, s15, s17
	s_add_u32 s18, s18, 0x7800100
	s_addc_u32 s19, s19, 0
	s_add_u32 s48, s34, s16
	s_addc_u32 s49, s35, s17
	s_cmpk_eq_i32 s16, 0x1500
	s_cselect_b32 s21, s11, s19
	s_cselect_b32 s20, s10, s18
	s_cselect_b32 s19, s1, s49
	s_cselect_b32 s18, s0, s48
	s_mov_b32 m0, s38
	v_lshl_add_u64 v[126:127], v[112:113], 0, s[16:17]
	ds_read_b128 v[186:189], v118
	ds_read_b128 v[194:197], v118 offset:1024
	ds_read_b128 v[198:201], v118 offset:2048
	ds_read_b128 v[202:205], v118 offset:3072
	ds_read_b128 v[206:209], v118 offset:4096
	ds_read_b128 v[210:213], v118 offset:5120
	ds_read_b128 v[214:217], v118 offset:6144
	ds_read_b128 v[218:221], v118 offset:7168
	global_load_lds_dwordx4 v[126:127], off
	v_lshl_add_u64 v[126:127], v[114:115], 0, s[16:17]
	s_mov_b32 m0, s39
	s_nop 0
	global_load_lds_dwordx4 v[126:127], off
	s_waitcnt vmcnt(8)
	s_waitcnt lgkmcnt(0)
	s_barrier
	s_setprio 1
	s_waitcnt lgkmcnt(0)
	v_mfma_f32_16x16x32_bf16 v[140:143], v[122:125], v[186:189], 0
	v_mfma_f32_16x16x32_bf16 v[136:139], v[162:165], v[186:189], 0
	v_mfma_f32_16x16x32_bf16 v[108:111], v[122:125], v[198:201], 0
	v_mfma_f32_16x16x32_bf16 v[104:107], v[162:165], v[198:201], 0
	v_mfma_f32_16x16x32_bf16 v[92:95], v[122:125], v[206:209], 0
	v_mfma_f32_16x16x32_bf16 v[88:91], v[162:165], v[206:209], 0
	v_mfma_f32_16x16x32_bf16 v[76:79], v[122:125], v[214:217], 0
	v_mfma_f32_16x16x32_bf16 v[72:75], v[162:165], v[214:217], 0
	v_mfma_f32_16x16x32_bf16 v[140:143], v[158:161], v[194:197], v[140:143]
	v_mfma_f32_16x16x32_bf16 v[136:139], v[166:169], v[194:197], v[136:139]
	v_mfma_f32_16x16x32_bf16 v[108:111], v[158:161], v[202:205], v[108:111]
	v_mfma_f32_16x16x32_bf16 v[104:107], v[166:169], v[202:205], v[104:107]
	v_mfma_f32_16x16x32_bf16 v[92:95], v[158:161], v[210:213], v[92:95]
	v_mfma_f32_16x16x32_bf16 v[88:91], v[166:169], v[210:213], v[88:91]
	v_mfma_f32_16x16x32_bf16 v[76:79], v[158:161], v[218:221], v[76:79]
	v_mfma_f32_16x16x32_bf16 v[72:75], v[166:169], v[218:221], v[72:75]
	s_setprio 0
	s_setprio 1
	v_mfma_f32_16x16x32_bf16 v[132:135], v[170:173], v[186:189], 0
	v_mfma_f32_16x16x32_bf16 v[126:129], v[178:181], v[186:189], 0
	v_mfma_f32_16x16x32_bf16 v[100:103], v[170:173], v[198:201], 0
	v_mfma_f32_16x16x32_bf16 v[96:99], v[178:181], v[198:201], 0
	v_mfma_f32_16x16x32_bf16 v[84:87], v[170:173], v[206:209], 0
	v_mfma_f32_16x16x32_bf16 v[80:83], v[178:181], v[206:209], 0
	v_mfma_f32_16x16x32_bf16 v[68:71], v[170:173], v[214:217], 0
	v_mfma_f32_16x16x32_bf16 v[64:67], v[178:181], v[214:217], 0
	v_mfma_f32_16x16x32_bf16 v[132:135], v[174:177], v[194:197], v[132:135]
	v_mfma_f32_16x16x32_bf16 v[126:129], v[182:185], v[194:197], v[126:129]
	v_mfma_f32_16x16x32_bf16 v[100:103], v[174:177], v[202:205], v[100:103]
	v_mfma_f32_16x16x32_bf16 v[96:99], v[182:185], v[202:205], v[96:99]
	v_mfma_f32_16x16x32_bf16 v[84:87], v[174:177], v[210:213], v[84:87]
	v_mfma_f32_16x16x32_bf16 v[80:83], v[182:185], v[210:213], v[80:83]
	v_mfma_f32_16x16x32_bf16 v[68:71], v[174:177], v[218:221], v[68:71]
	v_mfma_f32_16x16x32_bf16 v[64:67], v[182:185], v[218:221], v[64:67]
	s_setprio 0
	s_barrier
; #define PG8_STAGE(bufoff, gbase, voff) do { _Pragma("unroll") for (int _i = 0; _i < 2; ++_i) \
;         __builtin_amdgcn_global_load_lds((const unsigned*)((const char*)(gbase) + (voff)[_i]), (PG8_LAS unsigned*)(lds + (bufoff) + ldsw + _i * 8192), 16, 0, 0); } while (0)
; #define PG8_LDA(dst, b, h) do { _Pragma("unroll") for (int m = 0; m < 4; ++m) _Pragma("unroll") for (int k = 0; k < 2; ++k) dst[m][k] = *(const PG8_LAS bf16x8*)(lds + PG8_SA(b, h) + aoff + m * 2048 + k * 1024); } while (0)
; #define PG8_LDB(dst, b, h) do { _Pragma("unroll") for (int n = 0; n < 2; ++n) _Pragma("unroll") for (int k = 0; k < 2; ++k) dst[n][k] = *(const PG8_LAS bf16x8*)(lds + PG8_SB(b, h) + boff + n * 2048 + k * 1024); } while (0)
; #define PG8_MMA(ai, bj, At, Bt) do { __builtin_amdgcn_s_setprio(1); _Pragma("unroll") for (int m = 0; m < 4; ++m) _Pragma("unroll") for (int n = 0; n < 2; ++n) _Pragma("unroll") for (int k = 0; k < 2; ++k) \
;         acc[ai][bj][m][n] = __builtin_amdgcn_mfma_f32_16x16x32_bf16(Bt[n][k], At[m][k], acc[ai][bj][m][n], 0, 0, 0); __builtin_amdgcn_s_setprio(0); } while (0)
; #define PG8_WAIT_V(n) asm volatile("s_waitcnt vmcnt(" #n ")" ::: "memory")
; #define PG8_WAIT_L(n) asm volatile("s_waitcnt lgkmcnt(" #n ")" ::: "memory")
; #define PG8_BAR __builtin_amdgcn_s_barrier()
; #define PG8_SCHED __builtin_amdgcn_sched_barrier(0)
; template <class Epi, class Sched, bool ALIGN_EPI = false, bool SP2 = false>
; __device__ __forceinline__ void gemm_phase(PG8_LAS unsigned char* lds, const Gemm g, const Sched& S, const Epi& E) {
;     ...
;             PG8_LDA(At, 0, 1); PG8_STAGE(PG8_SB(0, 0), b2, voffB); PG8_STAGE(PG8_SB(0, 1), b2 + hstepB, voffB); PG8_STAGE(PG8_SA(0, 0), a2, voffA);
;             PG8_WAIT_V(8); PG8_WAIT_L(0); PG8_BAR; PG8_MMA(1, 0, At, B0); PG8_MMA(1, 1, At, B1); PG8_BAR; PG8_SCHED;
;             PG8_LDB(B0, 1, 0); PG8_LDB(B1, 1, 1); PG8_SCHED; PG8_LDA(At, 1, 0); PG8_STAGE(PG8_SA(0, 1), a2 + hstepA, voffA);
;             PG8_WAIT_V(8); PG8_WAIT_L(0); PG8_BAR; PG8_MMA(0, 0, At, B0); PG8_MMA(0, 1, At, B1); PG8_BAR; PG8_SCHED;
	s_mov_b32 m0, s40
	v_lshl_add_u64 v[154:155], s[18:19], 0, v[146:147]
	s_add_u32 s48, s18, 0xb0000
	ds_read_b128 v[186:189], v118 offset:16384
	ds_read_b128 v[194:197], v118 offset:17408
	ds_read_b128 v[198:201], v118 offset:18432
	ds_read_b128 v[202:205], v118 offset:19456
	ds_read_b128 v[206:209], v118 offset:20480
	ds_read_b128 v[210:213], v118 offset:21504
	ds_read_b128 v[214:217], v118 offset:22528
	ds_read_b128 v[218:221], v118 offset:23552
	global_load_lds_dwordx4 v[154:155], off
	v_lshl_add_u64 v[190:191], s[18:19], 0, v[150:151]
	s_mov_b32 m0, s41
	s_addc_u32 s49, s19, 0
	global_load_lds_dwordx4 v[190:191], off
	v_lshl_add_u64 v[130:131], s[48:49], 0, v[146:147]
	s_mov_b32 m0, s42
	v_lshl_add_u64 v[222:223], s[20:21], 0, v[144:145]
	global_load_lds_dwordx4 v[130:131], off
	v_lshl_add_u64 v[130:131], s[48:49], 0, v[150:151]
	s_mov_b32 m0, s43
	v_lshl_add_u64 v[224:225], s[20:21], 0, v[148:149]
	global_load_lds_dwordx4 v[130:131], off
	s_mov_b32 m0, s28
	s_nop 0
	global_load_lds_dwordx4 v[222:223], off
	s_mov_b32 m0, s27
	s_nop 0
	global_load_lds_dwordx4 v[224:225], off
	s_waitcnt vmcnt(8)
	s_waitcnt lgkmcnt(0)
	s_barrier
	s_setprio 1
	s_waitcnt lgkmcnt(0)
	v_mfma_f32_16x16x32_bf16 v[60:63], v[122:125], v[186:189], 0
	v_mfma_f32_16x16x32_bf16 v[56:59], v[162:165], v[186:189], 0
	v_mfma_f32_16x16x32_bf16 v[44:47], v[122:125], v[198:201], 0
	v_mfma_f32_16x16x32_bf16 v[40:43], v[162:165], v[198:201], 0
	v_mfma_f32_16x16x32_bf16 v[28:31], v[122:125], v[206:209], 0
	v_mfma_f32_16x16x32_bf16 v[24:27], v[162:165], v[206:209], 0
	v_mfma_f32_16x16x32_bf16 v[12:15], v[122:125], v[214:217], 0
	v_mfma_f32_16x16x32_bf16 v[8:11], v[162:165], v[214:217], 0
	v_mfma_f32_16x16x32_bf16 v[60:63], v[158:161], v[194:197], v[60:63]
	v_mfma_f32_16x16x32_bf16 v[56:59], v[166:169], v[194:197], v[56:59]
	v_mfma_f32_16x16x32_bf16 v[44:47], v[158:161], v[202:205], v[44:47]
	v_mfma_f32_16x16x32_bf16 v[40:43], v[166:169], v[202:205], v[40:43]
	v_mfma_f32_16x16x32_bf16 v[28:31], v[158:161], v[210:213], v[28:31]
	v_mfma_f32_16x16x32_bf16 v[24:27], v[166:169], v[210:213], v[24:27]
	v_mfma_f32_16x16x32_bf16 v[12:15], v[158:161], v[218:221], v[12:15]
	v_mfma_f32_16x16x32_bf16 v[8:11], v[166:169], v[218:221], v[8:11]
	s_setprio 0
	s_setprio 1
	v_mfma_f32_16x16x32_bf16 v[52:55], v[170:173], v[186:189], 0
	v_mfma_f32_16x16x32_bf16 v[48:51], v[178:181], v[186:189], 0
	v_mfma_f32_16x16x32_bf16 v[36:39], v[170:173], v[198:201], 0
	v_mfma_f32_16x16x32_bf16 v[32:35], v[178:181], v[198:201], 0
	v_mfma_f32_16x16x32_bf16 v[20:23], v[170:173], v[206:209], 0
	v_mfma_f32_16x16x32_bf16 v[16:19], v[178:181], v[206:209], 0
	v_mfma_f32_16x16x32_bf16 v[4:7], v[170:173], v[214:217], 0
	v_mfma_f32_16x16x32_bf16 v[0:3], v[178:181], v[214:217], 0
	v_mfma_f32_16x16x32_bf16 v[52:55], v[174:177], v[194:197], v[52:55]
	v_mfma_f32_16x16x32_bf16 v[48:51], v[182:185], v[194:197], v[48:51]
	v_mfma_f32_16x16x32_bf16 v[36:39], v[174:177], v[202:205], v[36:39]
	v_mfma_f32_16x16x32_bf16 v[32:35], v[182:185], v[202:205], v[32:35]
	v_mfma_f32_16x16x32_bf16 v[20:23], v[174:177], v[210:213], v[20:23]
	v_mfma_f32_16x16x32_bf16 v[16:19], v[182:185], v[210:213], v[16:19]
	v_mfma_f32_16x16x32_bf16 v[4:7], v[174:177], v[218:221], v[4:7]
	v_mfma_f32_16x16x32_bf16 v[0:3], v[182:185], v[218:221], v[0:3]
	s_setprio 0
	s_barrier
	ds_read_b128 v[122:125], v119
	ds_read_b128 v[158:161], v119 offset:1024
	ds_read_b128 v[162:165], v119 offset:2048
	ds_read_b128 v[166:169], v119 offset:3072
	ds_read_b128 v[170:173], v120
	ds_read_b128 v[174:177], v120 offset:1024
	ds_read_b128 v[178:181], v120 offset:2048
	ds_read_b128 v[182:185], v120 offset:3072
	s_add_u32 s20, s20, 0xb4000
	s_addc_u32 s21, s21, 0
	s_mov_b32 m0, s29
	v_lshl_add_u64 v[130:131], s[20:21], 0, v[144:145]
	ds_read_b128 v[186:189], v118 offset:32768
	ds_read_b128 v[194:197], v118 offset:33792
	ds_read_b128 v[198:201], v118 offset:34816
	ds_read_b128 v[202:205], v118 offset:35840
	ds_read_b128 v[206:209], v118 offset:36864
	ds_read_b128 v[210:213], v118 offset:37888
	ds_read_b128 v[214:217], v118 offset:38912
	ds_read_b128 v[218:221], v118 offset:39936
	global_load_lds_dwordx4 v[130:131], off
	v_lshl_add_u64 v[130:131], s[20:21], 0, v[148:149]
	s_mov_b32 m0, s31
	s_nop 0
	global_load_lds_dwordx4 v[130:131], off
	s_waitcnt vmcnt(8)
	s_waitcnt lgkmcnt(0)
	s_barrier
; #define PG8_STAGE(bufoff, gbase, voff) do { _Pragma("unroll") for (int _i = 0; _i < 2; ++_i) \
;         __builtin_amdgcn_global_load_lds((const unsigned*)((const char*)(gbase) + (voff)[_i]), (PG8_LAS unsigned*)(lds + (bufoff) + ldsw + _i * 8192), 16, 0, 0); } while (0)
; #define PG8_LDA(dst, b, h) do { _Pragma("unroll") for (int m = 0; m < 4; ++m) _Pragma("unroll") for (int k = 0; k < 2; ++k) dst[m][k] = *(const PG8_LAS bf16x8*)(lds + PG8_SA(b, h) + aoff + m * 2048 + k * 1024); } while (0)
; #define PG8_MMA(ai, bj, At, Bt) do { __builtin_amdgcn_s_setprio(1); _Pragma("unroll") for (int m = 0; m < 4; ++m) _Pragma("unroll") for (int n = 0; n < 2; ++n) _Pragma("unroll") for (int k = 0; k < 2; ++k) \
;         acc[ai][bj][m][n] = __builtin_amdgcn_mfma_f32_16x16x32_bf16(Bt[n][k], At[m][k], acc[ai][bj][m][n], 0, 0, 0); __builtin_amdgcn_s_setprio(0); } while (0)
; #define PG8_WAIT_V(n) asm volatile("s_waitcnt vmcnt(" #n ")" ::: "memory")
; #define PG8_WAIT_L(n) asm volatile("s_waitcnt lgkmcnt(" #n ")" ::: "memory")
; #define PG8_BAR __builtin_amdgcn_s_barrier()
; #define PG8_SCHED __builtin_amdgcn_sched_barrier(0)
; template <class Epi, class Sched, bool ALIGN_EPI = false, bool SP2 = false>
; __device__ __forceinline__ void gemm_phase(PG8_LAS unsigned char* lds, const Gemm g, const Sched& S, const Epi& E) {
;     ...
;         for (int t = 0; t < nt; t += 2) {
;     ...
;             PG8_WAIT_V(8); PG8_WAIT_L(0); PG8_BAR; PG8_MMA(0, 0, At, B0); PG8_MMA(0, 1, At, B1); PG8_BAR; PG8_SCHED;
;             PG8_LDA(At, 1, 1); PG8_STAGE(PG8_SB(1, 0), b3, voffB); PG8_STAGE(PG8_SB(1, 1), b3 + hstepB, voffB); PG8_STAGE(PG8_SA(1, 0), a3, voffA);
;             PG8_WAIT_V(8); PG8_WAIT_L(0); PG8_BAR; PG8_MMA(1, 0, At, B0); PG8_MMA(1, 1, At, B1); PG8_BAR; PG8_SCHED;
	s_setprio 1
	s_waitcnt lgkmcnt(0)
	v_mfma_f32_16x16x32_bf16 v[140:143], v[122:125], v[186:189], v[140:143]
	v_mfma_f32_16x16x32_bf16 v[136:139], v[162:165], v[186:189], v[136:139]
	v_mfma_f32_16x16x32_bf16 v[108:111], v[122:125], v[198:201], v[108:111]
	v_mfma_f32_16x16x32_bf16 v[104:107], v[162:165], v[198:201], v[104:107]
	v_mfma_f32_16x16x32_bf16 v[92:95], v[122:125], v[206:209], v[92:95]
	v_mfma_f32_16x16x32_bf16 v[88:91], v[162:165], v[206:209], v[88:91]
	v_mfma_f32_16x16x32_bf16 v[76:79], v[122:125], v[214:217], v[76:79]
	v_mfma_f32_16x16x32_bf16 v[72:75], v[162:165], v[214:217], v[72:75]
	v_mfma_f32_16x16x32_bf16 v[140:143], v[158:161], v[194:197], v[140:143]
	v_mfma_f32_16x16x32_bf16 v[136:139], v[166:169], v[194:197], v[136:139]
	v_mfma_f32_16x16x32_bf16 v[108:111], v[158:161], v[202:205], v[108:111]
	v_mfma_f32_16x16x32_bf16 v[104:107], v[166:169], v[202:205], v[104:107]
	v_mfma_f32_16x16x32_bf16 v[92:95], v[158:161], v[210:213], v[92:95]
	v_mfma_f32_16x16x32_bf16 v[88:91], v[166:169], v[210:213], v[88:91]
	v_mfma_f32_16x16x32_bf16 v[76:79], v[158:161], v[218:221], v[76:79]
	v_mfma_f32_16x16x32_bf16 v[72:75], v[166:169], v[218:221], v[72:75]
	s_setprio 0
	s_setprio 1
	v_mfma_f32_16x16x32_bf16 v[130:133], v[170:173], v[186:189], v[132:135]
	v_mfma_f32_16x16x32_bf16 v[126:129], v[178:181], v[186:189], v[126:129]
	v_mfma_f32_16x16x32_bf16 v[100:103], v[170:173], v[198:201], v[100:103]
	v_mfma_f32_16x16x32_bf16 v[96:99], v[178:181], v[198:201], v[96:99]
	v_mfma_f32_16x16x32_bf16 v[84:87], v[170:173], v[206:209], v[84:87]
	v_mfma_f32_16x16x32_bf16 v[80:83], v[178:181], v[206:209], v[80:83]
	v_mfma_f32_16x16x32_bf16 v[68:71], v[170:173], v[214:217], v[68:71]
	v_mfma_f32_16x16x32_bf16 v[64:67], v[178:181], v[214:217], v[64:67]
	v_mfma_f32_16x16x32_bf16 v[132:135], v[174:177], v[194:197], v[130:133]
	v_mfma_f32_16x16x32_bf16 v[128:131], v[182:185], v[194:197], v[126:129]
	v_mfma_f32_16x16x32_bf16 v[100:103], v[174:177], v[202:205], v[100:103]
	v_mfma_f32_16x16x32_bf16 v[96:99], v[182:185], v[202:205], v[96:99]
	v_mfma_f32_16x16x32_bf16 v[84:87], v[174:177], v[210:213], v[84:87]
	v_mfma_f32_16x16x32_bf16 v[80:83], v[182:185], v[210:213], v[80:83]
	v_mfma_f32_16x16x32_bf16 v[68:71], v[174:177], v[218:221], v[68:71]
	v_mfma_f32_16x16x32_bf16 v[64:67], v[182:185], v[218:221], v[64:67]
	s_setprio 0
	s_barrier
	s_mov_b32 m0, s44
	v_lshl_add_u64 v[126:127], v[154:155], 0, s[12:13]
	s_add_u32 s18, s18, 0xb0080
	ds_read_b128 v[186:189], v118 offset:49152
	ds_read_b128 v[194:197], v118 offset:50176
	ds_read_b128 v[198:201], v118 offset:51200
	ds_read_b128 v[202:205], v118 offset:52224
	ds_read_b128 v[206:209], v118 offset:53248
	ds_read_b128 v[210:213], v118 offset:54272
	ds_read_b128 v[214:217], v118 offset:55296
	ds_read_b128 v[218:221], v118 offset:56320
	global_load_lds_dwordx4 v[126:127], off
	v_lshl_add_u64 v[126:127], v[190:191], 0, s[12:13]
	s_mov_b32 m0, s45
	s_addc_u32 s19, s19, 0
	global_load_lds_dwordx4 v[126:127], off
	v_lshl_add_u64 v[126:127], s[18:19], 0, v[146:147]
	s_mov_b32 m0, s46
	s_nop 0
	global_load_lds_dwordx4 v[126:127], off
	v_lshl_add_u64 v[126:127], s[18:19], 0, v[150:151]
	s_mov_b32 m0, s47
	s_nop 0
	global_load_lds_dwordx4 v[126:127], off
	v_lshl_add_u64 v[126:127], v[222:223], 0, s[12:13]
	s_mov_b32 m0, s33
	s_nop 0
	global_load_lds_dwordx4 v[126:127], off
	v_lshl_add_u64 v[126:127], v[224:225], 0, s[12:13]
	s_mov_b32 m0, s36
	s_nop 0
	global_load_lds_dwordx4 v[126:127], off
	s_waitcnt vmcnt(8)
	s_waitcnt lgkmcnt(0)
	s_barrier
	s_setprio 1
	s_waitcnt lgkmcnt(0)
	v_mfma_f32_16x16x32_bf16 v[60:63], v[122:125], v[186:189], v[60:63]
	v_mfma_f32_16x16x32_bf16 v[56:59], v[162:165], v[186:189], v[56:59]
	v_mfma_f32_16x16x32_bf16 v[44:47], v[122:125], v[198:201], v[44:47]
	v_mfma_f32_16x16x32_bf16 v[40:43], v[162:165], v[198:201], v[40:43]
	v_mfma_f32_16x16x32_bf16 v[28:31], v[122:125], v[206:209], v[28:31]
	v_mfma_f32_16x16x32_bf16 v[24:27], v[162:165], v[206:209], v[24:27]
	v_mfma_f32_16x16x32_bf16 v[12:15], v[122:125], v[214:217], v[12:15]
	v_mfma_f32_16x16x32_bf16 v[8:11], v[162:165], v[214:217], v[8:11]
	v_mfma_f32_16x16x32_bf16 v[60:63], v[158:161], v[194:197], v[60:63]
	v_mfma_f32_16x16x32_bf16 v[56:59], v[166:169], v[194:197], v[56:59]
	v_mfma_f32_16x16x32_bf16 v[44:47], v[158:161], v[202:205], v[44:47]
	v_mfma_f32_16x16x32_bf16 v[40:43], v[166:169], v[202:205], v[40:43]
	v_mfma_f32_16x16x32_bf16 v[28:31], v[158:161], v[210:213], v[28:31]
	v_mfma_f32_16x16x32_bf16 v[24:27], v[166:169], v[210:213], v[24:27]
	v_mfma_f32_16x16x32_bf16 v[12:15], v[158:161], v[218:221], v[12:15]
	v_mfma_f32_16x16x32_bf16 v[8:11], v[166:169], v[218:221], v[8:11]
	s_setprio 0
	s_setprio 1
	v_mfma_f32_16x16x32_bf16 v[52:55], v[170:173], v[186:189], v[52:55]
	v_mfma_f32_16x16x32_bf16 v[48:51], v[178:181], v[186:189], v[48:51]
	v_mfma_f32_16x16x32_bf16 v[36:39], v[170:173], v[198:201], v[36:39]
	v_mfma_f32_16x16x32_bf16 v[32:35], v[178:181], v[198:201], v[32:35]
	v_mfma_f32_16x16x32_bf16 v[20:23], v[170:173], v[206:209], v[20:23]
	v_mfma_f32_16x16x32_bf16 v[16:19], v[178:181], v[206:209], v[16:19]
	v_mfma_f32_16x16x32_bf16 v[4:7], v[170:173], v[214:217], v[4:7]
	v_mfma_f32_16x16x32_bf16 v[0:3], v[178:181], v[214:217], v[0:3]
	v_mfma_f32_16x16x32_bf16 v[52:55], v[174:177], v[194:197], v[52:55]
	v_mfma_f32_16x16x32_bf16 v[48:51], v[182:185], v[194:197], v[48:51]
	v_mfma_f32_16x16x32_bf16 v[36:39], v[174:177], v[202:205], v[36:39]
	v_mfma_f32_16x16x32_bf16 v[32:35], v[182:185], v[202:205], v[32:35]
	v_mfma_f32_16x16x32_bf16 v[20:23], v[174:177], v[210:213], v[20:23]
	v_mfma_f32_16x16x32_bf16 v[16:19], v[182:185], v[210:213], v[16:19]
	v_mfma_f32_16x16x32_bf16 v[4:7], v[174:177], v[218:221], v[4:7]
	v_mfma_f32_16x16x32_bf16 v[0:3], v[182:185], v[218:221], v[0:3]
	s_setprio 0
	s_barrier
	s_add_i32 s37, s37, 2
	s_add_u32 s16, s16, 0x100
	s_addc_u32 s17, s17, 0
